# GEMM k-loops: flat->global loads + counted vmcnt (2 k-steps in flight); own-block attention: combine loads hoisted above attention, one K/V LDS fill per query-block pair, balanced wave->tile map
# speedup vs baseline: 1.0239x; 1.0239x over previous
.LBB0_170:
	v_mov_b32_e32 v1, v196
	v_mov_b32_e32 v5, 0
	v_ashrrev_i32_e32 v6, 3, v1
	v_add_u32_e32 v2, s91, v6
	v_ashrrev_i32_e32 v3, 31, v2
	v_lshlrev_b32_e32 v1, 4, v1
	v_lshlrev_b64 v[2:3], 11, v[2:3]
	v_and_b32_e32 v4, 0x70, v1
	v_add_u32_e32 v1, s89, v6
	v_lshl_add_u64 v[2:3], s[68:69], 0, v[2:3]
	v_mad_i64_i32 v[6:7], s[4:5], v1, s70, 0
	v_lshl_add_u64 v[2:3], v[2:3], 0, v[4:5]
	v_lshl_add_u64 v[6:7], v[6:7], 1, s[72:73]
	s_mov_b32 s4, 0x10000
	v_lshl_add_u64 v[4:5], v[6:7], 0, v[4:5]
	v_add_co_u32_e32 v6, vcc, s4, v2
	s_ashr_i32 s71, s70, 31
	s_nop 0
	v_addc_co_u32_e32 v7, vcc, 0, v3, vcc
	s_mov_b32 s10, 0x20000
	s_lshl_b64 s[4:5], s[70:71], 6
	v_add_co_u32_e32 v10, vcc, s10, v2
	v_lshl_add_u64 v[8:9], v[4:5], 0, s[4:5]
	s_nop 0
	v_addc_co_u32_e32 v11, vcc, 0, v3, vcc
	v_lshl_add_u64 v[12:13], v[8:9], 0, s[4:5]
	v_add_co_u32_e32 v14, vcc, 0x30000, v2
	v_lshl_add_u64 v[16:17], v[12:13], 0, s[4:5]
	s_nop 0
	v_addc_co_u32_e32 v15, vcc, 0, v3, vcc
	global_load_dwordx4 v[64:67], v[2:3], off
	global_load_dwordx4 v[68:71], v[2:3], off offset:128
	global_load_dwordx4 v[76:79], v[4:5], off
	global_load_dwordx4 v[72:75], v[4:5], off offset:128
	global_load_dwordx4 v[96:99], v[6:7], off
	global_load_dwordx4 v[92:95], v[6:7], off offset:128
	global_load_dwordx4 v[88:91], v[8:9], off
	global_load_dwordx4 v[84:87], v[8:9], off offset:128
	global_load_dwordx4 v[112:115], v[10:11], off
	global_load_dwordx4 v[108:111], v[10:11], off offset:128
	global_load_dwordx4 v[104:107], v[12:13], off
	global_load_dwordx4 v[100:103], v[12:13], off offset:128
	global_load_dwordx4 v[128:131], v[14:15], off
	global_load_dwordx4 v[124:127], v[14:15], off offset:128
	global_load_dwordx4 v[120:123], v[16:17], off
	global_load_dwordx4 v[116:119], v[16:17], off offset:128

.LBB0_173:
	v_cvt_pk_bf16_f32 v48, v48, s0
	v_add_u32_e32 v81, v149, v151
	ds_write_b16 v81, v48
	v_cvt_pk_bf16_f32 v48, v49, s0
	ds_write_b16 v81, v48 offset:144
	v_cvt_pk_bf16_f32 v48, v50, s0
	ds_write_b16 v81, v48 offset:288
	v_cvt_pk_bf16_f32 v48, v51, s0
	v_add_u32_e32 v49, v149, v180
	ds_write_b16 v49, v48
	v_cvt_pk_bf16_f32 v48, v52, s0
	ds_write_b16 v81, v48 offset:1152
	v_cvt_pk_bf16_f32 v48, v53, s0
	ds_write_b16 v81, v48 offset:1296
	v_cvt_pk_bf16_f32 v48, v54, s0
	ds_write_b16 v81, v48 offset:1440
	v_cvt_pk_bf16_f32 v48, v55, s0
	v_add_u32_e32 v49, v149, v181
	ds_write_b16 v49, v48
	v_cvt_pk_bf16_f32 v48, v56, s0
	ds_write_b16 v81, v48 offset:2304
	v_cvt_pk_bf16_f32 v48, v57, s0
	ds_write_b16 v81, v48 offset:2448
	v_cvt_pk_bf16_f32 v48, v58, s0
	ds_write_b16 v81, v48 offset:2592
	v_cvt_pk_bf16_f32 v48, v59, s0
	v_add_u32_e32 v49, v149, v182
	ds_write_b16 v49, v48
	v_cvt_pk_bf16_f32 v48, v60, s0
	ds_write_b16 v81, v48 offset:3456
	v_cvt_pk_bf16_f32 v48, v61, s0
	ds_write_b16 v81, v48 offset:3600
	v_cvt_pk_bf16_f32 v48, v62, s0
	ds_write_b16 v81, v48 offset:3744
	v_cvt_pk_bf16_f32 v48, v63, s0
	v_add_u32_e32 v49, v149, v183
	ds_write_b16 v49, v48
	v_cvt_pk_bf16_f32 v32, v32, s0
	v_add_u32_e32 v48, v184, v151
	ds_write_b16 v48, v32
	v_cvt_pk_bf16_f32 v32, v33, s0
	ds_write_b16 v48, v32 offset:144
	v_cvt_pk_bf16_f32 v32, v34, s0
	ds_write_b16 v48, v32 offset:288
	v_cvt_pk_bf16_f32 v32, v35, s0
	v_add_u32_e32 v33, v184, v180
	ds_write_b16 v33, v32
	v_cvt_pk_bf16_f32 v32, v36, s0
	ds_write_b16 v48, v32 offset:1152
	v_cvt_pk_bf16_f32 v32, v37, s0
	ds_write_b16 v48, v32 offset:1296
	v_cvt_pk_bf16_f32 v32, v38, s0
	ds_write_b16 v48, v32 offset:1440
	v_cvt_pk_bf16_f32 v32, v39, s0
	v_add_u32_e32 v33, v184, v181
	ds_write_b16 v33, v32
	v_cvt_pk_bf16_f32 v32, v40, s0
	ds_write_b16 v48, v32 offset:2304
	v_cvt_pk_bf16_f32 v32, v41, s0
	ds_write_b16 v48, v32 offset:2448
	v_cvt_pk_bf16_f32 v32, v42, s0
	ds_write_b16 v48, v32 offset:2592
	v_cvt_pk_bf16_f32 v32, v43, s0
	v_add_u32_e32 v33, v184, v182
	ds_write_b16 v33, v32
	v_cvt_pk_bf16_f32 v32, v44, s0
	ds_write_b16 v48, v32 offset:3456
	v_cvt_pk_bf16_f32 v32, v45, s0
	ds_write_b16 v48, v32 offset:3600
	v_cvt_pk_bf16_f32 v32, v46, s0
	ds_write_b16 v48, v32 offset:3744
	v_cvt_pk_bf16_f32 v32, v47, s0
	v_add_u32_e32 v33, v184, v183
	v_cvt_pk_bf16_f32 v16, v16, s0
	ds_write_b16 v33, v32
	ds_write_b16 v81, v16 offset:4608
	v_cvt_pk_bf16_f32 v16, v17, s0
	ds_write_b16 v81, v16 offset:4752
	v_cvt_pk_bf16_f32 v16, v18, s0
	ds_write_b16 v81, v16 offset:4896
	v_cvt_pk_bf16_f32 v16, v19, s0
	v_add_u32_e32 v17, v149, v185
	ds_write_b16 v17, v16
	v_cvt_pk_bf16_f32 v16, v20, s0
	ds_write_b16 v81, v16 offset:5760
	v_cvt_pk_bf16_f32 v16, v21, s0
	ds_write_b16 v81, v16 offset:5904
	v_cvt_pk_bf16_f32 v16, v22, s0
	ds_write_b16 v81, v16 offset:6048
	v_cvt_pk_bf16_f32 v16, v23, s0
	v_add_u32_e32 v17, v149, v186
	ds_write_b16 v17, v16
	v_cvt_pk_bf16_f32 v16, v24, s0
	ds_write_b16 v81, v16 offset:6912
	v_cvt_pk_bf16_f32 v16, v25, s0
	ds_write_b16 v81, v16 offset:7056
	v_cvt_pk_bf16_f32 v16, v26, s0
	ds_write_b16 v81, v16 offset:7200
	v_cvt_pk_bf16_f32 v16, v27, s0
	v_add_u32_e32 v17, v149, v187
	ds_write_b16 v17, v16
	v_cvt_pk_bf16_f32 v16, v28, s0
	ds_write_b16 v81, v16 offset:8064
	v_cvt_pk_bf16_f32 v16, v29, s0
	ds_write_b16 v81, v16 offset:8208
	v_cvt_pk_bf16_f32 v16, v30, s0
	ds_write_b16 v81, v16 offset:8352
	v_cvt_pk_bf16_f32 v16, v31, s0
	v_add_u32_e32 v17, v149, v188
	v_cvt_pk_bf16_f32 v0, v0, s0
	ds_write_b16 v17, v16
	ds_write_b16 v48, v0 offset:4608
	v_cvt_pk_bf16_f32 v0, v1, s0
	ds_write_b16 v48, v0 offset:4752
	v_cvt_pk_bf16_f32 v0, v2, s0
	ds_write_b16 v48, v0 offset:4896
	v_cvt_pk_bf16_f32 v0, v3, s0
	v_add_u32_e32 v1, v184, v185
	ds_write_b16 v1, v0
	v_cvt_pk_bf16_f32 v0, v4, s0
	ds_write_b16 v48, v0 offset:5760
	v_cvt_pk_bf16_f32 v0, v5, s0
	ds_write_b16 v48, v0 offset:5904
	v_cvt_pk_bf16_f32 v0, v6, s0
	ds_write_b16 v48, v0 offset:6048
	v_cvt_pk_bf16_f32 v0, v7, s0
	v_add_u32_e32 v1, v184, v186
	ds_write_b16 v1, v0
	v_cvt_pk_bf16_f32 v0, v8, s0
	ds_write_b16 v48, v0 offset:6912
	v_cvt_pk_bf16_f32 v0, v9, s0
	s_cmp_eq_u32 s15, 2
	s_brev_b32 s20, 8
	ds_write_b16 v48, v0 offset:7056
	v_cvt_pk_bf16_f32 v0, v10, s0
	s_cselect_b32 s20, s20, 0x14000000
	s_cmp_lg_u32 s15, 1
	ds_write_b16 v48, v0 offset:7200
	v_cvt_pk_bf16_f32 v0, v11, s0
	v_add_u32_e32 v1, v184, v187
	s_cselect_b32 s15, s20, 0xc000000
	s_cmp_gt_u32 s14, 7
	ds_write_b16 v1, v0
	v_cvt_pk_bf16_f32 v0, v12, s0
	s_cselect_b32 s15, s15, 0x8000000
	v_lshl_add_u32 v82, s88, 7, v133
	ds_write_b16 v48, v0 offset:8064
	v_cvt_pk_bf16_f32 v0, v13, s0
	s_add_u32 s20, s0, s15
	v_ashrrev_i32_e32 v83, 31, v82
	ds_write_b16 v48, v0 offset:8208
	v_cvt_pk_bf16_f32 v0, v14, s0
	s_addc_u32 s21, s1, 0
	v_lshlrev_b64 v[82:83], 11, v[82:83]
	s_lshl_b32 s14, s14, 8
	ds_write_b16 v48, v0 offset:8352
	v_cvt_pk_bf16_f32 v0, v15, s0
	v_add_u32_e32 v1, v184, v188
	v_add_u32_e32 v8, v189, v190
	v_lshl_add_u64 v[82:83], s[20:21], 0, v[82:83]
	s_and_b32 s74, s14, 0x700
	ds_write_b16 v1, v0
	ds_read_b128 v[0:3], v8
	v_lshl_add_u64 v[82:83], v[82:83], 0, s[74:75]
	v_mov_b32_e32 v159, v80
	v_lshl_add_u64 v[82:83], v[82:83], 0, v[158:159]
	v_lshlrev_b32_e32 v4, 1, v132
	v_mov_b32_e32 v5, v80
	v_lshl_add_u64 v[4:5], v[82:83], 0, v[4:5]
	v_mov_b32_e32 v161, v80
	v_lshl_add_u64 v[6:7], v[4:5], 0, v[160:161]
	s_waitcnt lgkmcnt(0)
	global_store_dwordx4 v[6:7], v[0:3], off
	ds_read_b128 v[0:3], v8 offset:1152
	v_mov_b32_e32 v163, v80
	v_lshl_add_u64 v[6:7], v[4:5], 0, v[162:163]
	v_mov_b32_e32 v165, v80
	v_mov_b32_e32 v167, v80
	s_waitcnt lgkmcnt(0)
	global_store_dwordx4 v[6:7], v[0:3], off
	ds_read_b128 v[0:3], v8 offset:2304
	v_lshl_add_u64 v[6:7], v[4:5], 0, v[164:165]
	v_mov_b32_e32 v169, v80
	v_mov_b32_e32 v171, v80
	v_mov_b32_e32 v173, v80
	s_waitcnt lgkmcnt(0)
	global_store_dwordx4 v[6:7], v[0:3], off
	ds_read_b128 v[0:3], v8 offset:3456
	v_lshl_add_u64 v[6:7], v[4:5], 0, v[166:167]
	v_mov_b32_e32 v175, v80
	s_waitcnt lgkmcnt(0)
	global_store_dwordx4 v[6:7], v[0:3], off
	ds_read_b128 v[0:3], v8 offset:4608
	v_lshl_add_u64 v[6:7], v[4:5], 0, v[168:169]
	s_waitcnt lgkmcnt(0)
	global_store_dwordx4 v[6:7], v[0:3], off
	ds_read_b128 v[0:3], v8 offset:5760
	v_lshl_add_u64 v[6:7], v[4:5], 0, v[170:171]
	s_waitcnt lgkmcnt(0)
	global_store_dwordx4 v[6:7], v[0:3], off
	ds_read_b128 v[0:3], v8 offset:6912
	v_lshl_add_u64 v[6:7], v[4:5], 0, v[172:173]
	v_lshl_add_u64 v[4:5], v[4:5], 0, v[174:175]
	s_waitcnt lgkmcnt(0)
	global_store_dwordx4 v[6:7], v[0:3], off
	ds_read_b128 v[0:3], v8 offset:8064
	s_waitcnt lgkmcnt(0)
	global_store_dwordx4 v[4:5], v[0:3], off

.LBB0_176:
	s_add_i32 s20, s71, 2
	s_cmp_lt_i32 s20, s90
	s_cselect_b64 s[82:83], -1, 0
	s_cmp_ge_i32 s20, s90
	s_cselect_b64 s[80:81], -1, 0
	s_and_b64 vcc, exec, s[80:81]
	s_cbranch_vccnz .LBB0_180
	s_add_i32 s74, s15, 0x800
	s_cmp_lt_u32 s71, 14
	s_cselect_b64 s[84:85], -1, 0
	s_and_b64 vcc, s[84:85], exec
	s_cselect_b32 vcc_lo, s74, s15
	v_mov_b32_e32 v81, v80
	s_ashr_i32 vcc_hi, vcc_lo, 31
	v_mov_b32_e32 v82, v80
	v_mov_b32_e32 v83, v80
	s_waitcnt vmcnt(8)
	v_mov_b64_e32 v[64:65], v[80:81]
	v_lshl_add_u64 v[120:121], vcc, 1, v[178:179]
	s_or_b64 vcc, s[84:85], s[4:5]
	v_mov_b64_e32 v[66:67], v[82:83]
	s_and_saveexec_b64 s[84:85], vcc
	s_cbranch_execz .LBB0_179
	global_load_dwordx4 v[64:67], v[120:121], off
.LBB0_179:
	s_or_b64 exec, exec, s[84:85]
	v_add_co_u32_e32 v88, vcc, 0x10000, v120
	v_lshl_add_u64 v[82:83], s[74:75], 1, v[176:177]
	s_nop 0
	v_addc_co_u32_e32 v89, vcc, 0, v121, vcc
	v_add_co_u32_e32 v104, vcc, 0x20000, v120
	global_load_dwordx4 v[76:79], v[82:83], off
	v_lshl_add_u64 v[82:83], s[76:77], 1, v[82:83]
	v_addc_co_u32_e32 v105, vcc, 0, v121, vcc
	global_load_dwordx4 v[96:99], v[88:89], off
	global_load_dwordx4 v[112:115], v[104:105], off
	v_add_co_u32_e32 v120, vcc, 0x30000, v120
	global_load_dwordx4 v[88:91], v[82:83], off
	v_lshl_add_u64 v[82:83], v[82:83], 0, s[78:79]
	global_load_dwordx4 v[104:107], v[82:83], off
	v_addc_co_u32_e32 v121, vcc, 0, v121, vcc
	v_lshl_add_u64 v[82:83], v[82:83], 0, s[78:79]
	global_load_dwordx4 v[128:131], v[120:121], off
	s_nop 0
	global_load_dwordx4 v[120:123], v[82:83], off
.LBB0_180:
	v_add_u32_e32 v157, v137, v139
	ds_read_b128 v[198:201], v157
	v_add_u32_e32 v165, v137, v141
	ds_read_b128 v[202:205], v165 offset:16384
	ds_read_b128 v[206:209], v165 offset:20480
	v_add_u32_e32 v159, v143, v139
	v_add_u32_e32 v167, v143, v141
	v_add_u32_e32 v161, v153, v139
	v_add_u32_e32 v169, v153, v141
	v_add_u32_e32 v163, v155, v139
	s_waitcnt lgkmcnt(0)
	v_mfma_f32_32x32x16_bf16 v[48:63], v[198:201], v[202:205], v[48:63]
	v_add_u32_e32 v171, v155, v141
	s_add_i32 s21, s71, 3
	s_cmp_ge_i32 s21, s90
	v_mfma_f32_32x32x16_bf16 v[32:47], v[198:201], v[206:209], v[32:47]
	ds_read_b128 v[198:201], v157 offset:4096
	s_waitcnt lgkmcnt(0)
	v_mfma_f32_32x32x16_bf16 v[16:31], v[198:201], v[202:205], v[16:31]
	ds_read_b128 v[202:205], v167 offset:16384
	v_mfma_f32_32x32x16_bf16 v[0:15], v[198:201], v[206:209], v[0:15]
	ds_read_b128 v[198:201], v159
	ds_read_b128 v[206:209], v167 offset:20480
	s_waitcnt lgkmcnt(0)
	v_mfma_f32_32x32x16_bf16 v[48:63], v[198:201], v[202:205], v[48:63]
	v_mfma_f32_32x32x16_bf16 v[32:47], v[198:201], v[206:209], v[32:47]
	ds_read_b128 v[198:201], v159 offset:4096
	s_waitcnt lgkmcnt(0)
	v_mfma_f32_32x32x16_bf16 v[16:31], v[198:201], v[202:205], v[16:31]
	ds_read_b128 v[202:205], v169 offset:16384
	v_mfma_f32_32x32x16_bf16 v[0:15], v[198:201], v[206:209], v[0:15]
	ds_read_b128 v[198:201], v161
	ds_read_b128 v[206:209], v169 offset:20480
	s_waitcnt lgkmcnt(0)
	v_mfma_f32_32x32x16_bf16 v[48:63], v[198:201], v[202:205], v[48:63]
	v_mfma_f32_32x32x16_bf16 v[32:47], v[198:201], v[206:209], v[32:47]
	ds_read_b128 v[198:201], v161 offset:4096
	s_waitcnt lgkmcnt(0)
	v_mfma_f32_32x32x16_bf16 v[16:31], v[198:201], v[202:205], v[16:31]
	ds_read_b128 v[202:205], v171 offset:16384
	v_mfma_f32_32x32x16_bf16 v[0:15], v[198:201], v[206:209], v[0:15]
	ds_read_b128 v[198:201], v163
	ds_read_b128 v[206:209], v171 offset:20480
	s_waitcnt lgkmcnt(0)
	v_mfma_f32_32x32x16_bf16 v[48:63], v[198:201], v[202:205], v[48:63]
	v_mfma_f32_32x32x16_bf16 v[32:47], v[198:201], v[206:209], v[32:47]
	ds_read_b128 v[198:201], v163 offset:4096
	s_mov_b64 vcc, s[80:81]
	s_cbranch_vccnz .Lgm1_cw0
	s_waitcnt vmcnt(8)
	s_branch .Lgm1_cw1

.Lgm1_cw1:
	ds_write_b128 v135, v[68:71] offset:32768
	ds_write_b128 v135, v[72:75] offset:49152
	ds_write_b128 v135, v[92:95] offset:36864
	ds_write_b128 v135, v[84:87] offset:53248
	ds_write_b128 v135, v[108:111] offset:40960
	ds_write_b128 v135, v[100:103] offset:57344
	ds_write_b128 v135, v[124:127] offset:45056
	ds_write_b128 v135, v[116:119] offset:61440
	s_waitcnt lgkmcnt(0)
	s_barrier
	v_mfma_f32_32x32x16_bf16 v[16:31], v[198:201], v[202:205], v[16:31]
	v_mfma_f32_32x32x16_bf16 v[0:15], v[198:201], v[206:209], v[0:15]
	s_cbranch_scc1 .LBB0_184
	s_add_i32 s21, s15, 64
	s_add_i32 s74, s15, 0x840
	s_cmp_lt_u32 s71, 13
	s_cselect_b64 s[84:85], -1, 0
	s_and_b64 vcc, s[84:85], exec
	s_cselect_b32 vcc_lo, s74, s21
	v_mov_b32_e32 v81, v80
	s_ashr_i32 vcc_hi, vcc_lo, 31
	v_mov_b32_e32 v82, v80
	v_mov_b32_e32 v83, v80
	v_mov_b64_e32 v[68:69], v[80:81]
	v_lshl_add_u64 v[116:117], vcc, 1, v[178:179]
	s_or_b64 vcc, s[84:85], s[4:5]
	v_mov_b64_e32 v[70:71], v[82:83]
	s_and_saveexec_b64 s[84:85], vcc
	s_cbranch_execz .LBB0_183
	global_load_dwordx4 v[68:71], v[116:117], off
.LBB0_183:
	s_or_b64 exec, exec, s[84:85]
	v_add_co_u32_e32 v84, vcc, 0x10000, v116
	v_lshl_add_u64 v[82:83], s[74:75], 1, v[176:177]
	s_nop 0
	v_addc_co_u32_e32 v85, vcc, 0, v117, vcc
	v_add_co_u32_e32 v100, vcc, 0x20000, v116
	global_load_dwordx4 v[72:75], v[82:83], off
	v_lshl_add_u64 v[82:83], s[76:77], 1, v[82:83]
	v_addc_co_u32_e32 v101, vcc, 0, v117, vcc
	global_load_dwordx4 v[92:95], v[84:85], off
	global_load_dwordx4 v[108:111], v[100:101], off
	v_add_co_u32_e32 v116, vcc, 0x30000, v116
	global_load_dwordx4 v[84:87], v[82:83], off
	v_lshl_add_u64 v[82:83], v[82:83], 0, s[78:79]
	global_load_dwordx4 v[100:103], v[82:83], off
	v_addc_co_u32_e32 v117, vcc, 0, v117, vcc
	v_lshl_add_u64 v[82:83], v[82:83], 0, s[78:79]
	global_load_dwordx4 v[124:127], v[116:117], off
	s_nop 0
	global_load_dwordx4 v[116:119], v[82:83], off
.LBB0_184:
	ds_read_b128 v[198:201], v157 offset:32768
	ds_read_b128 v[202:205], v165 offset:49152
	ds_read_b128 v[206:209], v165 offset:53248
	s_andn2_b64 vcc, exec, s[82:83]
	s_waitcnt lgkmcnt(0)
	v_mfma_f32_32x32x16_bf16 v[48:63], v[198:201], v[202:205], v[48:63]
	v_mfma_f32_32x32x16_bf16 v[32:47], v[198:201], v[206:209], v[32:47]
	ds_read_b128 v[198:201], v157 offset:36864
	s_waitcnt lgkmcnt(0)
	v_mfma_f32_32x32x16_bf16 v[16:31], v[198:201], v[202:205], v[16:31]
	v_mfma_f32_32x32x16_bf16 v[0:15], v[198:201], v[206:209], v[0:15]
	ds_read_b128 v[198:201], v159 offset:32768
	ds_read_b128 v[202:205], v167 offset:49152
	ds_read_b128 v[206:209], v167 offset:53248
	s_waitcnt lgkmcnt(0)
	v_mfma_f32_32x32x16_bf16 v[48:63], v[198:201], v[202:205], v[48:63]
	v_mfma_f32_32x32x16_bf16 v[32:47], v[198:201], v[206:209], v[32:47]
	ds_read_b128 v[198:201], v159 offset:36864
	s_waitcnt lgkmcnt(0)
	v_mfma_f32_32x32x16_bf16 v[16:31], v[198:201], v[202:205], v[16:31]
	v_mfma_f32_32x32x16_bf16 v[0:15], v[198:201], v[206:209], v[0:15]
	ds_read_b128 v[198:201], v161 offset:32768
	ds_read_b128 v[202:205], v169 offset:49152
	ds_read_b128 v[206:209], v169 offset:53248
	s_waitcnt lgkmcnt(0)
	v_mfma_f32_32x32x16_bf16 v[48:63], v[198:201], v[202:205], v[48:63]
	v_mfma_f32_32x32x16_bf16 v[32:47], v[198:201], v[206:209], v[32:47]
	ds_read_b128 v[198:201], v161 offset:36864
	s_waitcnt lgkmcnt(0)
	v_mfma_f32_32x32x16_bf16 v[16:31], v[198:201], v[202:205], v[16:31]
	v_mfma_f32_32x32x16_bf16 v[0:15], v[198:201], v[206:209], v[0:15]
	ds_read_b128 v[198:201], v163 offset:32768
	ds_read_b128 v[202:205], v171 offset:49152
	ds_read_b128 v[206:209], v171 offset:53248
	s_waitcnt lgkmcnt(0)
	v_mfma_f32_32x32x16_bf16 v[48:63], v[198:201], v[202:205], v[48:63]
	v_mfma_f32_32x32x16_bf16 v[32:47], v[198:201], v[206:209], v[32:47]
	ds_read_b128 v[198:201], v163 offset:36864
	s_waitcnt lgkmcnt(0)
	v_mfma_f32_32x32x16_bf16 v[16:31], v[198:201], v[202:205], v[16:31]
	v_mfma_f32_32x32x16_bf16 v[0:15], v[198:201], v[206:209], v[0:15]
	s_cbranch_vccnz .LBB0_186
	s_waitcnt vmcnt(8)
	ds_write_b128 v135, v[64:67]
	ds_write_b128 v135, v[76:79] offset:16384
	ds_write_b128 v135, v[96:99] offset:4096
	ds_write_b128 v135, v[88:91] offset:20480
	ds_write_b128 v135, v[112:115] offset:8192
	ds_write_b128 v135, v[104:107] offset:24576
	ds_write_b128 v135, v[128:131] offset:12288
	ds_write_b128 v135, v[120:123] offset:28672

.LBB0_200:
	s_waitcnt vmcnt(0)
	v_mov_b32_e32 v66, v196
	v_mov_b32_e32 v67, v80
	v_ashrrev_i32_e32 v70, 3, v66
	v_add_u32_e32 v64, s91, v70
	v_ashrrev_i32_e32 v65, 31, v64
	v_lshlrev_b64 v[64:65], 11, v[64:65]
	v_lshlrev_b32_e32 v66, 4, v66
	v_lshl_add_u64 v[64:65], s[68:69], 0, v[64:65]
	v_and_b32_e32 v66, 0x70, v66
	v_lshl_add_u64 v[68:69], v[64:65], 0, v[66:67]
	v_add_u32_e32 v64, s89, v70
	s_mov_b32 s15, 0x10000
	v_mad_i64_i32 v[64:65], s[20:21], v64, s70, 0
	v_add_co_u32_e32 v82, vcc, s15, v68
	s_ashr_i32 s71, s70, 31
	v_lshl_add_u64 v[64:65], v[64:65], 1, s[72:73]
	v_addc_co_u32_e32 v83, vcc, 0, v69, vcc
	s_mov_b32 s15, 0x20000
	v_lshl_add_u64 v[72:73], v[64:65], 0, v[66:67]
	s_lshl_b64 s[20:21], s[70:71], 6
	v_add_co_u32_e32 v100, vcc, s15, v68
	v_lshl_add_u64 v[84:85], v[72:73], 0, s[20:21]
	s_nop 0
	v_addc_co_u32_e32 v101, vcc, 0, v69, vcc
	v_lshl_add_u64 v[102:103], v[84:85], 0, s[20:21]
	v_add_co_u32_e32 v116, vcc, 0x30000, v68
	v_lshl_add_u64 v[118:119], v[102:103], 0, s[20:21]
	s_nop 0
	v_addc_co_u32_e32 v117, vcc, 0, v69, vcc
	global_load_dwordx4 v[64:67], v[68:69], off
	s_nop 0
	global_load_dwordx4 v[68:71], v[68:69], off offset:128
	s_nop 0
	global_load_dwordx4 v[76:79], v[72:73], off
	s_nop 0
	global_load_dwordx4 v[72:75], v[72:73], off offset:128
	s_nop 0
	global_load_dwordx4 v[96:99], v[82:83], off
	global_load_dwordx4 v[92:95], v[82:83], off offset:128
	global_load_dwordx4 v[88:91], v[84:85], off
	s_nop 0
	global_load_dwordx4 v[84:87], v[84:85], off offset:128
	s_nop 0
	global_load_dwordx4 v[112:115], v[100:101], off
	global_load_dwordx4 v[108:111], v[100:101], off offset:128
	global_load_dwordx4 v[104:107], v[102:103], off
	s_nop 0
	global_load_dwordx4 v[100:103], v[102:103], off offset:128
	s_nop 0
	global_load_dwordx4 v[128:131], v[116:117], off
	global_load_dwordx4 v[124:127], v[116:117], off offset:128
	global_load_dwordx4 v[120:123], v[118:119], off
	s_nop 0
	global_load_dwordx4 v[116:119], v[118:119], off offset:128

.LBB0_460:
	s_or_b64 exec, exec, s[76:77]
	v_lshl_add_u32 v146, s88, 7, v133
	v_ashrrev_i32_e32 v147, 31, v146
	v_lshl_add_u64 v[82:83], s[0:1], 0, v[82:83]
	v_lshlrev_b64 v[146:147], 7, v[146:147]
	v_lshl_add_u64 v[82:83], v[82:83], 0, v[146:147]
	v_cvt_pk_bf16_f32 v145, v201, s0
	v_add_u32_e32 v146, v149, v151
	ds_write_b16 v146, v145
	v_cvt_pk_bf16_f32 v145, v198, s0
	ds_write_b16 v146, v145 offset:144
	v_cvt_pk_bf16_f32 v145, v199, s0
	ds_write_b16 v146, v145 offset:288
	v_cvt_pk_bf16_f32 v145, v200, s0
	v_add_u32_e32 v147, v149, v180
	ds_write_b16 v147, v145
	v_cvt_pk_bf16_f32 v145, v193, s0
	ds_write_b16 v146, v145 offset:1152
	v_cvt_pk_bf16_f32 v145, v194, s0
	ds_write_b16 v146, v145 offset:1296
	v_cvt_pk_bf16_f32 v145, v195, s0
	ds_write_b16 v146, v145 offset:1440
	v_cvt_pk_bf16_f32 v145, v197, s0
	v_add_u32_e32 v147, v149, v181
	v_cvt_pk_bf16_f32 v143, v143, s0
	ds_write_b16 v147, v145
	ds_write_b16 v146, v143 offset:2304
	v_cvt_pk_bf16_f32 v143, v153, s0
	ds_write_b16 v146, v143 offset:2448
	v_cvt_pk_bf16_f32 v143, v155, s0
	ds_write_b16 v146, v143 offset:2592
	v_cvt_pk_bf16_f32 v143, v157, s0
	v_add_u32_e32 v145, v149, v182
	v_cvt_pk_bf16_f32 v135, v135, s0
	ds_write_b16 v145, v143
	ds_write_b16 v146, v135 offset:3456
	v_cvt_pk_bf16_f32 v135, v137, s0
	ds_write_b16 v146, v135 offset:3600
	v_cvt_pk_bf16_f32 v135, v139, s0
	ds_write_b16 v146, v135 offset:3744
	v_cvt_pk_bf16_f32 v135, v141, s0
	v_add_u32_e32 v137, v149, v183
	ds_write_b16 v137, v135
	v_cvt_pk_bf16_f32 v135, v217, s0
	v_add_u32_e32 v137, v184, v151
	ds_write_b16 v137, v135
	v_cvt_pk_bf16_f32 v135, v214, s0
	ds_write_b16 v137, v135 offset:144
	v_cvt_pk_bf16_f32 v135, v215, s0
	ds_write_b16 v137, v135 offset:288
	v_cvt_pk_bf16_f32 v135, v216, s0
	v_add_u32_e32 v139, v184, v180
	ds_write_b16 v139, v135
	v_cvt_pk_bf16_f32 v135, v210, s0
	ds_write_b16 v137, v135 offset:1152
	v_cvt_pk_bf16_f32 v135, v211, s0
	ds_write_b16 v137, v135 offset:1296
	v_cvt_pk_bf16_f32 v135, v212, s0
	ds_write_b16 v137, v135 offset:1440
	v_cvt_pk_bf16_f32 v135, v213, s0
	v_add_u32_e32 v139, v184, v181
	ds_write_b16 v139, v135
	v_cvt_pk_bf16_f32 v135, v176, s0
	ds_write_b16 v137, v135 offset:2304
	v_cvt_pk_bf16_f32 v135, v177, s0
	ds_write_b16 v137, v135 offset:2448
	v_cvt_pk_bf16_f32 v135, v178, s0
	ds_write_b16 v137, v135 offset:2592
	v_cvt_pk_bf16_f32 v135, v179, s0
	v_add_u32_e32 v139, v184, v182
	ds_write_b16 v139, v135
	v_cvt_pk_bf16_f32 v135, v169, s0
	ds_write_b16 v137, v135 offset:3456
	v_cvt_pk_bf16_f32 v135, v171, s0
	ds_write_b16 v137, v135 offset:3600
	v_cvt_pk_bf16_f32 v135, v173, s0
	ds_write_b16 v137, v135 offset:3744
	v_cvt_pk_bf16_f32 v135, v175, s0
	v_add_u32_e32 v139, v184, v183
	ds_write_b16 v139, v135
	v_cvt_pk_bf16_f32 v135, v237, s0
	ds_write_b16 v146, v135 offset:4608
	v_cvt_pk_bf16_f32 v135, v238, s0
	ds_write_b16 v146, v135 offset:4752
	v_cvt_pk_bf16_f32 v135, v239, s0
	ds_write_b16 v146, v135 offset:4896
	v_cvt_pk_bf16_f32 v135, v240, s0
	v_add_u32_e32 v139, v149, v185
	ds_write_b16 v139, v135
	v_cvt_pk_bf16_f32 v135, v226, s0
	ds_write_b16 v146, v135 offset:5760
	v_cvt_pk_bf16_f32 v135, v234, s0
	ds_write_b16 v146, v135 offset:5904
	v_cvt_pk_bf16_f32 v135, v235, s0
	ds_write_b16 v146, v135 offset:6048
	v_cvt_pk_bf16_f32 v135, v236, s0
	v_add_u32_e32 v139, v149, v186
	ds_write_b16 v139, v135
	v_cvt_pk_bf16_f32 v135, v206, s0
	ds_write_b16 v146, v135 offset:6912
	v_cvt_pk_bf16_f32 v135, v207, s0
	ds_write_b16 v146, v135 offset:7056
	v_cvt_pk_bf16_f32 v135, v208, s0
	ds_write_b16 v146, v135 offset:7200
	v_cvt_pk_bf16_f32 v135, v209, s0
	v_add_u32_e32 v139, v149, v187
	ds_write_b16 v139, v135
	v_cvt_pk_bf16_f32 v135, v202, s0
	ds_write_b16 v146, v135 offset:8064
	v_cvt_pk_bf16_f32 v135, v203, s0
	ds_write_b16 v146, v135 offset:8208
	v_cvt_pk_bf16_f32 v135, v204, s0
	ds_write_b16 v146, v135 offset:8352
	v_cvt_pk_bf16_f32 v135, v205, s0
	v_add_u32_e32 v139, v149, v188
	ds_write_b16 v139, v135
	v_cvt_pk_bf16_f32 v135, v230, s0
	ds_write_b16 v137, v135 offset:4608
	v_cvt_pk_bf16_f32 v135, v231, s0
	ds_write_b16 v137, v135 offset:4752
	v_cvt_pk_bf16_f32 v135, v232, s0
	ds_write_b16 v137, v135 offset:4896
	v_cvt_pk_bf16_f32 v135, v233, s0
	v_add_u32_e32 v139, v184, v185
	ds_write_b16 v139, v135
	v_cvt_pk_bf16_f32 v135, v227, s0
	ds_write_b16 v137, v135 offset:5760
	v_cvt_pk_bf16_f32 v135, v228, s0
	ds_write_b16 v137, v135 offset:5904
	v_cvt_pk_bf16_f32 v135, v229, s0
	ds_write_b16 v137, v135 offset:6048
	v_cvt_pk_bf16_f32 v135, v225, s0
	v_add_u32_e32 v139, v184, v186
	ds_write_b16 v139, v135
	v_cvt_pk_bf16_f32 v135, v221, s0
	ds_write_b16 v137, v135 offset:6912
	v_cvt_pk_bf16_f32 v135, v222, s0
	ds_write_b16 v137, v135 offset:7056
	v_cvt_pk_bf16_f32 v135, v223, s0
	ds_write_b16 v137, v135 offset:7200
	v_cvt_pk_bf16_f32 v135, v224, s0
	v_add_u32_e32 v139, v184, v187
	ds_write_b16 v139, v135
	v_cvt_pk_bf16_f32 v135, v218, s0
	ds_write_b16 v137, v135 offset:8064
	v_cvt_pk_bf16_f32 v135, v219, s0
	ds_write_b16 v137, v135 offset:8208
	v_cvt_pk_bf16_f32 v135, v220, s0
	ds_write_b16 v137, v135 offset:8352
	v_cvt_pk_bf16_f32 v81, v81, s0
	v_add_u32_e32 v135, v184, v188
	ds_write_b16 v135, v81
	v_add_u32_e32 v81, v189, v190
	ds_read_b128 v[176:179], v81
	v_lshlrev_b32_e32 v146, 1, v132
	v_mov_b32_e32 v147, v80
	v_lshl_add_u64 v[82:83], v[82:83], 0, v[146:147]
	v_mov_b32_e32 v135, v80
	v_lshl_add_u64 v[146:147], v[82:83], 0, v[134:135]
	s_waitcnt lgkmcnt(0)
	global_store_dwordx4 v[146:147], v[176:179], off
	ds_read_b128 v[176:179], v81 offset:1152
	v_mov_b32_e32 v137, v80
	v_lshl_add_u64 v[146:147], v[82:83], 0, v[136:137]
	v_mov_b32_e32 v139, v80
	v_mov_b32_e32 v141, v80
	s_waitcnt lgkmcnt(0)
	global_store_dwordx4 v[146:147], v[176:179], off
	ds_read_b128 v[176:179], v81 offset:2304
	v_lshl_add_u64 v[146:147], v[82:83], 0, v[138:139]
	v_mov_b32_e32 v143, v80
	v_mov_b32_e32 v153, v80
	v_mov_b32_e32 v155, v80
	s_waitcnt lgkmcnt(0)
	global_store_dwordx4 v[146:147], v[176:179], off
	ds_read_b128 v[176:179], v81 offset:3456
	v_lshl_add_u64 v[146:147], v[82:83], 0, v[140:141]
	v_mov_b32_e32 v157, v80
	s_waitcnt lgkmcnt(0)
	global_store_dwordx4 v[146:147], v[176:179], off
	ds_read_b128 v[176:179], v81 offset:4608
	v_lshl_add_u64 v[146:147], v[82:83], 0, v[142:143]
	s_waitcnt lgkmcnt(0)
	global_store_dwordx4 v[146:147], v[176:179], off
	ds_read_b128 v[176:179], v81 offset:5760
	v_lshl_add_u64 v[146:147], v[82:83], 0, v[152:153]
	s_waitcnt lgkmcnt(0)
	global_store_dwordx4 v[146:147], v[176:179], off
	ds_read_b128 v[176:179], v81 offset:6912
	v_lshl_add_u64 v[146:147], v[82:83], 0, v[154:155]
	v_lshl_add_u64 v[82:83], v[82:83], 0, v[156:157]
	s_waitcnt lgkmcnt(0)
	global_store_dwordx4 v[146:147], v[176:179], off
	ds_read_b128 v[176:179], v81 offset:8064
	s_waitcnt lgkmcnt(0)
	global_store_dwordx4 v[82:83], v[176:179], off
	s_branch .LBB0_174

.LBB0_879:
	s_or_b64 exec, exec, s[0:1]
	s_add_u32 s28, s56, 0x1c000000
	s_addc_u32 s29, s57, 0
	s_add_u32 s0, s56, 0x900000
	s_addc_u32 s1, s57, 0
	s_cmpk_lt_u32 s12, 0x800
	s_mov_b64 s[2:3], s[28:29]
	v_mov_b32_e32 v0, v196
	s_cselect_b64 s[24:25], -1, 0
	s_cmpk_gt_u32 s12, 0x7ff
	s_waitcnt lgkmcnt(0)
	s_barrier
	s_cbranch_scc1 .LBB0_892
	s_lshr_b32 s4, s12, 6
	s_and_b32 s4, s4, 24
	s_bfe_u32 s5, s12, 0x30003
	s_or_b32 s4, s4, s5
	s_or_b32 s8, s4, s96
	v_mov_b32_e32 v1, v196
	s_lshl_b32 s10, s8, 7
	s_bfe_u32 s9, s12, 0x30006
	v_ashrrev_i32_e32 v4, 3, v1
	v_add_u32_e32 v2, s10, v4
	s_lshl_b32 s11, s9, 7
	v_ashrrev_i32_e32 v3, 31, v2
	v_lshlrev_b64 v[2:3], 11, v[2:3]
	v_lshlrev_b32_e32 v1, 4, v1
	v_add_u32_e32 v4, s11, v4
	v_lshl_add_u64 v[2:3], s[2:3], 0, v[2:3]
	v_and_b32_e32 v128, 0x70, v1
	v_mov_b32_e32 v129, 0
	v_ashrrev_i32_e32 v5, 31, v4
	v_lshl_add_u64 v[2:3], v[2:3], 0, v[128:129]
	v_lshlrev_b64 v[4:5], 11, v[4:5]
	s_mov_b32 s14, 0x10000
	v_lshl_add_u64 v[4:5], s[0:1], 0, v[4:5]
	v_add_co_u32_e32 v6, vcc, s14, v2
	v_lshl_add_u64 v[4:5], v[4:5], 0, v[128:129]
	s_nop 0
	v_addc_co_u32_e32 v7, vcc, 0, v3, vcc
	v_add_co_u32_e32 v8, vcc, s14, v4
	s_mov_b32 s15, 0x20000
	s_nop 0
	v_addc_co_u32_e32 v9, vcc, 0, v5, vcc
	v_add_co_u32_e32 v10, vcc, s15, v2
	s_mov_b32 s4, 0x30000
	s_nop 0
	v_addc_co_u32_e32 v11, vcc, 0, v3, vcc
	v_add_co_u32_e32 v12, vcc, s15, v4
	v_ashrrev_i32_e32 v1, 1, v0
	s_nop 0
	v_addc_co_u32_e32 v13, vcc, 0, v5, vcc
	v_add_co_u32_e32 v14, vcc, s4, v2
	v_and_b32_e32 v138, 0xffffffc0, v1
	s_nop 0
	v_addc_co_u32_e32 v15, vcc, 0, v3, vcc
	v_add_co_u32_e32 v16, vcc, s4, v4
	v_lshrrev_b32_e32 v1, 3, v0
	s_nop 0
	v_addc_co_u32_e32 v17, vcc, 0, v5, vcc
	global_load_dwordx4 v[64:67], v[2:3], off
	global_load_dwordx4 v[68:71], v[2:3], off offset:128
	global_load_dwordx4 v[72:75], v[4:5], off
	global_load_dwordx4 v[76:79], v[4:5], off offset:128
	global_load_dwordx4 v[80:83], v[6:7], off
	global_load_dwordx4 v[84:87], v[6:7], off offset:128
	global_load_dwordx4 v[88:91], v[8:9], off
	global_load_dwordx4 v[92:95], v[8:9], off offset:128
	global_load_dwordx4 v[96:99], v[10:11], off
	global_load_dwordx4 v[100:103], v[10:11], off offset:128
	global_load_dwordx4 v[104:107], v[12:13], off
	global_load_dwordx4 v[108:111], v[12:13], off offset:128
	global_load_dwordx4 v[112:115], v[14:15], off
	global_load_dwordx4 v[116:119], v[14:15], off offset:128
	global_load_dwordx4 v[120:123], v[16:17], off
	global_load_dwordx4 v[124:127], v[16:17], off offset:128
	s_movk_i32 s33, 0x70
	v_and_b32_e32 v139, 4, v1
	v_and_b32_e32 v140, 0x5f, v0
	s_mov_b32 s35, 0x1ffffc0
	s_mov_b64 s[4:5], 0x100
	s_mov_b32 s36, s95
	s_branch .LBB0_882

.LBB0_884:
	s_cmp_lt_u32 s39, 14
	s_cselect_b64 s[8:9], -1, 0
	s_cmp_gt_u32 s39, 13
	s_cselect_b64 s[6:7], -1, 0
	s_and_b64 vcc, exec, s[6:7]
	v_lshl_add_u64 v[136:137], v[132:133], 0, v[128:129]
	v_lshl_add_u64 v[134:135], v[130:131], 0, v[128:129]
	s_cbranch_vccnz .LBB0_886
	s_waitcnt vmcnt(8)
	v_add_co_u32_e32 v80, vcc, 0x10000, v136
	global_load_dwordx4 v[64:67], v[136:137], off offset:256
	global_load_dwordx4 v[72:75], v[134:135], off offset:256
	v_addc_co_u32_e32 v81, vcc, 0, v137, vcc
	v_add_co_u32_e32 v88, vcc, 0x10000, v134
	global_load_dwordx4 v[80:83], v[80:81], off offset:256
	s_nop 0
	v_addc_co_u32_e32 v89, vcc, 0, v135, vcc
	v_add_co_u32_e32 v96, vcc, 0x20000, v136
	global_load_dwordx4 v[88:91], v[88:89], off offset:256
	s_nop 0
	v_addc_co_u32_e32 v97, vcc, 0, v137, vcc
	v_add_co_u32_e32 v104, vcc, 0x20000, v134
	global_load_dwordx4 v[96:99], v[96:97], off offset:256
	s_nop 0
	v_addc_co_u32_e32 v105, vcc, 0, v135, vcc
	v_add_co_u32_e32 v112, vcc, 0x30000, v136
	global_load_dwordx4 v[104:107], v[104:105], off offset:256
	s_nop 0
	v_addc_co_u32_e32 v113, vcc, 0, v137, vcc
	v_add_co_u32_e32 v120, vcc, 0x30000, v134
	global_load_dwordx4 v[112:115], v[112:113], off offset:256
	s_nop 0
	v_addc_co_u32_e32 v121, vcc, 0, v135, vcc
	global_load_dwordx4 v[120:123], v[120:121], off offset:256
.LBB0_886:
	v_add_u32_e32 v151, v142, v143
	ds_read_b128 v[154:157], v151
	v_add_u32_e32 v152, v142, v145
	ds_read_b128 v[158:161], v152 offset:16384
	ds_read_b128 v[162:165], v151 offset:4096
	ds_read_b128 v[166:169], v152 offset:20480
	v_add_u32_e32 v153, v148, v143
	s_waitcnt lgkmcnt(0)
	v_mfma_f32_32x32x16_bf16 v[16:31], v[162:165], v[158:161], v[16:31]
	s_cmp_gt_u32 s39, 12
	v_mfma_f32_32x32x16_bf16 v[48:63], v[154:157], v[158:161], v[48:63]
	v_mfma_f32_32x32x16_bf16 v[32:47], v[154:157], v[166:169], v[32:47]
	ds_read_b128 v[156:159], v153
	v_add_u32_e32 v154, v148, v145
	v_add_u32_e32 v155, v149, v143
	v_mfma_f32_32x32x16_bf16 v[0:15], v[162:165], v[166:169], v[0:15]
	ds_read_b128 v[160:163], v154 offset:16384
	ds_read_b128 v[164:167], v153 offset:4096
	ds_read_b128 v[168:171], v154 offset:20480
	s_waitcnt lgkmcnt(0)
	v_mfma_f32_32x32x16_bf16 v[48:63], v[156:159], v[160:163], v[48:63]
	v_mfma_f32_32x32x16_bf16 v[32:47], v[156:159], v[168:171], v[32:47]
	v_add_u32_e32 v156, v149, v145
	v_add_u32_e32 v157, v150, v143
	v_mfma_f32_32x32x16_bf16 v[16:31], v[164:167], v[160:163], v[16:31]
	ds_read_b128 v[158:161], v155
	v_mfma_f32_32x32x16_bf16 v[0:15], v[164:167], v[168:171], v[0:15]
	ds_read_b128 v[162:165], v156 offset:16384
	ds_read_b128 v[166:169], v155 offset:4096
	ds_read_b128 v[170:173], v156 offset:20480
	s_waitcnt lgkmcnt(0)
	v_mfma_f32_32x32x16_bf16 v[48:63], v[158:161], v[162:165], v[48:63]
	v_mfma_f32_32x32x16_bf16 v[32:47], v[158:161], v[170:173], v[32:47]
	v_add_u32_e32 v158, v150, v145
	v_mfma_f32_32x32x16_bf16 v[16:31], v[166:169], v[162:165], v[16:31]
	ds_read_b128 v[160:163], v157
	v_mfma_f32_32x32x16_bf16 v[0:15], v[166:169], v[170:173], v[0:15]
	ds_read_b128 v[164:167], v158 offset:16384
	ds_read_b128 v[168:171], v157 offset:4096
	ds_read_b128 v[172:175], v158 offset:20480
	s_mov_b64 vcc, s[6:7]
	s_cbranch_vccnz .Lgr1_cw0
	s_waitcnt vmcnt(8)
	s_branch .Lgr1_cw1

.Lgr1_cw1:
	ds_write_b128 v141, v[68:71] offset:32768
	ds_write_b128 v141, v[76:79] offset:49152
	ds_write_b128 v141, v[84:87] offset:36864
	ds_write_b128 v141, v[92:95] offset:53248
	ds_write_b128 v141, v[100:103] offset:40960
	ds_write_b128 v141, v[108:111] offset:57344
	ds_write_b128 v141, v[116:119] offset:45056
	ds_write_b128 v141, v[124:127] offset:61440
	s_waitcnt lgkmcnt(0)
	s_barrier
	v_mfma_f32_32x32x16_bf16 v[48:63], v[160:163], v[164:167], v[48:63]
	v_mfma_f32_32x32x16_bf16 v[32:47], v[160:163], v[172:175], v[32:47]
	v_mfma_f32_32x32x16_bf16 v[16:31], v[168:171], v[164:167], v[16:31]
	v_mfma_f32_32x32x16_bf16 v[0:15], v[168:171], v[172:175], v[0:15]
	s_cbranch_scc1 .LBB0_888
	v_add_co_u32_e32 v84, vcc, 0x10000, v136
	global_load_dwordx4 v[68:71], v[136:137], off offset:384
	global_load_dwordx4 v[76:79], v[134:135], off offset:384
	v_addc_co_u32_e32 v85, vcc, 0, v137, vcc
	v_add_co_u32_e32 v92, vcc, 0x10000, v134
	global_load_dwordx4 v[84:87], v[84:85], off offset:384
	s_nop 0
	v_addc_co_u32_e32 v93, vcc, 0, v135, vcc
	v_add_co_u32_e32 v100, vcc, 0x20000, v136
	global_load_dwordx4 v[92:95], v[92:93], off offset:384
	s_nop 0
	v_addc_co_u32_e32 v101, vcc, 0, v137, vcc
	v_add_co_u32_e32 v108, vcc, 0x20000, v134
	global_load_dwordx4 v[100:103], v[100:101], off offset:384
	s_nop 0
	v_addc_co_u32_e32 v109, vcc, 0, v135, vcc
	v_add_co_u32_e32 v116, vcc, 0x30000, v136
	global_load_dwordx4 v[108:111], v[108:109], off offset:384
	s_nop 0
	v_addc_co_u32_e32 v117, vcc, 0, v137, vcc
	v_add_co_u32_e32 v124, vcc, 0x30000, v134
	global_load_dwordx4 v[116:119], v[116:117], off offset:384
	s_nop 0
	v_addc_co_u32_e32 v125, vcc, 0, v135, vcc
	global_load_dwordx4 v[124:127], v[124:125], off offset:384
.LBB0_888:
	ds_read_b128 v[134:137], v151 offset:32768
	ds_read_b128 v[160:163], v152 offset:49152
	ds_read_b128 v[164:167], v151 offset:36864
	ds_read_b128 v[168:171], v152 offset:53248
	s_andn2_b64 vcc, exec, s[8:9]
	s_waitcnt lgkmcnt(0)
	v_mfma_f32_32x32x16_bf16 v[48:63], v[134:137], v[160:163], v[48:63]
	v_mfma_f32_32x32x16_bf16 v[32:47], v[134:137], v[168:171], v[32:47]
	v_mfma_f32_32x32x16_bf16 v[16:31], v[164:167], v[160:163], v[16:31]
	v_mfma_f32_32x32x16_bf16 v[0:15], v[164:167], v[168:171], v[0:15]
	ds_read_b128 v[134:137], v153 offset:32768
	ds_read_b128 v[160:163], v154 offset:49152
	ds_read_b128 v[164:167], v153 offset:36864
	ds_read_b128 v[168:171], v154 offset:53248
	s_waitcnt lgkmcnt(0)
	v_mfma_f32_32x32x16_bf16 v[48:63], v[134:137], v[160:163], v[48:63]
	v_mfma_f32_32x32x16_bf16 v[32:47], v[134:137], v[168:171], v[32:47]
	v_mfma_f32_32x32x16_bf16 v[16:31], v[164:167], v[160:163], v[16:31]
	v_mfma_f32_32x32x16_bf16 v[0:15], v[164:167], v[168:171], v[0:15]
	ds_read_b128 v[134:137], v155 offset:32768
	ds_read_b128 v[160:163], v156 offset:49152
	ds_read_b128 v[152:155], v155 offset:36864
	ds_read_b128 v[164:167], v156 offset:53248
	s_waitcnt lgkmcnt(0)
	v_mfma_f32_32x32x16_bf16 v[48:63], v[134:137], v[160:163], v[48:63]
	v_mfma_f32_32x32x16_bf16 v[32:47], v[134:137], v[164:167], v[32:47]
	v_mfma_f32_32x32x16_bf16 v[16:31], v[152:155], v[160:163], v[16:31]
	v_mfma_f32_32x32x16_bf16 v[0:15], v[152:155], v[164:167], v[0:15]
	ds_read_b128 v[134:137], v157 offset:32768
	ds_read_b128 v[152:155], v158 offset:49152
	ds_read_b128 v[160:163], v157 offset:36864
	ds_read_b128 v[156:159], v158 offset:53248
	s_waitcnt lgkmcnt(0)
	v_mfma_f32_32x32x16_bf16 v[48:63], v[134:137], v[152:155], v[48:63]
	v_mfma_f32_32x32x16_bf16 v[32:47], v[134:137], v[156:159], v[32:47]
	v_mfma_f32_32x32x16_bf16 v[16:31], v[160:163], v[152:155], v[16:31]
	v_mfma_f32_32x32x16_bf16 v[0:15], v[160:163], v[156:159], v[0:15]
	s_cbranch_vccnz .LBB0_883
	s_waitcnt vmcnt(8)
	ds_write_b128 v141, v[64:67]
	ds_write_b128 v141, v[72:75] offset:16384
	ds_write_b128 v141, v[80:83] offset:4096
	ds_write_b128 v141, v[88:91] offset:20480
	ds_write_b128 v141, v[96:99] offset:8192
	ds_write_b128 v141, v[104:107] offset:24576
	ds_write_b128 v141, v[112:115] offset:12288
	ds_write_b128 v141, v[120:123] offset:28672
	s_branch .LBB0_883
.LBB0_890:
	s_add_i32 s36, s36, s94
	s_cmpk_gt_u32 s36, 0xff
	s_cselect_b64 s[6:7], -1, 0
	s_lshr_b32 s8, s36, 3
	s_and_b32 s8, s8, 24
	s_and_b32 s9, s36, 7
	s_or_b32 s8, s9, s8
	s_or_b32 s8, s8, s96
	s_bfe_u32 s9, s36, 0x30003
	s_and_b64 vcc, exec, s[6:7]
	s_cbranch_vccnz .LBB0_881
	s_waitcnt vmcnt(0)
	v_mov_b32_e32 v66, v196
	s_lshl_b32 s10, s8, 7
	s_lshl_b32 s11, s9, 7
	v_ashrrev_i32_e32 v67, 3, v66
	v_add_u32_e32 v64, s10, v67
	v_ashrrev_i32_e32 v65, 31, v64
	v_lshlrev_b64 v[64:65], 11, v[64:65]
	v_lshlrev_b32_e32 v66, 4, v66
	v_lshl_add_u64 v[64:65], s[2:3], 0, v[64:65]
	v_and_b32_e32 v128, 0x70, v66
	v_lshl_add_u64 v[68:69], v[64:65], 0, v[128:129]
	v_add_u32_e32 v64, s11, v67
	v_ashrrev_i32_e32 v65, 31, v64
	v_lshlrev_b64 v[64:65], 11, v[64:65]
	v_lshl_add_u64 v[64:65], s[0:1], 0, v[64:65]
	v_add_co_u32_e32 v84, vcc, s14, v68
	v_lshl_add_u64 v[76:77], v[64:65], 0, v[128:129]
	s_nop 0
	v_addc_co_u32_e32 v85, vcc, 0, v69, vcc
	v_add_co_u32_e32 v92, vcc, s14, v76
	s_nop 1
	v_addc_co_u32_e32 v93, vcc, 0, v77, vcc
	v_add_co_u32_e32 v100, vcc, s15, v68
	s_nop 1
	v_addc_co_u32_e32 v101, vcc, 0, v69, vcc
	v_add_co_u32_e32 v108, vcc, s15, v76
	s_nop 1
	v_addc_co_u32_e32 v109, vcc, 0, v77, vcc
	v_add_co_u32_e32 v116, vcc, 0x30000, v68
	s_nop 1
	v_addc_co_u32_e32 v117, vcc, 0, v69, vcc
	v_add_co_u32_e32 v124, vcc, 0x30000, v76
	s_nop 1
	v_addc_co_u32_e32 v125, vcc, 0, v77, vcc
	global_load_dwordx4 v[64:67], v[68:69], off
	s_nop 0
	global_load_dwordx4 v[68:71], v[68:69], off offset:128
	s_nop 0
	global_load_dwordx4 v[72:75], v[76:77], off
	s_nop 0
	global_load_dwordx4 v[76:79], v[76:77], off offset:128
	s_nop 0
	global_load_dwordx4 v[80:83], v[84:85], off
	s_nop 0
	global_load_dwordx4 v[84:87], v[84:85], off offset:128
	s_nop 0
	global_load_dwordx4 v[88:91], v[92:93], off
	s_nop 0
	global_load_dwordx4 v[92:95], v[92:93], off offset:128
	s_nop 0
	global_load_dwordx4 v[96:99], v[100:101], off
	s_nop 0
	global_load_dwordx4 v[100:103], v[100:101], off offset:128
	s_nop 0
	global_load_dwordx4 v[104:107], v[108:109], off
	s_nop 0
	global_load_dwordx4 v[108:111], v[108:109], off offset:128
	s_nop 0
	global_load_dwordx4 v[112:115], v[116:117], off
	s_nop 0
	global_load_dwordx4 v[116:119], v[116:117], off offset:128
	s_nop 0
	global_load_dwordx4 v[120:123], v[124:125], off
	s_nop 0
	global_load_dwordx4 v[124:127], v[124:125], off offset:128
	s_branch .LBB0_881

.LBB0_1001:
	s_or_b64 exec, exec, s[0:1]
	s_mov_b64 s[16:17], s[56:57]
	v_mov_b32_e32 v0, v196
	s_cmpk_gt_u32 s12, 0x1fff
	s_waitcnt lgkmcnt(0)
	s_barrier
	s_cbranch_scc1 .LBB0_1030
	s_add_u32 s36, s16, 0x4000000
	s_addc_u32 s37, s17, 0
	s_add_u32 s38, s16, 0xb00000
	s_addc_u32 s39, s17, 0
	s_add_u32 s40, s16, 0x10000000
	s_addc_u32 s41, s17, 0
	s_add_u32 s42, s16, 0x18000000
	s_addc_u32 s43, s17, 0
	s_add_u32 s44, s16, 0x1540000
	s_addc_u32 s45, s17, 0
	s_lshr_b32 s0, s12, 11
	s_lshl_b32 s1, s0, 3
	s_bfe_u32 s2, s12, 0x30003
	s_or_b32 s1, s1, s2
	s_or_b32 s70, s1, s96
	s_lshr_b32 s1, s12, 6
	s_lshl_b32 s0, s0, 5
	s_and_b32 s1, s1, 0x78
	v_mov_b32_e32 v4, v196
	s_sub_i32 s0, s1, s0
	s_bfe_u32 s1, s12, 0x30006
	s_lshl_b32 s10, s70, 7
	s_or_b32 s48, s0, s1
	v_ashrrev_i32_e32 v5, 3, v4
	v_add_u32_e32 v2, s10, v5
	s_lshl_b32 s11, s48, 7
	v_ashrrev_i32_e32 v3, 31, v2
	v_lshlrev_b32_e32 v4, 4, v4
	v_lshlrev_b64 v[2:3], 11, v[2:3]
	v_and_b32_e32 v130, 0x70, v4
	v_add_u32_e32 v4, s11, v5
	v_lshl_add_u64 v[2:3], s[36:37], 0, v[2:3]
	v_mov_b32_e32 v131, 0
	v_ashrrev_i32_e32 v5, 31, v4
	v_lshl_add_u64 v[2:3], v[2:3], 0, v[130:131]
	v_lshlrev_b64 v[4:5], 11, v[4:5]
	s_mov_b32 s15, 0x10000
	v_lshl_add_u64 v[4:5], s[38:39], 0, v[4:5]
	v_add_co_u32_e32 v6, vcc, s15, v2
	v_lshl_add_u64 v[4:5], v[4:5], 0, v[130:131]
	s_nop 0
	v_addc_co_u32_e32 v7, vcc, 0, v3, vcc
	v_add_co_u32_e32 v8, vcc, s15, v4
	s_mov_b32 s33, 0x20000
	s_nop 0
	v_addc_co_u32_e32 v9, vcc, 0, v5, vcc
	v_add_co_u32_e32 v10, vcc, s33, v2
	s_mov_b32 s0, 0x30000
	s_nop 0
	v_addc_co_u32_e32 v11, vcc, 0, v3, vcc
	v_add_co_u32_e32 v12, vcc, s33, v4
	v_and_b32_e32 v129, 63, v0
	s_nop 0
	v_addc_co_u32_e32 v13, vcc, 0, v5, vcc
	v_add_co_u32_e32 v14, vcc, s0, v2
	v_ashrrev_i32_e32 v1, 6, v0
	s_nop 0
	v_addc_co_u32_e32 v15, vcc, 0, v3, vcc
	v_add_co_u32_e32 v16, vcc, s0, v4
	s_movk_i32 s0, 0x2400
	s_nop 0
	v_addc_co_u32_e32 v17, vcc, 0, v5, vcc
	global_load_dwordx4 v[64:67], v[2:3], off
	global_load_dwordx4 v[68:71], v[2:3], off offset:128
	global_load_dwordx4 v[72:75], v[4:5], off
	global_load_dwordx4 v[76:79], v[4:5], off offset:128
	global_load_dwordx4 v[80:83], v[6:7], off
	global_load_dwordx4 v[84:87], v[6:7], off offset:128
	global_load_dwordx4 v[88:91], v[8:9], off
	global_load_dwordx4 v[92:95], v[8:9], off offset:128
	global_load_dwordx4 v[96:99], v[10:11], off
	global_load_dwordx4 v[100:103], v[10:11], off offset:128
	global_load_dwordx4 v[104:107], v[12:13], off
	global_load_dwordx4 v[108:111], v[12:13], off offset:128
	global_load_dwordx4 v[112:115], v[14:15], off
	global_load_dwordx4 v[116:119], v[14:15], off offset:128
	global_load_dwordx4 v[120:123], v[16:17], off
	global_load_dwordx4 v[124:127], v[16:17], off offset:128
	v_bfe_u32 v3, v0, 3, 3
	v_and_b32_e32 v4, 4, v3
	v_mul_u32_u24_e32 v199, 0x90, v4
	v_or_b32_e32 v4, 3, v3
	s_waitcnt vmcnt(0)
	v_mul_u32_u24_e32 v200, 0x90, v4
	v_or_b32_e32 v4, 11, v3
	v_mul_u32_u24_e32 v201, 0x90, v4
	v_or_b32_e32 v4, 19, v3
	v_and_b32_e32 v133, 1, v1
	v_mul_lo_u32 v1, v1, s0
	v_lshlrev_b32_e32 v5, 1, v129
	v_mul_u32_u24_e32 v202, 0x90, v4
	v_or_b32_e32 v4, 27, v3
	v_add_u32_e32 v1, 16, v1
	v_mul_u32_u24_e32 v203, 0x90, v4
	v_or_b32_e32 v4, 64, v5
	v_add_u32_e32 v204, v1, v4
	v_or_b32_e32 v4, 35, v3
	v_mul_u32_u24_e32 v205, 0x90, v4
	v_or_b32_e32 v4, 43, v3
	v_mul_u32_u24_e32 v206, 0x90, v4
	v_or_b32_e32 v4, 51, v3
	v_mul_u32_u24_e32 v207, 0x90, v4
	v_or_b32_e32 v4, 59, v3
	v_lshrrev_b32_e32 v20, 2, v0
	v_and_b32_e32 v128, 31, v0
	v_ashrrev_i32_e32 v2, 1, v0
	v_and_b32_e32 v6, 62, v5
	s_movk_i32 s0, 0x90
	v_mul_u32_u24_e32 v208, 0x90, v4
	v_and_b32_e32 v4, 7, v0
	v_or_b32_e32 v5, 8, v3
	v_or_b32_e32 v7, 16, v3
	v_or_b32_e32 v9, 24, v3
	v_or_b32_e32 v11, 32, v3
	v_or_b32_e32 v13, 40, v3
	v_or_b32_e32 v15, 48, v3
	v_or_b32_e32 v17, 56, v3
	v_and_b32_e32 v21, 8, v20
	v_or_b32_e32 v20, 32, v129
	v_and_b32_e32 v0, 39, v0
	v_and_b32_e32 v145, 0xffffffc0, v2
	v_lshlrev_b32_e32 v2, 6, v133
	v_add_u32_e32 v198, v1, v6
	v_lshl_add_u32 v209, v4, 4, v1
	v_lshlrev_b32_e32 v132, 3, v4
	v_lshlrev_b32_e32 v4, 10, v3
	v_lshlrev_b32_e32 v6, 10, v5
	v_lshlrev_b32_e32 v8, 10, v7
	v_lshlrev_b32_e32 v10, 10, v9
	v_lshlrev_b32_e32 v12, 10, v11
	v_lshlrev_b32_e32 v14, 10, v13
	v_lshlrev_b32_e32 v16, 10, v15
	v_lshlrev_b32_e32 v18, 10, v17
	v_mad_u32_u24 v19, v128, s0, v1
	v_mad_u32_u24 v23, v20, s0, v1
	v_lshlrev_b32_e32 v20, 13, v3
	v_lshlrev_b32_e32 v22, 13, v5
	v_lshlrev_b32_e32 v24, 13, v7
	v_lshlrev_b32_e32 v26, 13, v9
	v_lshlrev_b32_e32 v28, 13, v11
	v_lshlrev_b32_e32 v30, 13, v13
	v_lshlrev_b32_e32 v32, 13, v15
	v_lshlrev_b32_e32 v34, 13, v17
	v_lshl_add_u32 v212, v0, 3, v1
	s_add_u32 s50, s16, 0x2800000
	v_lshlrev_b32_e32 v0, 6, v3
	v_lshlrev_b32_e32 v36, 6, v5
	v_lshlrev_b32_e32 v38, 6, v7
	v_lshlrev_b32_e32 v40, 6, v9
	v_lshlrev_b32_e32 v42, 6, v11
	v_lshlrev_b32_e32 v44, 6, v13
	v_lshlrev_b32_e32 v46, 6, v15
	v_lshlrev_b32_e32 v48, 6, v17
	s_movk_i32 s14, 0x70
	s_mov_b32 s49, 0
	v_mul_u32_u24_e32 v210, 0x90, v3
	v_lshl_add_u32 v211, v129, 3, v1
	v_cmp_gt_u32_e64 s[2:3], 8, v128
	v_cmp_gt_u32_e64 s[4:5], 16, v128
	s_addc_u32 s51, s17, 0
	v_cmp_gt_u32_e64 s[6:7], 32, v129
	s_mov_b32 s35, 0x1ffffc0
	s_mov_b64 s[52:53], 0x100
	v_lshlrev_b32_e32 v134, 1, v2
	v_lshlrev_b32_e32 v136, 1, v4
	v_lshlrev_b32_e32 v138, 1, v6
	v_lshlrev_b32_e32 v140, 1, v8
	v_lshlrev_b32_e32 v142, 1, v10
	v_lshlrev_b32_e32 v148, 1, v12
	v_lshlrev_b32_e32 v150, 1, v14
	v_lshlrev_b32_e32 v152, 1, v16
	v_lshlrev_b32_e32 v154, 1, v18
	v_add_u32_e32 v213, v19, v21
	v_add_u32_e32 v214, v23, v21
	v_lshlrev_b32_e32 v156, 1, v20
	v_lshlrev_b32_e32 v158, 1, v22
	v_lshlrev_b32_e32 v160, 1, v24
	v_lshlrev_b32_e32 v162, 1, v26
	v_lshlrev_b32_e32 v164, 1, v28
	v_lshlrev_b32_e32 v166, 1, v30
	v_lshlrev_b32_e32 v168, 1, v32
	v_lshlrev_b32_e32 v170, 1, v34
	s_mov_b32 s62, 0x3c800000
	s_mov_b32 s64, 0x358637bd
	s_mov_b32 s46, 0x800000
	s_brev_b32 s47, 48
	v_lshlrev_b32_e32 v172, 1, v0
	v_lshlrev_b32_e32 v174, 1, v36
	v_lshlrev_b32_e32 v176, 1, v38
	v_lshlrev_b32_e32 v178, 1, v40
	v_lshlrev_b32_e32 v180, 1, v42
	v_lshlrev_b32_e32 v182, 1, v44
	v_lshlrev_b32_e32 v184, 1, v46
	v_lshlrev_b32_e32 v186, 1, v48
	v_mov_b32_e32 v215, 0x3e38aa3b
	v_mbcnt_hi_u32_b32 v216, -1, v253
	s_mov_b32 s63, s95
	s_mov_b32 s72, 0
	s_mov_b32 s65, 0
	s_branch .LBB0_1006

.LBB0_1004:
	s_and_b64 s[0:1], s[70:71], exec
	s_cselect_b32 s0, s47, 0x14000000
	v_lshl_or_b32 v0, v177, 4, v175
	s_add_u32 s0, s16, s0
	v_ashrrev_i32_e32 v1, 31, v0
	s_addc_u32 s1, s17, 0
	v_lshlrev_b64 v[0:1], 20, v[0:1]
	v_lshl_add_u64 v[0:1], s[0:1], 0, v[0:1]
	v_lshlrev_b32_e32 v130, 7, v173
	v_lshl_add_u64 v[146:147], v[0:1], 0, v[130:131]
	v_cvt_pk_bf16_f32 v0, v48, s0
	v_add_u32_e32 v1, v198, v199
	ds_write_b16 v1, v0
	v_cvt_pk_bf16_f32 v0, v49, s0
	ds_write_b16 v1, v0 offset:144
	v_cvt_pk_bf16_f32 v0, v50, s0
	ds_write_b16 v1, v0 offset:288
	v_cvt_pk_bf16_f32 v0, v51, s0
	v_add_u32_e32 v48, v198, v200
	ds_write_b16 v48, v0
	v_cvt_pk_bf16_f32 v0, v52, s0
	ds_write_b16 v1, v0 offset:1152
	v_cvt_pk_bf16_f32 v0, v53, s0
	ds_write_b16 v1, v0 offset:1296
	v_cvt_pk_bf16_f32 v0, v54, s0
	ds_write_b16 v1, v0 offset:1440
	v_cvt_pk_bf16_f32 v0, v55, s0
	v_add_u32_e32 v48, v198, v201
	ds_write_b16 v48, v0
	v_cvt_pk_bf16_f32 v0, v56, s0
	ds_write_b16 v1, v0 offset:2304
	v_cvt_pk_bf16_f32 v0, v57, s0
	ds_write_b16 v1, v0 offset:2448
	v_cvt_pk_bf16_f32 v0, v58, s0
	ds_write_b16 v1, v0 offset:2592
	v_cvt_pk_bf16_f32 v0, v59, s0
	v_add_u32_e32 v48, v198, v202
	ds_write_b16 v48, v0
	v_cvt_pk_bf16_f32 v0, v60, s0
	ds_write_b16 v1, v0 offset:3456
	v_cvt_pk_bf16_f32 v0, v61, s0
	ds_write_b16 v1, v0 offset:3600
	v_cvt_pk_bf16_f32 v0, v62, s0
	ds_write_b16 v1, v0 offset:3744
	v_cvt_pk_bf16_f32 v0, v141, s0
	v_add_u32_e32 v48, v198, v203
	ds_write_b16 v48, v0
	v_cvt_pk_bf16_f32 v0, v32, s0
	v_add_u32_e32 v32, v204, v199
	ds_write_b16 v32, v0
	v_cvt_pk_bf16_f32 v0, v33, s0
	ds_write_b16 v32, v0 offset:144
	v_cvt_pk_bf16_f32 v0, v34, s0
	ds_write_b16 v32, v0 offset:288
	v_cvt_pk_bf16_f32 v0, v35, s0
	v_add_u32_e32 v33, v204, v200
	ds_write_b16 v33, v0
	v_cvt_pk_bf16_f32 v0, v36, s0
	ds_write_b16 v32, v0 offset:1152
	v_cvt_pk_bf16_f32 v0, v37, s0
	ds_write_b16 v32, v0 offset:1296
	v_cvt_pk_bf16_f32 v0, v38, s0
	ds_write_b16 v32, v0 offset:1440
	v_cvt_pk_bf16_f32 v0, v39, s0
	v_add_u32_e32 v33, v204, v201
	ds_write_b16 v33, v0
	v_cvt_pk_bf16_f32 v0, v40, s0
	ds_write_b16 v32, v0 offset:2304
	v_cvt_pk_bf16_f32 v0, v41, s0
	ds_write_b16 v32, v0 offset:2448
	v_cvt_pk_bf16_f32 v0, v42, s0
	ds_write_b16 v32, v0 offset:2592
	v_cvt_pk_bf16_f32 v0, v43, s0
	v_add_u32_e32 v33, v204, v202
	ds_write_b16 v33, v0
	v_cvt_pk_bf16_f32 v0, v44, s0
	ds_write_b16 v32, v0 offset:3456
	v_cvt_pk_bf16_f32 v0, v45, s0
	ds_write_b16 v32, v0 offset:3600
	v_cvt_pk_bf16_f32 v0, v46, s0
	ds_write_b16 v32, v0 offset:3744
	v_cvt_pk_bf16_f32 v0, v47, s0
	v_add_u32_e32 v33, v204, v203
	ds_write_b16 v33, v0
	v_cvt_pk_bf16_f32 v0, v63, s0
	ds_write_b16 v1, v0 offset:4608
	v_cvt_pk_bf16_f32 v0, v143, s0
	ds_write_b16 v1, v0 offset:4752
	v_cvt_pk_bf16_f32 v0, v18, s0
	ds_write_b16 v1, v0 offset:4896
	v_cvt_pk_bf16_f32 v0, v19, s0
	v_add_u32_e32 v18, v198, v205
	ds_write_b16 v18, v0
	v_cvt_pk_bf16_f32 v0, v20, s0
	ds_write_b16 v1, v0 offset:5760
	v_cvt_pk_bf16_f32 v0, v21, s0
	ds_write_b16 v1, v0 offset:5904
	v_cvt_pk_bf16_f32 v0, v22, s0
	ds_write_b16 v1, v0 offset:6048
	v_cvt_pk_bf16_f32 v0, v23, s0
	v_add_u32_e32 v18, v198, v206
	ds_write_b16 v18, v0
	v_cvt_pk_bf16_f32 v0, v24, s0
	ds_write_b16 v1, v0 offset:6912
	v_cvt_pk_bf16_f32 v0, v25, s0
	ds_write_b16 v1, v0 offset:7056
	v_cvt_pk_bf16_f32 v0, v26, s0
	ds_write_b16 v1, v0 offset:7200
	v_cvt_pk_bf16_f32 v0, v27, s0
	v_add_u32_e32 v18, v198, v207
	ds_write_b16 v18, v0
	v_cvt_pk_bf16_f32 v0, v28, s0
	ds_write_b16 v1, v0 offset:8064
	v_cvt_pk_bf16_f32 v0, v29, s0
	ds_write_b16 v1, v0 offset:8208
	v_cvt_pk_bf16_f32 v0, v30, s0
	ds_write_b16 v1, v0 offset:8352
	v_cvt_pk_bf16_f32 v0, v31, s0
	v_add_u32_e32 v1, v198, v208
	ds_write_b16 v1, v0
	v_cvt_pk_bf16_f32 v0, v16, s0
	ds_write_b16 v32, v0 offset:4608
	v_cvt_pk_bf16_f32 v0, v17, s0
	ds_write_b16 v32, v0 offset:4752
	v_cvt_pk_bf16_f32 v0, v2, s0
	ds_write_b16 v32, v0 offset:4896
	v_cvt_pk_bf16_f32 v0, v3, s0
	v_add_u32_e32 v1, v204, v205
	ds_write_b16 v1, v0
	v_cvt_pk_bf16_f32 v0, v4, s0
	ds_write_b16 v32, v0 offset:5760
	v_cvt_pk_bf16_f32 v0, v5, s0
	ds_write_b16 v32, v0 offset:5904
	v_cvt_pk_bf16_f32 v0, v6, s0
	ds_write_b16 v32, v0 offset:6048
	v_cvt_pk_bf16_f32 v0, v7, s0
	v_add_u32_e32 v1, v204, v206
	ds_write_b16 v1, v0
	v_cvt_pk_bf16_f32 v0, v8, s0
	ds_write_b16 v32, v0 offset:6912
	v_cvt_pk_bf16_f32 v0, v9, s0
	ds_write_b16 v32, v0 offset:7056
	v_cvt_pk_bf16_f32 v0, v10, s0
	ds_write_b16 v32, v0 offset:7200
	v_cvt_pk_bf16_f32 v0, v11, s0
	v_add_u32_e32 v1, v204, v207
	ds_write_b16 v1, v0
	v_cvt_pk_bf16_f32 v0, v12, s0
	ds_write_b16 v32, v0 offset:8064
	v_cvt_pk_bf16_f32 v0, v13, s0
	ds_write_b16 v32, v0 offset:8208
	v_cvt_pk_bf16_f32 v0, v14, s0
	ds_write_b16 v32, v0 offset:8352
	v_cvt_pk_bf16_f32 v0, v15, s0
	v_add_u32_e32 v1, v204, v208
	v_add_u32_e32 v8, v209, v210
	ds_write_b16 v1, v0
	ds_read_b128 v[0:3], v8
	v_lshlrev_b32_e32 v130, 1, v132
	v_lshl_add_u64 v[4:5], v[146:147], 0, v[130:131]
	v_mov_b32_e32 v173, v131
	v_lshl_add_u64 v[6:7], v[4:5], 0, v[172:173]
	s_waitcnt lgkmcnt(0)
	global_store_dwordx4 v[6:7], v[0:3], off
	ds_read_b128 v[0:3], v8 offset:1152
	v_mov_b32_e32 v175, v131
	v_lshl_add_u64 v[6:7], v[4:5], 0, v[174:175]
	v_mov_b32_e32 v177, v131
	v_mov_b32_e32 v179, v131
	s_waitcnt lgkmcnt(0)
	global_store_dwordx4 v[6:7], v[0:3], off
	ds_read_b128 v[0:3], v8 offset:2304
	v_lshl_add_u64 v[6:7], v[4:5], 0, v[176:177]
	v_mov_b32_e32 v181, v131
	v_mov_b32_e32 v183, v131
	v_mov_b32_e32 v185, v131
	s_waitcnt lgkmcnt(0)
	global_store_dwordx4 v[6:7], v[0:3], off
	ds_read_b128 v[0:3], v8 offset:3456
	v_lshl_add_u64 v[6:7], v[4:5], 0, v[178:179]
	v_mov_b32_e32 v187, v131
	s_waitcnt lgkmcnt(0)
	global_store_dwordx4 v[6:7], v[0:3], off
	ds_read_b128 v[0:3], v8 offset:4608
	v_lshl_add_u64 v[6:7], v[4:5], 0, v[180:181]
	s_waitcnt lgkmcnt(0)
	global_store_dwordx4 v[6:7], v[0:3], off
	ds_read_b128 v[0:3], v8 offset:5760
	v_lshl_add_u64 v[6:7], v[4:5], 0, v[182:183]
	s_waitcnt lgkmcnt(0)
	global_store_dwordx4 v[6:7], v[0:3], off
	ds_read_b128 v[0:3], v8 offset:6912
	v_lshl_add_u64 v[6:7], v[4:5], 0, v[184:185]
	v_lshl_add_u64 v[4:5], v[4:5], 0, v[186:187]
	s_waitcnt lgkmcnt(0)
	global_store_dwordx4 v[6:7], v[0:3], off
	ds_read_b128 v[0:3], v8 offset:8064
	s_waitcnt lgkmcnt(0)
	global_store_dwordx4 v[4:5], v[0:3], off

.LBB0_1008:
	s_cmp_lt_u32 s68, 14
	s_cselect_b64 s[8:9], -1, 0
	s_cmp_gt_u32 s68, 13
	s_cselect_b64 s[0:1], -1, 0
	s_and_b64 vcc, exec, s[0:1]
	v_lshl_add_u64 v[194:195], v[190:191], 0, v[130:131]
	v_lshl_add_u64 v[192:193], v[188:189], 0, v[130:131]
	s_cbranch_vccnz .LBB0_1010
	s_waitcnt vmcnt(8)
	v_add_co_u32_e32 v80, vcc, 0x10000, v194
	global_load_dwordx4 v[64:67], v[194:195], off offset:256
	global_load_dwordx4 v[72:75], v[192:193], off offset:256
	v_addc_co_u32_e32 v81, vcc, 0, v195, vcc
	v_add_co_u32_e32 v88, vcc, 0x10000, v192
	global_load_dwordx4 v[80:83], v[80:81], off offset:256
	s_nop 0
	v_addc_co_u32_e32 v89, vcc, 0, v193, vcc
	v_add_co_u32_e32 v96, vcc, 0x20000, v194
	global_load_dwordx4 v[88:91], v[88:89], off offset:256
	s_nop 0
	v_addc_co_u32_e32 v97, vcc, 0, v195, vcc
	v_add_co_u32_e32 v104, vcc, 0x20000, v192
	global_load_dwordx4 v[96:99], v[96:97], off offset:256
	s_nop 0
	v_addc_co_u32_e32 v105, vcc, 0, v193, vcc
	v_add_co_u32_e32 v112, vcc, 0x30000, v194
	global_load_dwordx4 v[104:107], v[104:105], off offset:256
	s_nop 0
	v_addc_co_u32_e32 v113, vcc, 0, v195, vcc
	v_add_co_u32_e32 v120, vcc, 0x30000, v192
	global_load_dwordx4 v[112:115], v[112:113], off offset:256
	s_nop 0
	v_addc_co_u32_e32 v121, vcc, 0, v193, vcc
	global_load_dwordx4 v[120:123], v[120:121], off offset:256
.LBB0_1010:
	v_add_u32_e32 v153, v137, v139
	ds_read_b128 v[218:221], v153
	v_add_u32_e32 v155, v137, v141
	ds_read_b128 v[222:225], v155 offset:16384
	ds_read_b128 v[226:229], v153 offset:4096
	ds_read_b128 v[230:233], v155 offset:20480
	v_add_u32_e32 v157, v143, v139
	s_waitcnt lgkmcnt(0)
	v_mfma_f32_32x32x16_bf16 v[0:15], v[226:229], v[222:225], v[0:15]
	v_add_u32_e32 v159, v143, v141
	v_add_u32_e32 v161, v149, v139
	v_add_u32_e32 v163, v149, v141
	v_add_u32_e32 v165, v151, v139
	v_add_u32_e32 v167, v151, v141
	s_cmp_gt_u32 s68, 12
	v_mfma_f32_32x32x16_bf16 v[32:47], v[218:221], v[222:225], v[32:47]
	v_mfma_f32_32x32x16_bf16 v[48:63], v[218:221], v[230:233], v[48:63]
	ds_read_b128 v[218:221], v157
	v_mfma_f32_32x32x16_bf16 v[16:31], v[226:229], v[230:233], v[16:31]
	ds_read_b128 v[222:225], v159 offset:16384
	ds_read_b128 v[226:229], v157 offset:4096
	ds_read_b128 v[230:233], v159 offset:20480
	s_waitcnt lgkmcnt(0)
	v_mfma_f32_32x32x16_bf16 v[32:47], v[218:221], v[222:225], v[32:47]
	v_mfma_f32_32x32x16_bf16 v[48:63], v[218:221], v[230:233], v[48:63]
	ds_read_b128 v[218:221], v161
	v_mfma_f32_32x32x16_bf16 v[0:15], v[226:229], v[222:225], v[0:15]
	v_mfma_f32_32x32x16_bf16 v[16:31], v[226:229], v[230:233], v[16:31]
	ds_read_b128 v[222:225], v163 offset:16384
	ds_read_b128 v[226:229], v161 offset:4096
	ds_read_b128 v[230:233], v163 offset:20480
	s_waitcnt lgkmcnt(0)
	v_mfma_f32_32x32x16_bf16 v[32:47], v[218:221], v[222:225], v[32:47]
	v_mfma_f32_32x32x16_bf16 v[48:63], v[218:221], v[230:233], v[48:63]
	ds_read_b128 v[218:221], v165
	v_mfma_f32_32x32x16_bf16 v[0:15], v[226:229], v[222:225], v[0:15]
	v_mfma_f32_32x32x16_bf16 v[16:31], v[226:229], v[230:233], v[16:31]
	ds_read_b128 v[222:225], v167 offset:16384
	ds_read_b128 v[226:229], v165 offset:4096
	ds_read_b128 v[230:233], v167 offset:20480
	s_mov_b64 vcc, s[0:1]
	s_cbranch_vccnz .Lkvq_cw0
	s_waitcnt vmcnt(8)
	s_branch .Lkvq_cw1

.Lkvq_cw1:
	ds_write_b128 v135, v[68:71] offset:32768
	ds_write_b128 v135, v[76:79] offset:49152
	ds_write_b128 v135, v[84:87] offset:36864
	ds_write_b128 v135, v[92:95] offset:53248
	ds_write_b128 v135, v[100:103] offset:40960
	ds_write_b128 v135, v[108:111] offset:57344
	ds_write_b128 v135, v[116:119] offset:45056
	ds_write_b128 v135, v[124:127] offset:61440
	s_waitcnt lgkmcnt(0)
	s_barrier
	v_mfma_f32_32x32x16_bf16 v[32:47], v[218:221], v[222:225], v[32:47]
	v_mfma_f32_32x32x16_bf16 v[48:63], v[218:221], v[230:233], v[48:63]
	v_mfma_f32_32x32x16_bf16 v[0:15], v[226:229], v[222:225], v[0:15]
	v_mfma_f32_32x32x16_bf16 v[16:31], v[226:229], v[230:233], v[16:31]
	s_cbranch_scc1 .LBB0_1012
	v_add_co_u32_e32 v84, vcc, 0x10000, v194
	global_load_dwordx4 v[68:71], v[194:195], off offset:384
	global_load_dwordx4 v[76:79], v[192:193], off offset:384
	v_addc_co_u32_e32 v85, vcc, 0, v195, vcc
	v_add_co_u32_e32 v92, vcc, 0x10000, v192
	global_load_dwordx4 v[84:87], v[84:85], off offset:384
	s_nop 0
	v_addc_co_u32_e32 v93, vcc, 0, v193, vcc
	v_add_co_u32_e32 v100, vcc, 0x20000, v194
	global_load_dwordx4 v[92:95], v[92:93], off offset:384
	s_nop 0
	v_addc_co_u32_e32 v101, vcc, 0, v195, vcc
	v_add_co_u32_e32 v108, vcc, 0x20000, v192
	global_load_dwordx4 v[100:103], v[100:101], off offset:384
	s_nop 0
	v_addc_co_u32_e32 v109, vcc, 0, v193, vcc
	v_add_co_u32_e32 v116, vcc, 0x30000, v194
	global_load_dwordx4 v[108:111], v[108:109], off offset:384
	s_nop 0
	v_addc_co_u32_e32 v117, vcc, 0, v195, vcc
	v_add_co_u32_e32 v124, vcc, 0x30000, v192
	global_load_dwordx4 v[116:119], v[116:117], off offset:384
	s_nop 0
	v_addc_co_u32_e32 v125, vcc, 0, v193, vcc
	global_load_dwordx4 v[124:127], v[124:125], off offset:384
.LBB0_1012:
	ds_read_b128 v[192:195], v153 offset:32768
	ds_read_b128 v[218:221], v155 offset:49152
	ds_read_b128 v[222:225], v153 offset:36864
	ds_read_b128 v[226:229], v155 offset:53248
	s_andn2_b64 vcc, exec, s[8:9]
	s_waitcnt lgkmcnt(0)
	v_mfma_f32_32x32x16_bf16 v[32:47], v[192:195], v[218:221], v[32:47]
	v_mfma_f32_32x32x16_bf16 v[48:63], v[192:195], v[226:229], v[48:63]
	v_mfma_f32_32x32x16_bf16 v[0:15], v[222:225], v[218:221], v[0:15]
	v_mfma_f32_32x32x16_bf16 v[16:31], v[222:225], v[226:229], v[16:31]
	ds_read_b128 v[192:195], v157 offset:32768
	ds_read_b128 v[218:221], v159 offset:49152
	ds_read_b128 v[222:225], v157 offset:36864
	ds_read_b128 v[226:229], v159 offset:53248
	s_waitcnt lgkmcnt(0)
	v_mfma_f32_32x32x16_bf16 v[32:47], v[192:195], v[218:221], v[32:47]
	v_mfma_f32_32x32x16_bf16 v[48:63], v[192:195], v[226:229], v[48:63]
	v_mfma_f32_32x32x16_bf16 v[0:15], v[222:225], v[218:221], v[0:15]
	v_mfma_f32_32x32x16_bf16 v[16:31], v[222:225], v[226:229], v[16:31]
	ds_read_b128 v[192:195], v161 offset:32768
	ds_read_b128 v[218:221], v163 offset:49152
	ds_read_b128 v[222:225], v161 offset:36864
	ds_read_b128 v[226:229], v163 offset:53248
	s_waitcnt lgkmcnt(0)
	v_mfma_f32_32x32x16_bf16 v[32:47], v[192:195], v[218:221], v[32:47]
	v_mfma_f32_32x32x16_bf16 v[48:63], v[192:195], v[226:229], v[48:63]
	v_mfma_f32_32x32x16_bf16 v[0:15], v[222:225], v[218:221], v[0:15]
	v_mfma_f32_32x32x16_bf16 v[16:31], v[222:225], v[226:229], v[16:31]
	ds_read_b128 v[192:195], v165 offset:32768
	ds_read_b128 v[218:221], v167 offset:49152
	ds_read_b128 v[222:225], v165 offset:36864
	ds_read_b128 v[226:229], v167 offset:53248
	s_waitcnt lgkmcnt(0)
	v_mfma_f32_32x32x16_bf16 v[32:47], v[192:195], v[218:221], v[32:47]
	v_mfma_f32_32x32x16_bf16 v[48:63], v[192:195], v[226:229], v[48:63]
	v_mfma_f32_32x32x16_bf16 v[0:15], v[222:225], v[218:221], v[0:15]
	v_mfma_f32_32x32x16_bf16 v[16:31], v[222:225], v[226:229], v[16:31]
	s_cbranch_vccnz .LBB0_1007
	s_waitcnt vmcnt(8)
	ds_write_b128 v135, v[64:67]
	ds_write_b128 v135, v[72:75] offset:16384
	ds_write_b128 v135, v[80:83] offset:4096
	ds_write_b128 v135, v[88:91] offset:20480
	ds_write_b128 v135, v[96:99] offset:8192
	ds_write_b128 v135, v[104:107] offset:24576
	ds_write_b128 v135, v[112:115] offset:12288
	ds_write_b128 v135, v[120:123] offset:28672
	s_branch .LBB0_1007

.LBB0_1016:
	s_andn2_b64 vcc, exec, s[0:1]
	s_cbranch_vccnz .LBB0_1018
	s_waitcnt vmcnt(0)
	v_mov_b32_e32 v66, v196
	s_lshl_b32 s10, s65, 7
	s_lshl_b32 s11, s72, 7
	v_ashrrev_i32_e32 v67, 3, v66
	v_add_u32_e32 v64, s10, v67
	v_ashrrev_i32_e32 v65, 31, v64
	v_lshlrev_b64 v[64:65], 11, v[64:65]
	v_lshlrev_b32_e32 v66, 4, v66
	v_lshl_add_u64 v[64:65], s[36:37], 0, v[64:65]
	v_and_b32_e32 v130, 0x70, v66
	v_lshl_add_u64 v[68:69], v[64:65], 0, v[130:131]
	v_add_u32_e32 v64, s11, v67
	v_ashrrev_i32_e32 v65, 31, v64
	v_lshlrev_b64 v[64:65], 11, v[64:65]
	v_lshl_add_u64 v[64:65], s[38:39], 0, v[64:65]
	v_add_co_u32_e32 v84, vcc, s15, v68
	v_lshl_add_u64 v[76:77], v[64:65], 0, v[130:131]
	s_nop 0
	v_addc_co_u32_e32 v85, vcc, 0, v69, vcc
	v_add_co_u32_e32 v92, vcc, s15, v76
	s_nop 1
	v_addc_co_u32_e32 v93, vcc, 0, v77, vcc
	v_add_co_u32_e32 v100, vcc, s33, v68
	s_nop 1
	v_addc_co_u32_e32 v101, vcc, 0, v69, vcc
	v_add_co_u32_e32 v108, vcc, s33, v76
	s_nop 1
	v_addc_co_u32_e32 v109, vcc, 0, v77, vcc
	v_add_co_u32_e32 v116, vcc, 0x30000, v68
	s_nop 1
	v_addc_co_u32_e32 v117, vcc, 0, v69, vcc
	v_add_co_u32_e32 v124, vcc, 0x30000, v76
	s_nop 1
	v_addc_co_u32_e32 v125, vcc, 0, v77, vcc
	global_load_dwordx4 v[64:67], v[68:69], off
	s_nop 0
	global_load_dwordx4 v[68:71], v[68:69], off offset:128
	s_nop 0
	global_load_dwordx4 v[72:75], v[76:77], off
	s_nop 0
	global_load_dwordx4 v[76:79], v[76:77], off offset:128
	s_nop 0
	global_load_dwordx4 v[80:83], v[84:85], off
	s_nop 0
	global_load_dwordx4 v[84:87], v[84:85], off offset:128
	s_nop 0
	global_load_dwordx4 v[88:91], v[92:93], off
	s_nop 0
	global_load_dwordx4 v[92:95], v[92:93], off offset:128
	s_nop 0
	global_load_dwordx4 v[96:99], v[100:101], off
	s_nop 0
	global_load_dwordx4 v[100:103], v[100:101], off offset:128
	s_nop 0
	global_load_dwordx4 v[104:107], v[108:109], off
	s_nop 0
	global_load_dwordx4 v[108:111], v[108:109], off offset:128
	s_nop 0
	global_load_dwordx4 v[112:115], v[116:117], off
	s_nop 0
	global_load_dwordx4 v[116:119], v[116:117], off offset:128
	s_nop 0
	global_load_dwordx4 v[120:123], v[124:125], off
	s_nop 0
	global_load_dwordx4 v[124:127], v[124:125], off offset:128
.LBB0_1018:
	s_lshl_b32 s0, s48, 1
	s_ashr_i32 s73, s48, 3
	s_cmp_lt_u32 s48, 8
	v_lshl_add_u32 v188, s70, 7, v145
	s_cselect_b64 s[70:71], -1, 0
	s_cmp_eq_u32 s73, 2
	s_cselect_b64 s[8:9], -1, 0
	v_and_or_b32 v175, s0, 14, v133
	s_or_b64 s[0:1], s[70:71], s[8:9]
	v_ashrrev_i32_e32 v177, 13, v188
	v_and_b32_e32 v173, 0x1fc0, v188
	s_andn2_b64 vcc, exec, s[0:1]
	s_mov_b64 s[0:1], -1
	s_cbranch_vccz .LBB0_1024
	s_cmp_eq_u32 s73, 1
	s_cbranch_scc1 .LBB0_1021
	v_mul_f32_e32 v130, 0xbfb8aa3b, v32
	v_exp_f32_e32 v130, v130
	s_nop 0
	v_add_f32_e32 v130, 1.0, v130
	v_div_scale_f32 v135, s[0:1], v130, v130, v32
	v_rcp_f32_e32 v137, v135
	s_nop 0
	v_fma_f32 v139, -v135, v137, 1.0
	v_fmac_f32_e32 v137, v139, v137
	v_div_scale_f32 v139, vcc, v32, v130, v32
	v_mul_f32_e32 v141, v139, v137
	v_fma_f32 v143, -v135, v141, v139
	v_fmac_f32_e32 v141, v143, v137
	v_fma_f32 v135, -v135, v141, v139
	v_div_fmas_f32 v135, v135, v137, v141
	v_div_fixup_f32 v130, v135, v130, v32
	v_mul_f32_e32 v135, 0xbfb8aa3b, v33
	v_exp_f32_e32 v135, v135
	s_nop 0
	v_add_f32_e32 v135, 1.0, v135
	v_div_scale_f32 v137, s[0:1], v135, v135, v33
	v_rcp_f32_e32 v139, v137
	s_nop 0
	v_fma_f32 v141, -v137, v139, 1.0
	v_fmac_f32_e32 v139, v141, v139
	v_div_scale_f32 v141, vcc, v33, v135, v33
	v_mul_f32_e32 v143, v141, v139
	v_fma_f32 v146, -v137, v143, v141
	v_fmac_f32_e32 v143, v146, v139
	v_fma_f32 v137, -v137, v143, v141
	v_div_fmas_f32 v137, v137, v139, v143
	v_div_fixup_f32 v137, v137, v135, v33
	v_mul_f32_e32 v135, 0xbfb8aa3b, v34
	v_exp_f32_e32 v135, v135
	s_nop 0
	v_add_f32_e32 v135, 1.0, v135
	v_div_scale_f32 v139, s[0:1], v135, v135, v34
	v_rcp_f32_e32 v141, v139
	s_nop 0
	v_fma_f32 v143, -v139, v141, 1.0
	v_fmac_f32_e32 v141, v143, v141
	v_div_scale_f32 v143, vcc, v34, v135, v34
	v_mul_f32_e32 v146, v143, v141
	v_fma_f32 v147, -v139, v146, v143
	v_fmac_f32_e32 v146, v147, v141
	v_fma_f32 v139, -v139, v146, v143
	v_div_fmas_f32 v139, v139, v141, v146
	v_div_fixup_f32 v139, v139, v135, v34
	v_mul_f32_e32 v135, 0xbfb8aa3b, v35
	v_exp_f32_e32 v135, v135
	s_nop 0
	v_add_f32_e32 v135, 1.0, v135
	v_div_scale_f32 v141, s[0:1], v135, v135, v35
	v_rcp_f32_e32 v143, v141
	s_nop 0
	v_fma_f32 v146, -v141, v143, 1.0
	v_fmac_f32_e32 v143, v146, v143
	v_div_scale_f32 v146, vcc, v35, v135, v35
	v_mul_f32_e32 v147, v146, v143
	v_fma_f32 v149, -v141, v147, v146
	v_fmac_f32_e32 v147, v149, v143
	v_fma_f32 v141, -v141, v147, v146
	v_div_fmas_f32 v141, v141, v143, v147
	v_div_fixup_f32 v141, v141, v135, v35
	v_mul_f32_e32 v135, 0xbfb8aa3b, v36
	v_exp_f32_e32 v135, v135
	s_nop 0
	v_add_f32_e32 v135, 1.0, v135
	v_div_scale_f32 v143, s[0:1], v135, v135, v36
	v_rcp_f32_e32 v146, v143
	s_nop 0
	v_fma_f32 v147, -v143, v146, 1.0
	v_fmac_f32_e32 v146, v147, v146
	v_div_scale_f32 v147, vcc, v36, v135, v36
	v_mul_f32_e32 v149, v147, v146
	v_fma_f32 v151, -v143, v149, v147
	v_fmac_f32_e32 v149, v151, v146
	v_fma_f32 v143, -v143, v149, v147
	v_div_fmas_f32 v143, v143, v146, v149
	v_div_fixup_f32 v143, v143, v135, v36
	v_mul_f32_e32 v135, 0xbfb8aa3b, v37
	v_exp_f32_e32 v135, v135
	s_nop 0
	v_add_f32_e32 v135, 1.0, v135
	v_div_scale_f32 v146, s[0:1], v135, v135, v37
	v_rcp_f32_e32 v147, v146
	s_nop 0
	v_fma_f32 v149, -v146, v147, 1.0
	v_fmac_f32_e32 v147, v149, v147
	v_div_scale_f32 v149, vcc, v37, v135, v37
	v_mul_f32_e32 v151, v149, v147
	v_fma_f32 v153, -v146, v151, v149
	v_fmac_f32_e32 v151, v153, v147
	v_fma_f32 v146, -v146, v151, v149
	v_div_fmas_f32 v146, v146, v147, v151
	v_div_fixup_f32 v149, v146, v135, v37
	v_mul_f32_e32 v135, 0xbfb8aa3b, v38
	v_exp_f32_e32 v135, v135
	s_nop 0
	v_add_f32_e32 v135, 1.0, v135
	v_div_scale_f32 v146, s[0:1], v135, v135, v38
	v_rcp_f32_e32 v147, v146
	s_nop 0
	v_fma_f32 v151, -v146, v147, 1.0
	v_fmac_f32_e32 v147, v151, v147
	v_div_scale_f32 v151, vcc, v38, v135, v38
	v_mul_f32_e32 v153, v151, v147
	v_fma_f32 v155, -v146, v153, v151
	v_fmac_f32_e32 v153, v155, v147
	v_fma_f32 v146, -v146, v153, v151
	v_div_fmas_f32 v146, v146, v147, v153
	v_div_fixup_f32 v151, v146, v135, v38
	v_mul_f32_e32 v135, 0xbfb8aa3b, v39
	v_exp_f32_e32 v135, v135
	s_nop 0
	v_add_f32_e32 v135, 1.0, v135
	v_div_scale_f32 v146, s[0:1], v135, v135, v39
	v_rcp_f32_e32 v147, v146
	s_nop 0
	v_fma_f32 v153, -v146, v147, 1.0
	v_fmac_f32_e32 v147, v153, v147
	v_div_scale_f32 v153, vcc, v39, v135, v39
	v_mul_f32_e32 v155, v153, v147
	v_fma_f32 v157, -v146, v155, v153
	v_fmac_f32_e32 v155, v157, v147
	v_fma_f32 v146, -v146, v155, v153
	v_div_fmas_f32 v146, v146, v147, v155
	v_div_fixup_f32 v153, v146, v135, v39
	v_mul_f32_e32 v135, 0xbfb8aa3b, v40
	v_exp_f32_e32 v135, v135
	s_nop 0
	v_add_f32_e32 v135, 1.0, v135
	v_div_scale_f32 v146, s[0:1], v135, v135, v40
	v_rcp_f32_e32 v147, v146
	s_nop 0
	v_fma_f32 v155, -v146, v147, 1.0
	v_fmac_f32_e32 v147, v155, v147
	v_div_scale_f32 v155, vcc, v40, v135, v40
	v_mul_f32_e32 v157, v155, v147
	v_fma_f32 v159, -v146, v157, v155
	v_fmac_f32_e32 v157, v159, v147
	v_fma_f32 v146, -v146, v157, v155
	v_div_fmas_f32 v146, v146, v147, v157
	v_div_fixup_f32 v155, v146, v135, v40
	v_mul_f32_e32 v135, 0xbfb8aa3b, v41
	v_exp_f32_e32 v135, v135
	s_nop 0
	v_add_f32_e32 v135, 1.0, v135
	v_div_scale_f32 v146, s[0:1], v135, v135, v41
	v_rcp_f32_e32 v147, v146
	s_nop 0
	v_fma_f32 v157, -v146, v147, 1.0
	v_fmac_f32_e32 v147, v157, v147
	v_div_scale_f32 v157, vcc, v41, v135, v41
	v_mul_f32_e32 v159, v157, v147
	v_fma_f32 v161, -v146, v159, v157
	v_fmac_f32_e32 v159, v161, v147
	v_fma_f32 v146, -v146, v159, v157
	v_div_fmas_f32 v146, v146, v147, v159
	v_div_fixup_f32 v157, v146, v135, v41
	v_mul_f32_e32 v135, 0xbfb8aa3b, v42
	v_exp_f32_e32 v135, v135
	s_nop 0
	v_add_f32_e32 v135, 1.0, v135
	v_div_scale_f32 v146, s[0:1], v135, v135, v42
	v_rcp_f32_e32 v147, v146
	s_nop 0
	v_fma_f32 v159, -v146, v147, 1.0
	v_fmac_f32_e32 v147, v159, v147
	v_div_scale_f32 v159, vcc, v42, v135, v42
	v_mul_f32_e32 v161, v159, v147
	v_fma_f32 v163, -v146, v161, v159
	v_fmac_f32_e32 v161, v163, v147
	v_fma_f32 v146, -v146, v161, v159
	v_div_fmas_f32 v146, v146, v147, v161
	v_div_fixup_f32 v159, v146, v135, v42
	v_mul_f32_e32 v135, 0xbfb8aa3b, v43
	v_exp_f32_e32 v135, v135
	s_nop 0
	v_add_f32_e32 v135, 1.0, v135
	v_div_scale_f32 v146, s[0:1], v135, v135, v43
	v_rcp_f32_e32 v147, v146
	s_nop 0
	v_fma_f32 v161, -v146, v147, 1.0
	v_fmac_f32_e32 v147, v161, v147
	v_div_scale_f32 v161, vcc, v43, v135, v43
	v_mul_f32_e32 v163, v161, v147
	v_fma_f32 v165, -v146, v163, v161
	v_fmac_f32_e32 v163, v165, v147
	v_fma_f32 v146, -v146, v163, v161
	v_div_fmas_f32 v146, v146, v147, v163
	v_div_fixup_f32 v161, v146, v135, v43
	v_mul_f32_e32 v135, 0xbfb8aa3b, v44
	v_exp_f32_e32 v135, v135
	s_nop 0
	v_add_f32_e32 v135, 1.0, v135
	v_div_scale_f32 v146, s[0:1], v135, v135, v44
	v_rcp_f32_e32 v147, v146
	s_nop 0
	v_fma_f32 v163, -v146, v147, 1.0
	v_fmac_f32_e32 v147, v163, v147
	v_div_scale_f32 v163, vcc, v44, v135, v44
	v_mul_f32_e32 v165, v163, v147
	v_fma_f32 v167, -v146, v165, v163
	v_fmac_f32_e32 v165, v167, v147
	v_fma_f32 v146, -v146, v165, v163
	v_div_fmas_f32 v146, v146, v147, v165
	v_div_fixup_f32 v163, v146, v135, v44
	v_mul_f32_e32 v135, 0xbfb8aa3b, v45
	v_exp_f32_e32 v135, v135
	s_nop 0
	v_add_f32_e32 v135, 1.0, v135
	v_div_scale_f32 v146, s[0:1], v135, v135, v45
	v_rcp_f32_e32 v147, v146
	s_nop 0
	v_fma_f32 v165, -v146, v147, 1.0
	v_fmac_f32_e32 v147, v165, v147
	v_div_scale_f32 v165, vcc, v45, v135, v45
	v_mul_f32_e32 v167, v165, v147
	v_fma_f32 v169, -v146, v167, v165
	v_fmac_f32_e32 v167, v169, v147
	v_fma_f32 v146, -v146, v167, v165
	v_div_fmas_f32 v146, v146, v147, v167
	v_div_fixup_f32 v165, v146, v135, v45
	v_mul_f32_e32 v135, 0xbfb8aa3b, v46
	v_exp_f32_e32 v135, v135
	s_nop 0
	v_add_f32_e32 v135, 1.0, v135
	v_div_scale_f32 v146, s[0:1], v135, v135, v46
	v_rcp_f32_e32 v147, v146
	s_nop 0
	v_fma_f32 v167, -v146, v147, 1.0
	v_fmac_f32_e32 v147, v167, v147
	v_div_scale_f32 v167, vcc, v46, v135, v46
	v_mul_f32_e32 v169, v167, v147
	v_fma_f32 v171, -v146, v169, v167
	v_fmac_f32_e32 v169, v171, v147
	v_fma_f32 v146, -v146, v169, v167
	v_div_fmas_f32 v146, v146, v147, v169
	v_div_fixup_f32 v167, v146, v135, v46
	v_mul_f32_e32 v135, 0xbfb8aa3b, v47
	v_exp_f32_e32 v135, v135
	s_nop 0
	v_add_f32_e32 v135, 1.0, v135
	v_div_scale_f32 v146, s[0:1], v135, v135, v47
	v_rcp_f32_e32 v147, v146
	s_nop 0
	v_fma_f32 v169, -v146, v147, 1.0
	v_fmac_f32_e32 v147, v169, v147
	v_div_scale_f32 v169, vcc, v47, v135, v47
	v_mul_f32_e32 v171, v169, v147
	v_fma_f32 v179, -v146, v171, v169
	v_fmac_f32_e32 v171, v179, v147
	v_fma_f32 v146, -v146, v171, v169
	v_div_fmas_f32 v146, v146, v147, v171
	v_div_fixup_f32 v169, v146, v135, v47
	v_mul_f32_e32 v135, 0xbfb8aa3b, v48
	v_exp_f32_e32 v135, v135
	s_nop 0
	v_add_f32_e32 v135, 1.0, v135
	v_div_scale_f32 v146, s[0:1], v135, v135, v48
	v_rcp_f32_e32 v147, v146
	s_nop 0
	v_fma_f32 v171, -v146, v147, 1.0
	v_fmac_f32_e32 v147, v171, v147
	v_div_scale_f32 v171, vcc, v48, v135, v48
	v_mul_f32_e32 v179, v171, v147
	v_fma_f32 v181, -v146, v179, v171
	v_fmac_f32_e32 v179, v181, v147
	v_fma_f32 v146, -v146, v179, v171
	v_div_fmas_f32 v146, v146, v147, v179
	v_div_fixup_f32 v171, v146, v135, v48
	v_mul_f32_e32 v135, 0xbfb8aa3b, v49
	v_exp_f32_e32 v135, v135
	s_nop 0
	v_add_f32_e32 v135, 1.0, v135
	v_div_scale_f32 v146, s[0:1], v135, v135, v49
	v_rcp_f32_e32 v147, v146
	s_nop 0
	v_fma_f32 v179, -v146, v147, 1.0
	v_fmac_f32_e32 v147, v179, v147
	v_div_scale_f32 v179, vcc, v49, v135, v49
	v_mul_f32_e32 v181, v179, v147
	v_fma_f32 v183, -v146, v181, v179
	v_fmac_f32_e32 v181, v183, v147
	v_fma_f32 v146, -v146, v181, v179
	v_div_fmas_f32 v146, v146, v147, v181
	v_div_fixup_f32 v179, v146, v135, v49
	v_mul_f32_e32 v135, 0xbfb8aa3b, v50
	v_exp_f32_e32 v135, v135
	s_nop 0
	v_add_f32_e32 v135, 1.0, v135
	v_div_scale_f32 v146, s[0:1], v135, v135, v50
	v_rcp_f32_e32 v147, v146
	s_nop 0
	v_fma_f32 v181, -v146, v147, 1.0
	v_fmac_f32_e32 v147, v181, v147
	v_div_scale_f32 v181, vcc, v50, v135, v50
	v_mul_f32_e32 v183, v181, v147
	v_fma_f32 v185, -v146, v183, v181
	v_fmac_f32_e32 v183, v185, v147
	v_fma_f32 v146, -v146, v183, v181
	v_div_fmas_f32 v146, v146, v147, v183
	v_div_fixup_f32 v181, v146, v135, v50
	v_mul_f32_e32 v135, 0xbfb8aa3b, v51
	v_exp_f32_e32 v135, v135
	s_nop 0
	v_add_f32_e32 v135, 1.0, v135
	v_div_scale_f32 v146, s[0:1], v135, v135, v51
	v_rcp_f32_e32 v147, v146
	s_nop 0
	v_fma_f32 v183, -v146, v147, 1.0
	v_fmac_f32_e32 v147, v183, v147
	v_div_scale_f32 v183, vcc, v51, v135, v51
	v_mul_f32_e32 v185, v183, v147
	v_fma_f32 v187, -v146, v185, v183
	v_fmac_f32_e32 v185, v187, v147
	v_fma_f32 v146, -v146, v185, v183
	v_div_fmas_f32 v146, v146, v147, v185
	v_div_fixup_f32 v183, v146, v135, v51
	v_mul_f32_e32 v135, 0xbfb8aa3b, v52
	v_exp_f32_e32 v135, v135
	s_nop 0
	v_add_f32_e32 v135, 1.0, v135
	v_div_scale_f32 v146, s[0:1], v135, v135, v52
	v_rcp_f32_e32 v147, v146
	s_nop 0
	v_fma_f32 v185, -v146, v147, 1.0
	v_fmac_f32_e32 v147, v185, v147
	v_div_scale_f32 v185, vcc, v52, v135, v52
	v_mul_f32_e32 v187, v185, v147
	v_fma_f32 v189, -v146, v187, v185
	v_fmac_f32_e32 v187, v189, v147
	v_fma_f32 v146, -v146, v187, v185
	v_div_fmas_f32 v146, v146, v147, v187
	v_div_fixup_f32 v185, v146, v135, v52
	v_mul_f32_e32 v135, 0xbfb8aa3b, v53
	v_exp_f32_e32 v135, v135
	s_nop 0
	v_add_f32_e32 v135, 1.0, v135
	v_div_scale_f32 v146, s[0:1], v135, v135, v53
	v_rcp_f32_e32 v147, v146
	s_nop 0
	v_fma_f32 v187, -v146, v147, 1.0
	v_fmac_f32_e32 v147, v187, v147
	v_div_scale_f32 v187, vcc, v53, v135, v53
	v_mul_f32_e32 v189, v187, v147
	v_fma_f32 v190, -v146, v189, v187
	v_fmac_f32_e32 v189, v190, v147
	v_fma_f32 v146, -v146, v189, v187
	v_div_fmas_f32 v146, v146, v147, v189
	v_div_fixup_f32 v187, v146, v135, v53
	v_mul_f32_e32 v135, 0xbfb8aa3b, v54
	v_exp_f32_e32 v135, v135
	s_nop 0
	v_add_f32_e32 v135, 1.0, v135
	v_div_scale_f32 v146, s[0:1], v135, v135, v54
	v_rcp_f32_e32 v147, v146
	s_nop 0
	v_fma_f32 v189, -v146, v147, 1.0
	v_fmac_f32_e32 v147, v189, v147
	v_div_scale_f32 v189, vcc, v54, v135, v54
	v_mul_f32_e32 v190, v189, v147
	v_fma_f32 v191, -v146, v190, v189
	v_fmac_f32_e32 v190, v191, v147
	v_fma_f32 v146, -v146, v190, v189
	v_div_fmas_f32 v146, v146, v147, v190
	v_div_fixup_f32 v190, v146, v135, v54
	v_mul_f32_e32 v135, 0xbfb8aa3b, v55
	v_exp_f32_e32 v135, v135
	s_nop 0
	v_add_f32_e32 v135, 1.0, v135
	v_div_scale_f32 v146, s[0:1], v135, v135, v55
	v_rcp_f32_e32 v147, v146
	s_nop 0
	v_fma_f32 v189, -v146, v147, 1.0
	v_fmac_f32_e32 v147, v189, v147
	v_div_scale_f32 v189, vcc, v55, v135, v55
	v_mul_f32_e32 v191, v189, v147
	v_fma_f32 v192, -v146, v191, v189
	v_fmac_f32_e32 v191, v192, v147
	v_fma_f32 v146, -v146, v191, v189
	v_div_fmas_f32 v146, v146, v147, v191
	v_div_fixup_f32 v191, v146, v135, v55
	v_mul_f32_e32 v135, 0xbfb8aa3b, v56
	v_exp_f32_e32 v135, v135
	s_nop 0
	v_add_f32_e32 v135, 1.0, v135
	v_div_scale_f32 v146, s[0:1], v135, v135, v56
	v_rcp_f32_e32 v147, v146
	s_nop 0
	v_fma_f32 v189, -v146, v147, 1.0
	v_fmac_f32_e32 v147, v189, v147
	v_div_scale_f32 v189, vcc, v56, v135, v56
	v_mul_f32_e32 v192, v189, v147
	v_fma_f32 v193, -v146, v192, v189
	v_fmac_f32_e32 v192, v193, v147
	v_fma_f32 v146, -v146, v192, v189
	v_div_fmas_f32 v146, v146, v147, v192
	v_div_fixup_f32 v192, v146, v135, v56
	v_mul_f32_e32 v135, 0xbfb8aa3b, v57
	v_exp_f32_e32 v135, v135
	s_nop 0
	v_add_f32_e32 v135, 1.0, v135
	v_div_scale_f32 v146, s[0:1], v135, v135, v57
	v_rcp_f32_e32 v147, v146
	s_nop 0
	v_fma_f32 v189, -v146, v147, 1.0
	v_fmac_f32_e32 v147, v189, v147
	v_div_scale_f32 v189, vcc, v57, v135, v57
	v_mul_f32_e32 v193, v189, v147
	v_fma_f32 v194, -v146, v193, v189
	v_fmac_f32_e32 v193, v194, v147
	v_fma_f32 v146, -v146, v193, v189
	v_div_fmas_f32 v146, v146, v147, v193
	v_div_fixup_f32 v193, v146, v135, v57
	v_mul_f32_e32 v135, 0xbfb8aa3b, v58
	v_exp_f32_e32 v135, v135
	s_nop 0
	v_add_f32_e32 v135, 1.0, v135
	v_div_scale_f32 v146, s[0:1], v135, v135, v58
	v_rcp_f32_e32 v147, v146
	s_nop 0
	v_fma_f32 v189, -v146, v147, 1.0
	v_fmac_f32_e32 v147, v189, v147
	v_div_scale_f32 v189, vcc, v58, v135, v58
	v_mul_f32_e32 v194, v189, v147
	v_fma_f32 v195, -v146, v194, v189
	v_fmac_f32_e32 v194, v195, v147
	v_fma_f32 v146, -v146, v194, v189
	v_div_fmas_f32 v146, v146, v147, v194
	v_div_fixup_f32 v194, v146, v135, v58
	v_mul_f32_e32 v135, 0xbfb8aa3b, v59
	v_exp_f32_e32 v135, v135
	s_nop 0
	v_add_f32_e32 v135, 1.0, v135
	v_div_scale_f32 v146, s[0:1], v135, v135, v59
	v_rcp_f32_e32 v147, v146
	s_nop 0
	v_fma_f32 v189, -v146, v147, 1.0
	v_fmac_f32_e32 v147, v189, v147
	v_div_scale_f32 v189, vcc, v59, v135, v59
	v_mul_f32_e32 v195, v189, v147
	v_fma_f32 v197, -v146, v195, v189
	v_fmac_f32_e32 v195, v197, v147
	v_fma_f32 v146, -v146, v195, v189
	v_div_fmas_f32 v146, v146, v147, v195
	v_div_fixup_f32 v195, v146, v135, v59
	v_mul_f32_e32 v135, 0xbfb8aa3b, v60
	v_exp_f32_e32 v135, v135
	s_nop 0
	v_add_f32_e32 v135, 1.0, v135
	v_div_scale_f32 v146, s[0:1], v135, v135, v60
	v_rcp_f32_e32 v147, v146
	s_nop 0
	v_fma_f32 v189, -v146, v147, 1.0
	v_fmac_f32_e32 v147, v189, v147
	v_div_scale_f32 v189, vcc, v60, v135, v60
	v_mul_f32_e32 v197, v189, v147
	v_fma_f32 v217, -v146, v197, v189
	v_fmac_f32_e32 v197, v217, v147
	v_fma_f32 v146, -v146, v197, v189
	v_div_fmas_f32 v146, v146, v147, v197
	v_div_fixup_f32 v217, v146, v135, v60
	v_mul_f32_e32 v135, 0xbfb8aa3b, v61
	v_exp_f32_e32 v135, v135
	s_nop 0
	v_add_f32_e32 v135, 1.0, v135
	v_div_scale_f32 v146, s[0:1], v135, v135, v61
	v_rcp_f32_e32 v147, v146
	s_nop 0
	v_fma_f32 v189, -v146, v147, 1.0
	v_fmac_f32_e32 v147, v189, v147
	v_div_scale_f32 v189, vcc, v61, v135, v61
	v_mul_f32_e32 v197, v189, v147
	v_fma_f32 v218, -v146, v197, v189
	v_fmac_f32_e32 v197, v218, v147
	v_fma_f32 v146, -v146, v197, v189
	v_div_fmas_f32 v146, v146, v147, v197
	v_div_fixup_f32 v218, v146, v135, v61
	v_mul_f32_e32 v135, 0xbfb8aa3b, v62
	v_exp_f32_e32 v135, v135
	s_nop 0
	v_add_f32_e32 v135, 1.0, v135
	v_div_scale_f32 v146, s[0:1], v135, v135, v62
	v_rcp_f32_e32 v147, v146
	s_nop 0
	v_fma_f32 v189, -v146, v147, 1.0
	v_fmac_f32_e32 v147, v189, v147
	v_div_scale_f32 v189, vcc, v62, v135, v62
	v_mul_f32_e32 v197, v189, v147
	v_fma_f32 v219, -v146, v197, v189
	v_fmac_f32_e32 v197, v219, v147
	v_fma_f32 v146, -v146, v197, v189
	v_div_fmas_f32 v146, v146, v147, v197
	v_div_fixup_f32 v219, v146, v135, v62
	v_mul_f32_e32 v135, 0xbfb8aa3b, v63
	v_exp_f32_e32 v135, v135
	s_nop 0
	v_add_f32_e32 v135, 1.0, v135
	v_div_scale_f32 v146, s[0:1], v135, v135, v63
	v_rcp_f32_e32 v147, v146
	s_nop 0
	v_fma_f32 v189, -v146, v147, 1.0
	v_fmac_f32_e32 v147, v189, v147
	v_div_scale_f32 v189, vcc, v63, v135, v63
	v_mul_f32_e32 v197, v189, v147
	v_fma_f32 v220, -v146, v197, v189
	v_fmac_f32_e32 v197, v220, v147
	v_fma_f32 v146, -v146, v197, v189
	v_div_fmas_f32 v146, v146, v147, v197
	v_div_fixup_f32 v220, v146, v135, v63
	v_mul_f32_e32 v135, 0xbfb8aa3b, v0
	v_exp_f32_e32 v135, v135
	s_nop 0
	v_add_f32_e32 v135, 1.0, v135
	v_div_scale_f32 v146, s[0:1], v135, v135, v0
	v_rcp_f32_e32 v147, v146
	s_nop 0
	v_fma_f32 v189, -v146, v147, 1.0
	v_fmac_f32_e32 v147, v189, v147
	v_div_scale_f32 v189, vcc, v0, v135, v0
	v_mul_f32_e32 v197, v189, v147
	v_fma_f32 v221, -v146, v197, v189
	v_fmac_f32_e32 v197, v221, v147
	v_fma_f32 v146, -v146, v197, v189
	v_div_fmas_f32 v146, v146, v147, v197
	v_div_fixup_f32 v221, v146, v135, v0
	v_mul_f32_e32 v135, 0xbfb8aa3b, v1
	v_exp_f32_e32 v135, v135
	s_nop 0
	v_add_f32_e32 v135, 1.0, v135
	v_div_scale_f32 v146, s[0:1], v135, v135, v1
	v_rcp_f32_e32 v147, v146
	s_nop 0
	v_fma_f32 v189, -v146, v147, 1.0
	v_fmac_f32_e32 v147, v189, v147
	v_div_scale_f32 v189, vcc, v1, v135, v1
	v_mul_f32_e32 v197, v189, v147
	v_fma_f32 v222, -v146, v197, v189
	v_fmac_f32_e32 v197, v222, v147
	v_fma_f32 v146, -v146, v197, v189
	v_div_fmas_f32 v146, v146, v147, v197
	v_div_fixup_f32 v222, v146, v135, v1
	v_mul_f32_e32 v135, 0xbfb8aa3b, v2
	v_exp_f32_e32 v135, v135
	s_nop 0
	v_add_f32_e32 v135, 1.0, v135
	v_div_scale_f32 v146, s[0:1], v135, v135, v2
	v_rcp_f32_e32 v147, v146
	s_nop 0
	v_fma_f32 v189, -v146, v147, 1.0
	v_fmac_f32_e32 v147, v189, v147
	v_div_scale_f32 v189, vcc, v2, v135, v2
	v_mul_f32_e32 v197, v189, v147
	v_fma_f32 v223, -v146, v197, v189
	v_fmac_f32_e32 v197, v223, v147
	v_fma_f32 v146, -v146, v197, v189
	v_div_fmas_f32 v146, v146, v147, v197
	v_div_fixup_f32 v223, v146, v135, v2
	v_mul_f32_e32 v135, 0xbfb8aa3b, v3
	v_exp_f32_e32 v135, v135
	s_nop 0
	v_add_f32_e32 v135, 1.0, v135
	v_div_scale_f32 v146, s[0:1], v135, v135, v3
	v_rcp_f32_e32 v147, v146
	s_nop 0
	v_fma_f32 v189, -v146, v147, 1.0
	v_fmac_f32_e32 v147, v189, v147
	v_div_scale_f32 v189, vcc, v3, v135, v3
	v_mul_f32_e32 v197, v189, v147
	v_fma_f32 v224, -v146, v197, v189
	v_fmac_f32_e32 v197, v224, v147
	v_fma_f32 v146, -v146, v197, v189
	v_div_fmas_f32 v146, v146, v147, v197
	v_div_fixup_f32 v224, v146, v135, v3
	v_mul_f32_e32 v135, 0xbfb8aa3b, v4
	v_exp_f32_e32 v135, v135
	s_nop 0
	v_add_f32_e32 v135, 1.0, v135
	v_div_scale_f32 v146, s[0:1], v135, v135, v4
	v_rcp_f32_e32 v147, v146
	s_nop 0
	v_fma_f32 v189, -v146, v147, 1.0
	v_fmac_f32_e32 v147, v189, v147
	v_div_scale_f32 v189, vcc, v4, v135, v4
	v_mul_f32_e32 v197, v189, v147
	v_fma_f32 v225, -v146, v197, v189
	v_fmac_f32_e32 v197, v225, v147
	v_fma_f32 v146, -v146, v197, v189
	v_div_fmas_f32 v146, v146, v147, v197
	v_div_fixup_f32 v225, v146, v135, v4
	v_mul_f32_e32 v135, 0xbfb8aa3b, v5
	v_exp_f32_e32 v135, v135
	s_nop 0
	v_add_f32_e32 v135, 1.0, v135
	v_div_scale_f32 v146, s[0:1], v135, v135, v5
	v_rcp_f32_e32 v147, v146
	s_nop 0
	v_fma_f32 v189, -v146, v147, 1.0
	v_fmac_f32_e32 v147, v189, v147
	v_div_scale_f32 v189, vcc, v5, v135, v5
	v_mul_f32_e32 v197, v189, v147
	v_fma_f32 v226, -v146, v197, v189
	v_fmac_f32_e32 v197, v226, v147
	v_fma_f32 v146, -v146, v197, v189
	v_div_fmas_f32 v146, v146, v147, v197
	v_div_fixup_f32 v226, v146, v135, v5
	v_mul_f32_e32 v135, 0xbfb8aa3b, v6
	v_exp_f32_e32 v135, v135
	s_nop 0
	v_add_f32_e32 v135, 1.0, v135
	v_div_scale_f32 v146, s[0:1], v135, v135, v6
	v_rcp_f32_e32 v147, v146
	s_nop 0
	v_fma_f32 v189, -v146, v147, 1.0
	v_fmac_f32_e32 v147, v189, v147
	v_div_scale_f32 v189, vcc, v6, v135, v6
	v_mul_f32_e32 v197, v189, v147
	v_fma_f32 v227, -v146, v197, v189
	v_fmac_f32_e32 v197, v227, v147
	v_fma_f32 v146, -v146, v197, v189
	v_div_fmas_f32 v146, v146, v147, v197
	v_div_fixup_f32 v227, v146, v135, v6
	v_mul_f32_e32 v135, 0xbfb8aa3b, v7
	v_exp_f32_e32 v135, v135
	s_nop 0
	v_add_f32_e32 v135, 1.0, v135
	v_div_scale_f32 v146, s[0:1], v135, v135, v7
	v_rcp_f32_e32 v147, v146
	s_nop 0
	v_fma_f32 v189, -v146, v147, 1.0
	v_fmac_f32_e32 v147, v189, v147
	v_div_scale_f32 v189, vcc, v7, v135, v7
	v_mul_f32_e32 v197, v189, v147
	v_fma_f32 v228, -v146, v197, v189
	v_fmac_f32_e32 v197, v228, v147
	v_fma_f32 v146, -v146, v197, v189
	v_div_fmas_f32 v146, v146, v147, v197
	v_div_fixup_f32 v228, v146, v135, v7
	v_mul_f32_e32 v135, 0xbfb8aa3b, v8
	v_exp_f32_e32 v135, v135
	s_nop 0
	v_add_f32_e32 v135, 1.0, v135
	v_div_scale_f32 v146, s[0:1], v135, v135, v8
	v_rcp_f32_e32 v147, v146
	s_nop 0
	v_fma_f32 v189, -v146, v147, 1.0
	v_fmac_f32_e32 v147, v189, v147
	v_div_scale_f32 v189, vcc, v8, v135, v8
	v_mul_f32_e32 v197, v189, v147
	v_fma_f32 v229, -v146, v197, v189
	v_fmac_f32_e32 v197, v229, v147
	v_fma_f32 v146, -v146, v197, v189
	v_div_fmas_f32 v146, v146, v147, v197
	v_div_fixup_f32 v229, v146, v135, v8
	v_mul_f32_e32 v135, 0xbfb8aa3b, v9
	v_exp_f32_e32 v135, v135
	s_nop 0
	v_add_f32_e32 v135, 1.0, v135
	v_div_scale_f32 v146, s[0:1], v135, v135, v9
	v_rcp_f32_e32 v147, v146
	s_nop 0
	v_fma_f32 v189, -v146, v147, 1.0
	v_fmac_f32_e32 v147, v189, v147
	v_div_scale_f32 v189, vcc, v9, v135, v9
	v_mul_f32_e32 v197, v189, v147
	v_fma_f32 v230, -v146, v197, v189
	v_fmac_f32_e32 v197, v230, v147
	v_fma_f32 v146, -v146, v197, v189
	v_div_fmas_f32 v146, v146, v147, v197
	v_div_fixup_f32 v230, v146, v135, v9
	v_mul_f32_e32 v135, 0xbfb8aa3b, v10
	v_exp_f32_e32 v135, v135
	s_nop 0
	v_add_f32_e32 v135, 1.0, v135
	v_div_scale_f32 v146, s[0:1], v135, v135, v10
	v_rcp_f32_e32 v147, v146
	s_nop 0
	v_fma_f32 v189, -v146, v147, 1.0
	v_fmac_f32_e32 v147, v189, v147
	v_div_scale_f32 v189, vcc, v10, v135, v10
	v_mul_f32_e32 v197, v189, v147
	v_fma_f32 v231, -v146, v197, v189
	v_fmac_f32_e32 v197, v231, v147
	v_fma_f32 v146, -v146, v197, v189
	v_div_fmas_f32 v146, v146, v147, v197
	v_div_fixup_f32 v231, v146, v135, v10
	v_mul_f32_e32 v135, 0xbfb8aa3b, v11
	v_exp_f32_e32 v135, v135
	s_nop 0
	v_add_f32_e32 v135, 1.0, v135
	v_div_scale_f32 v146, s[0:1], v135, v135, v11
	v_rcp_f32_e32 v147, v146
	s_nop 0
	v_fma_f32 v189, -v146, v147, 1.0
	v_fmac_f32_e32 v147, v189, v147
	v_div_scale_f32 v189, vcc, v11, v135, v11
	v_mul_f32_e32 v197, v189, v147
	v_fma_f32 v232, -v146, v197, v189
	v_fmac_f32_e32 v197, v232, v147
	v_fma_f32 v146, -v146, v197, v189
	v_div_fmas_f32 v146, v146, v147, v197
	v_div_fixup_f32 v232, v146, v135, v11
	v_mul_f32_e32 v135, 0xbfb8aa3b, v12
	v_exp_f32_e32 v135, v135
	s_nop 0
	v_add_f32_e32 v135, 1.0, v135
	v_div_scale_f32 v146, s[0:1], v135, v135, v12
	v_rcp_f32_e32 v147, v146
	s_nop 0
	v_fma_f32 v189, -v146, v147, 1.0
	v_fmac_f32_e32 v147, v189, v147
	v_div_scale_f32 v189, vcc, v12, v135, v12
	v_mul_f32_e32 v197, v189, v147
	v_fma_f32 v233, -v146, v197, v189
	v_fmac_f32_e32 v197, v233, v147
	v_fma_f32 v146, -v146, v197, v189
	v_div_fmas_f32 v146, v146, v147, v197
	v_div_fixup_f32 v233, v146, v135, v12
	v_mul_f32_e32 v135, 0xbfb8aa3b, v13
	v_exp_f32_e32 v135, v135
	s_nop 0
	v_add_f32_e32 v135, 1.0, v135
	v_div_scale_f32 v146, s[0:1], v135, v135, v13
	v_rcp_f32_e32 v147, v146
	s_nop 0
	v_fma_f32 v189, -v146, v147, 1.0
	v_fmac_f32_e32 v147, v189, v147
	v_div_scale_f32 v189, vcc, v13, v135, v13
	v_mul_f32_e32 v197, v189, v147
	v_fma_f32 v234, -v146, v197, v189
	v_fmac_f32_e32 v197, v234, v147
	v_fma_f32 v146, -v146, v197, v189
	v_div_fmas_f32 v146, v146, v147, v197
	v_div_fixup_f32 v234, v146, v135, v13
	v_mul_f32_e32 v135, 0xbfb8aa3b, v14
	v_exp_f32_e32 v135, v135
	s_nop 0
	v_add_f32_e32 v135, 1.0, v135
	v_div_scale_f32 v146, s[0:1], v135, v135, v14
	v_rcp_f32_e32 v147, v146
	s_nop 0
	v_fma_f32 v189, -v146, v147, 1.0
	v_fmac_f32_e32 v147, v189, v147
	v_div_scale_f32 v189, vcc, v14, v135, v14
	v_mul_f32_e32 v197, v189, v147
	v_fma_f32 v235, -v146, v197, v189
	v_fmac_f32_e32 v197, v235, v147
	v_fma_f32 v146, -v146, v197, v189
	v_div_fmas_f32 v146, v146, v147, v197
	v_div_fixup_f32 v235, v146, v135, v14
	v_mul_f32_e32 v135, 0xbfb8aa3b, v15
	v_exp_f32_e32 v135, v135
	s_nop 0
	v_add_f32_e32 v135, 1.0, v135
	v_div_scale_f32 v146, s[0:1], v135, v135, v15
	v_rcp_f32_e32 v147, v146
	s_nop 0
	v_fma_f32 v189, -v146, v147, 1.0
	v_fmac_f32_e32 v147, v189, v147
	v_div_scale_f32 v189, vcc, v15, v135, v15
	v_mul_f32_e32 v197, v189, v147
	v_fma_f32 v236, -v146, v197, v189
	v_fmac_f32_e32 v197, v236, v147
	v_fma_f32 v146, -v146, v197, v189
	v_div_fmas_f32 v146, v146, v147, v197
	v_div_fixup_f32 v236, v146, v135, v15
	v_mul_f32_e32 v135, 0xbfb8aa3b, v16
	v_exp_f32_e32 v135, v135
	s_nop 0
	v_add_f32_e32 v135, 1.0, v135
	v_div_scale_f32 v146, s[0:1], v135, v135, v16
	v_rcp_f32_e32 v147, v146
	s_nop 0
	v_fma_f32 v189, -v146, v147, 1.0
	v_fmac_f32_e32 v147, v189, v147
	v_div_scale_f32 v189, vcc, v16, v135, v16
	v_mul_f32_e32 v197, v189, v147
	v_fma_f32 v237, -v146, v197, v189
	v_fmac_f32_e32 v197, v237, v147
	v_fma_f32 v146, -v146, v197, v189
	v_div_fmas_f32 v146, v146, v147, v197
	v_div_fixup_f32 v237, v146, v135, v16
	v_mul_f32_e32 v135, 0xbfb8aa3b, v17
	v_exp_f32_e32 v135, v135
	s_nop 0
	v_add_f32_e32 v135, 1.0, v135
	v_div_scale_f32 v146, s[0:1], v135, v135, v17
	v_rcp_f32_e32 v147, v146
	s_nop 0
	v_fma_f32 v189, -v146, v147, 1.0
	v_fmac_f32_e32 v147, v189, v147
	v_div_scale_f32 v189, vcc, v17, v135, v17
	v_mul_f32_e32 v197, v189, v147
	v_fma_f32 v238, -v146, v197, v189
	v_fmac_f32_e32 v197, v238, v147
	v_fma_f32 v146, -v146, v197, v189
	v_div_fmas_f32 v146, v146, v147, v197
	v_div_fixup_f32 v238, v146, v135, v17
	v_mul_f32_e32 v135, 0xbfb8aa3b, v18
	v_exp_f32_e32 v135, v135
	s_nop 0
	v_add_f32_e32 v135, 1.0, v135
	v_div_scale_f32 v146, s[0:1], v135, v135, v18
	v_rcp_f32_e32 v147, v146
	s_nop 0
	v_fma_f32 v189, -v146, v147, 1.0
	v_fmac_f32_e32 v147, v189, v147
	v_div_scale_f32 v189, vcc, v18, v135, v18
	v_mul_f32_e32 v197, v189, v147
	v_fma_f32 v239, -v146, v197, v189
	v_fmac_f32_e32 v197, v239, v147
	v_fma_f32 v146, -v146, v197, v189
	v_div_fmas_f32 v146, v146, v147, v197
	v_div_fixup_f32 v239, v146, v135, v18
	v_mul_f32_e32 v135, 0xbfb8aa3b, v19
	v_exp_f32_e32 v135, v135
	s_nop 0
	v_add_f32_e32 v135, 1.0, v135
	v_div_scale_f32 v146, s[0:1], v135, v135, v19
	v_rcp_f32_e32 v147, v146
	s_nop 0
	v_fma_f32 v189, -v146, v147, 1.0
	v_fmac_f32_e32 v147, v189, v147
	v_div_scale_f32 v189, vcc, v19, v135, v19
	v_mul_f32_e32 v197, v189, v147
	v_fma_f32 v240, -v146, v197, v189
	v_fmac_f32_e32 v197, v240, v147
	v_fma_f32 v146, -v146, v197, v189
	v_div_fmas_f32 v146, v146, v147, v197
	v_div_fixup_f32 v240, v146, v135, v19
	v_mul_f32_e32 v135, 0xbfb8aa3b, v20
	v_exp_f32_e32 v135, v135
	s_nop 0
	v_add_f32_e32 v135, 1.0, v135
	v_div_scale_f32 v146, s[0:1], v135, v135, v20
	v_rcp_f32_e32 v147, v146
	s_nop 0
	v_fma_f32 v189, -v146, v147, 1.0
	v_fmac_f32_e32 v147, v189, v147
	v_div_scale_f32 v189, vcc, v20, v135, v20
	v_mul_f32_e32 v197, v189, v147
	v_fma_f32 v241, -v146, v197, v189
	v_fmac_f32_e32 v197, v241, v147
	v_fma_f32 v146, -v146, v197, v189
	v_div_fmas_f32 v146, v146, v147, v197
	v_div_fixup_f32 v241, v146, v135, v20
	v_mul_f32_e32 v135, 0xbfb8aa3b, v21
	v_exp_f32_e32 v135, v135
	s_nop 0
	v_add_f32_e32 v135, 1.0, v135
	v_div_scale_f32 v146, s[0:1], v135, v135, v21
	v_rcp_f32_e32 v147, v146
	s_nop 0
	v_fma_f32 v189, -v146, v147, 1.0
	v_fmac_f32_e32 v147, v189, v147
	v_div_scale_f32 v189, vcc, v21, v135, v21
	v_mul_f32_e32 v197, v189, v147
	v_fma_f32 v242, -v146, v197, v189
	v_fmac_f32_e32 v197, v242, v147
	v_fma_f32 v146, -v146, v197, v189
	v_div_fmas_f32 v146, v146, v147, v197
	v_div_fixup_f32 v242, v146, v135, v21
	v_mul_f32_e32 v135, 0xbfb8aa3b, v22
	v_exp_f32_e32 v135, v135
	s_nop 0
	v_add_f32_e32 v135, 1.0, v135
	v_div_scale_f32 v146, s[0:1], v135, v135, v22
	v_rcp_f32_e32 v147, v146
	s_nop 0
	v_fma_f32 v189, -v146, v147, 1.0
	v_fmac_f32_e32 v147, v189, v147
	v_div_scale_f32 v189, vcc, v22, v135, v22
	v_mul_f32_e32 v197, v189, v147
	v_fma_f32 v243, -v146, v197, v189
	v_fmac_f32_e32 v197, v243, v147
	v_fma_f32 v146, -v146, v197, v189
	v_div_fmas_f32 v146, v146, v147, v197
	v_div_fixup_f32 v243, v146, v135, v22
	v_mul_f32_e32 v135, 0xbfb8aa3b, v23
	v_exp_f32_e32 v135, v135
	s_nop 0
	v_add_f32_e32 v135, 1.0, v135
	v_div_scale_f32 v146, s[0:1], v135, v135, v23
	v_rcp_f32_e32 v147, v146
	s_nop 0
	v_fma_f32 v189, -v146, v147, 1.0
	v_fmac_f32_e32 v147, v189, v147
	v_div_scale_f32 v189, vcc, v23, v135, v23
	v_mul_f32_e32 v197, v189, v147
	v_fma_f32 v244, -v146, v197, v189
	v_fmac_f32_e32 v197, v244, v147
	v_fma_f32 v146, -v146, v197, v189
	v_div_fmas_f32 v146, v146, v147, v197
	v_div_fixup_f32 v244, v146, v135, v23
	v_mul_f32_e32 v135, 0xbfb8aa3b, v24
	v_exp_f32_e32 v135, v135
	s_nop 0
	v_add_f32_e32 v135, 1.0, v135
	v_div_scale_f32 v146, s[0:1], v135, v135, v24
	v_rcp_f32_e32 v147, v146
	s_nop 0
	v_fma_f32 v189, -v146, v147, 1.0
	v_fmac_f32_e32 v147, v189, v147
	v_div_scale_f32 v189, vcc, v24, v135, v24
	v_mul_f32_e32 v197, v189, v147
	v_fma_f32 v245, -v146, v197, v189
	v_fmac_f32_e32 v197, v245, v147
	v_fma_f32 v146, -v146, v197, v189
	v_div_fmas_f32 v146, v146, v147, v197
	v_div_fixup_f32 v245, v146, v135, v24
	v_mul_f32_e32 v135, 0xbfb8aa3b, v25
	v_exp_f32_e32 v135, v135
	s_nop 0
	v_add_f32_e32 v135, 1.0, v135
	v_div_scale_f32 v146, s[0:1], v135, v135, v25
	v_rcp_f32_e32 v147, v146
	s_nop 0
	v_fma_f32 v189, -v146, v147, 1.0
	v_fmac_f32_e32 v147, v189, v147
	v_div_scale_f32 v189, vcc, v25, v135, v25
	v_mul_f32_e32 v197, v189, v147
	v_fma_f32 v246, -v146, v197, v189
	v_fmac_f32_e32 v197, v246, v147
	v_fma_f32 v146, -v146, v197, v189
	v_div_fmas_f32 v146, v146, v147, v197
	v_div_fixup_f32 v197, v146, v135, v25
	v_mul_f32_e32 v135, 0xbfb8aa3b, v26
	v_exp_f32_e32 v135, v135
	s_nop 0
	v_add_f32_e32 v135, 1.0, v135
	v_div_scale_f32 v146, s[0:1], v135, v135, v26
	v_rcp_f32_e32 v147, v146
	s_nop 0
	v_fma_f32 v189, -v146, v147, 1.0
	v_fmac_f32_e32 v147, v189, v147
	v_div_scale_f32 v189, vcc, v26, v135, v26
	v_mul_f32_e32 v246, v189, v147
	v_fma_f32 v247, -v146, v246, v189
	v_fmac_f32_e32 v246, v247, v147
	v_fma_f32 v146, -v146, v246, v189
	v_div_fmas_f32 v146, v146, v147, v246
	v_div_fixup_f32 v246, v146, v135, v26
	v_mul_f32_e32 v135, 0xbfb8aa3b, v27
	v_exp_f32_e32 v135, v135
	s_nop 0
	v_add_f32_e32 v135, 1.0, v135
	v_div_scale_f32 v146, s[0:1], v135, v135, v27
	v_rcp_f32_e32 v147, v146
	s_nop 0
	v_fma_f32 v189, -v146, v147, 1.0
	v_fmac_f32_e32 v147, v189, v147
	v_div_scale_f32 v189, vcc, v27, v135, v27
	v_mul_f32_e32 v247, v189, v147
	v_fma_f32 v248, -v146, v247, v189
	v_fmac_f32_e32 v247, v248, v147
	v_fma_f32 v146, -v146, v247, v189
	v_div_fmas_f32 v146, v146, v147, v247
	v_div_fixup_f32 v247, v146, v135, v27
	v_mul_f32_e32 v135, 0xbfb8aa3b, v28
	v_exp_f32_e32 v135, v135
	s_nop 0
	v_add_f32_e32 v135, 1.0, v135
	v_div_scale_f32 v146, s[0:1], v135, v135, v28
	v_rcp_f32_e32 v147, v146
	s_nop 0
	v_fma_f32 v189, -v146, v147, 1.0
	v_fmac_f32_e32 v147, v189, v147
	v_div_scale_f32 v189, vcc, v28, v135, v28
	v_mul_f32_e32 v248, v189, v147
	v_fma_f32 v249, -v146, v248, v189
	v_fmac_f32_e32 v248, v249, v147
	v_fma_f32 v146, -v146, v248, v189
	v_div_fmas_f32 v146, v146, v147, v248
	v_div_fixup_f32 v248, v146, v135, v28
	v_mul_f32_e32 v135, 0xbfb8aa3b, v29
	v_exp_f32_e32 v135, v135
	s_nop 0
	v_add_f32_e32 v135, 1.0, v135
	v_div_scale_f32 v146, s[0:1], v135, v135, v29
	v_rcp_f32_e32 v147, v146
	s_nop 0
	v_fma_f32 v189, -v146, v147, 1.0
	v_fmac_f32_e32 v147, v189, v147
	v_div_scale_f32 v189, vcc, v29, v135, v29
	v_mul_f32_e32 v249, v189, v147
	v_fma_f32 v250, -v146, v249, v189
	v_fmac_f32_e32 v249, v250, v147
	v_fma_f32 v146, -v146, v249, v189
	v_div_fmas_f32 v146, v146, v147, v249
	v_div_fixup_f32 v249, v146, v135, v29
	v_mul_f32_e32 v135, 0xbfb8aa3b, v30
	v_exp_f32_e32 v135, v135
	s_nop 0
	v_add_f32_e32 v135, 1.0, v135
	v_div_scale_f32 v146, s[0:1], v135, v135, v30
	v_rcp_f32_e32 v147, v146
	s_nop 0
	v_fma_f32 v189, -v146, v147, 1.0
	v_fmac_f32_e32 v147, v189, v147
	v_div_scale_f32 v189, vcc, v30, v135, v30
	v_mul_f32_e32 v250, v189, v147
	v_fma_f32 v251, -v146, v250, v189
	v_fmac_f32_e32 v250, v251, v147
	v_fma_f32 v146, -v146, v250, v189
	v_div_fmas_f32 v146, v146, v147, v250
	v_div_fixup_f32 v250, v146, v135, v30
	v_mul_f32_e32 v135, 0xbfb8aa3b, v31
	v_exp_f32_e32 v135, v135
	s_nop 0
	v_add_f32_e32 v135, 1.0, v135
	v_div_scale_f32 v146, s[0:1], v135, v135, v31
	v_rcp_f32_e32 v147, v146
	s_lshl_b32 s0, s48, 8
	s_and_b32 s48, s0, 0x700
	v_cvt_pk_bf16_f32 v130, v130, s0
	v_fma_f32 v189, -v146, v147, 1.0
	v_fmac_f32_e32 v147, v189, v147
	v_div_scale_f32 v189, vcc, v31, v135, v31
	v_mul_f32_e32 v251, v189, v147
	v_fma_f32 v252, -v146, v251, v189
	v_fmac_f32_e32 v251, v252, v147
	v_fma_f32 v146, -v146, v251, v189
	v_div_fmas_f32 v146, v146, v147, v251
	v_ashrrev_i32_e32 v189, 31, v188
	v_div_fixup_f32 v251, v146, v135, v31
	v_lshlrev_b64 v[146:147], 11, v[188:189]
	v_lshl_add_u64 v[146:147], s[42:43], 0, v[146:147]
	v_lshl_add_u64 v[146:147], v[146:147], 0, s[48:49]
	v_mov_b32_e32 v135, v131
	v_lshl_add_u64 v[146:147], v[146:147], 0, v[134:135]
	v_add_u32_e32 v135, v198, v199
	ds_write_b16 v135, v130
	v_cvt_pk_bf16_f32 v130, v137, s0
	ds_write_b16 v135, v130 offset:144
	v_cvt_pk_bf16_f32 v130, v139, s0
	ds_write_b16 v135, v130 offset:288
	v_cvt_pk_bf16_f32 v130, v141, s0
	v_add_u32_e32 v137, v198, v200
	ds_write_b16 v137, v130
	v_cvt_pk_bf16_f32 v130, v143, s0
	ds_write_b16 v135, v130 offset:1152
	v_cvt_pk_bf16_f32 v130, v149, s0
	ds_write_b16 v135, v130 offset:1296
	v_cvt_pk_bf16_f32 v130, v151, s0
	ds_write_b16 v135, v130 offset:1440
	v_cvt_pk_bf16_f32 v130, v153, s0
	v_add_u32_e32 v137, v198, v201
	ds_write_b16 v137, v130
	v_cvt_pk_bf16_f32 v130, v155, s0
	ds_write_b16 v135, v130 offset:2304
	v_cvt_pk_bf16_f32 v130, v157, s0
	ds_write_b16 v135, v130 offset:2448
	v_cvt_pk_bf16_f32 v130, v159, s0
	ds_write_b16 v135, v130 offset:2592
	v_cvt_pk_bf16_f32 v130, v161, s0
	v_add_u32_e32 v137, v198, v202
	ds_write_b16 v137, v130
	v_cvt_pk_bf16_f32 v130, v163, s0
	ds_write_b16 v135, v130 offset:3456
	v_cvt_pk_bf16_f32 v130, v165, s0
	ds_write_b16 v135, v130 offset:3600
	v_cvt_pk_bf16_f32 v130, v167, s0
	ds_write_b16 v135, v130 offset:3744
	v_cvt_pk_bf16_f32 v130, v169, s0
	v_add_u32_e32 v137, v198, v203
	ds_write_b16 v137, v130
	v_cvt_pk_bf16_f32 v130, v171, s0
	v_add_u32_e32 v137, v204, v199
	ds_write_b16 v137, v130
	v_cvt_pk_bf16_f32 v130, v179, s0
	ds_write_b16 v137, v130 offset:144
	v_cvt_pk_bf16_f32 v130, v181, s0
	ds_write_b16 v137, v130 offset:288
	v_cvt_pk_bf16_f32 v130, v183, s0
	v_add_u32_e32 v139, v204, v200
	ds_write_b16 v139, v130
	v_cvt_pk_bf16_f32 v130, v185, s0
	ds_write_b16 v137, v130 offset:1152
	v_cvt_pk_bf16_f32 v130, v187, s0
	ds_write_b16 v137, v130 offset:1296
	v_cvt_pk_bf16_f32 v130, v190, s0
	ds_write_b16 v137, v130 offset:1440
	v_cvt_pk_bf16_f32 v130, v191, s0
	v_add_u32_e32 v139, v204, v201
	ds_write_b16 v139, v130
	v_cvt_pk_bf16_f32 v130, v192, s0
	ds_write_b16 v137, v130 offset:2304
	v_cvt_pk_bf16_f32 v130, v193, s0
	ds_write_b16 v137, v130 offset:2448
	v_cvt_pk_bf16_f32 v130, v194, s0
	ds_write_b16 v137, v130 offset:2592
	v_cvt_pk_bf16_f32 v130, v195, s0
	v_add_u32_e32 v139, v204, v202
	ds_write_b16 v139, v130
	v_cvt_pk_bf16_f32 v130, v217, s0
	ds_write_b16 v137, v130 offset:3456
	v_cvt_pk_bf16_f32 v130, v218, s0
	ds_write_b16 v137, v130 offset:3600
	v_cvt_pk_bf16_f32 v130, v219, s0
	ds_write_b16 v137, v130 offset:3744
	v_cvt_pk_bf16_f32 v130, v220, s0
	v_add_u32_e32 v139, v204, v203
	ds_write_b16 v139, v130
	v_cvt_pk_bf16_f32 v130, v221, s0
	ds_write_b16 v135, v130 offset:4608
	v_cvt_pk_bf16_f32 v130, v222, s0
	ds_write_b16 v135, v130 offset:4752
	v_cvt_pk_bf16_f32 v130, v223, s0
	ds_write_b16 v135, v130 offset:4896
	v_cvt_pk_bf16_f32 v130, v224, s0
	v_add_u32_e32 v139, v198, v205
	ds_write_b16 v139, v130
	v_cvt_pk_bf16_f32 v130, v225, s0
	ds_write_b16 v135, v130 offset:5760
	v_cvt_pk_bf16_f32 v130, v226, s0
	ds_write_b16 v135, v130 offset:5904
	v_cvt_pk_bf16_f32 v130, v227, s0
	ds_write_b16 v135, v130 offset:6048
	v_cvt_pk_bf16_f32 v130, v228, s0
	v_add_u32_e32 v139, v198, v206
	ds_write_b16 v139, v130
	v_cvt_pk_bf16_f32 v130, v229, s0
	ds_write_b16 v135, v130 offset:6912
	v_cvt_pk_bf16_f32 v130, v230, s0
	ds_write_b16 v135, v130 offset:7056
	v_cvt_pk_bf16_f32 v130, v231, s0
	ds_write_b16 v135, v130 offset:7200
	v_cvt_pk_bf16_f32 v130, v232, s0
	v_add_u32_e32 v139, v198, v207
	ds_write_b16 v139, v130
	v_cvt_pk_bf16_f32 v130, v233, s0
	ds_write_b16 v135, v130 offset:8064
	v_cvt_pk_bf16_f32 v130, v234, s0
	ds_write_b16 v135, v130 offset:8208
	v_cvt_pk_bf16_f32 v130, v235, s0
	ds_write_b16 v135, v130 offset:8352
	v_cvt_pk_bf16_f32 v130, v236, s0
	v_add_u32_e32 v135, v198, v208
	ds_write_b16 v135, v130
	v_cvt_pk_bf16_f32 v130, v237, s0
	ds_write_b16 v137, v130 offset:4608
	v_cvt_pk_bf16_f32 v130, v238, s0
	ds_write_b16 v137, v130 offset:4752
	v_cvt_pk_bf16_f32 v130, v239, s0
	ds_write_b16 v137, v130 offset:4896
	v_cvt_pk_bf16_f32 v130, v240, s0
	v_add_u32_e32 v135, v204, v205
	ds_write_b16 v135, v130
	v_cvt_pk_bf16_f32 v130, v241, s0
	ds_write_b16 v137, v130 offset:5760
	v_cvt_pk_bf16_f32 v130, v242, s0
	ds_write_b16 v137, v130 offset:5904
	v_cvt_pk_bf16_f32 v130, v243, s0
	ds_write_b16 v137, v130 offset:6048
	v_cvt_pk_bf16_f32 v130, v244, s0
	v_add_u32_e32 v135, v204, v206
	ds_write_b16 v135, v130
	v_cvt_pk_bf16_f32 v130, v245, s0
	ds_write_b16 v137, v130 offset:6912
	v_cvt_pk_bf16_f32 v130, v197, s0
	ds_write_b16 v137, v130 offset:7056
	v_cvt_pk_bf16_f32 v130, v246, s0
	ds_write_b16 v137, v130 offset:7200
	v_cvt_pk_bf16_f32 v130, v247, s0
	v_add_u32_e32 v135, v204, v207
	ds_write_b16 v135, v130
	v_cvt_pk_bf16_f32 v130, v248, s0
	ds_write_b16 v137, v130 offset:8064
	v_cvt_pk_bf16_f32 v130, v249, s0
	ds_write_b16 v137, v130 offset:8208
	v_cvt_pk_bf16_f32 v130, v250, s0
	ds_write_b16 v137, v130 offset:8352
	v_cvt_pk_bf16_f32 v130, v251, s0
	v_add_u32_e32 v135, v204, v208
	ds_write_b16 v135, v130
	v_lshlrev_b32_e32 v130, 1, v132
	v_lshl_add_u64 v[146:147], v[146:147], 0, v[130:131]
	v_add_u32_e32 v130, v209, v210
	ds_read_b128 v[190:193], v130
	v_mov_b32_e32 v137, v131
	v_lshl_add_u64 v[194:195], v[146:147], 0, v[136:137]
	v_mov_b32_e32 v139, v131
	v_mov_b32_e32 v141, v131
	s_waitcnt lgkmcnt(0)
	global_store_dwordx4 v[194:195], v[190:193], off
	ds_read_b128 v[190:193], v130 offset:1152
	v_lshl_add_u64 v[194:195], v[146:147], 0, v[138:139]
	v_mov_b32_e32 v143, v131
	v_mov_b32_e32 v149, v131
	v_mov_b32_e32 v151, v131
	s_waitcnt lgkmcnt(0)
	global_store_dwordx4 v[194:195], v[190:193], off
	ds_read_b128 v[190:193], v130 offset:2304
	v_lshl_add_u64 v[194:195], v[146:147], 0, v[140:141]
	v_mov_b32_e32 v153, v131
	v_mov_b32_e32 v155, v131
	v_and_b32_e32 v244, 63, v196
	s_waitcnt lgkmcnt(0)
	global_store_dwordx4 v[194:195], v[190:193], off
	ds_read_b128 v[190:193], v130 offset:3456
	v_lshl_add_u64 v[194:195], v[146:147], 0, v[142:143]
	s_mov_b64 s[0:1], 0
	s_waitcnt lgkmcnt(0)
	global_store_dwordx4 v[194:195], v[190:193], off
	ds_read_b128 v[190:193], v130 offset:4608
	v_lshl_add_u64 v[194:195], v[146:147], 0, v[148:149]
	s_waitcnt lgkmcnt(0)
	global_store_dwordx4 v[194:195], v[190:193], off
	ds_read_b128 v[190:193], v130 offset:5760
	v_lshl_add_u64 v[194:195], v[146:147], 0, v[150:151]
	s_waitcnt lgkmcnt(0)
	global_store_dwordx4 v[194:195], v[190:193], off
	ds_read_b128 v[190:193], v130 offset:6912
	v_lshl_add_u64 v[194:195], v[146:147], 0, v[152:153]
	v_lshl_add_u64 v[146:147], v[146:147], 0, v[154:155]
	s_waitcnt lgkmcnt(0)
	global_store_dwordx4 v[194:195], v[190:193], off
	ds_read_b128 v[190:193], v130 offset:8064
	s_waitcnt lgkmcnt(0)
	global_store_dwordx4 v[146:147], v[190:193], off
.LBB0_1021:
	s_andn2_b64 vcc, exec, s[0:1]
	s_cbranch_vccnz .LBB0_1023
	v_cvt_pk_bf16_f32 v190, v32, v33
	v_cvt_pk_bf16_f32 v191, v34, v35
	v_cvt_pk_bf16_f32 v192, v36, v37
	v_cvt_pk_bf16_f32 v193, v38, v39
	ds_write2_b64 v213, v[190:191], v[192:193] offset1:2
	v_cvt_pk_bf16_f32 v190, v40, v41
	v_cvt_pk_bf16_f32 v191, v42, v43
	v_cvt_pk_bf16_f32 v192, v44, v45
	v_cvt_pk_bf16_f32 v193, v46, v47
	ds_write2_b64 v213, v[190:191], v[192:193] offset0:4 offset1:6
	v_cvt_pk_bf16_f32 v190, v48, v49
	v_cvt_pk_bf16_f32 v191, v50, v51
	v_cvt_pk_bf16_f32 v192, v52, v53
	v_cvt_pk_bf16_f32 v193, v54, v55
	ds_write2_b64 v214, v[190:191], v[192:193] offset1:2
	v_cvt_pk_bf16_f32 v190, v56, v57
	v_cvt_pk_bf16_f32 v191, v58, v59
	v_cvt_pk_bf16_f32 v192, v60, v61
	v_cvt_pk_bf16_f32 v193, v62, v63
	ds_write2_b64 v214, v[190:191], v[192:193] offset0:4 offset1:6
	v_cvt_pk_bf16_f32 v190, v0, v1
	v_cvt_pk_bf16_f32 v191, v2, v3
	v_cvt_pk_bf16_f32 v192, v4, v5
	v_cvt_pk_bf16_f32 v193, v6, v7
	ds_write2_b64 v213, v[190:191], v[192:193] offset0:8 offset1:10
	v_cvt_pk_bf16_f32 v190, v8, v9
	v_cvt_pk_bf16_f32 v191, v10, v11
	v_cvt_pk_bf16_f32 v192, v12, v13
	v_cvt_pk_bf16_f32 v193, v14, v15
	v_lshl_or_b32 v146, v177, 4, v175
	ds_write2_b64 v213, v[190:191], v[192:193] offset0:12 offset1:14
	v_cvt_pk_bf16_f32 v190, v16, v17
	v_cvt_pk_bf16_f32 v191, v18, v19
	v_cvt_pk_bf16_f32 v192, v20, v21
	v_cvt_pk_bf16_f32 v193, v22, v23
	v_ashrrev_i32_e32 v147, 31, v146
	ds_write2_b64 v214, v[190:191], v[192:193] offset0:8 offset1:10
	v_cvt_pk_bf16_f32 v190, v24, v25
	v_cvt_pk_bf16_f32 v191, v26, v27
	v_cvt_pk_bf16_f32 v192, v28, v29
	v_cvt_pk_bf16_f32 v193, v30, v31
	v_add_u32_e32 v135, v209, v210
	v_lshlrev_b64 v[146:147], 20, v[146:147]
	ds_write2_b64 v214, v[190:191], v[192:193] offset0:12 offset1:14
	ds_read_b128 v[190:193], v135
	v_lshl_add_u64 v[146:147], s[40:41], 0, v[146:147]
	v_lshlrev_b32_e32 v130, 1, v173
	v_lshl_add_u64 v[146:147], v[146:147], 0, v[130:131]
	v_lshlrev_b32_e32 v130, 1, v132
	v_lshl_add_u64 v[146:147], v[146:147], 0, v[130:131]
	v_mov_b32_e32 v157, v131
	v_lshl_add_u64 v[194:195], v[146:147], 0, v[156:157]
	s_waitcnt lgkmcnt(0)
	global_store_dwordx4 v[194:195], v[190:193], off
	ds_read_b128 v[190:193], v135 offset:1152
	v_mov_b32_e32 v159, v131
	v_lshl_add_u64 v[194:195], v[146:147], 0, v[158:159]
	v_mov_b32_e32 v161, v131
	v_mov_b32_e32 v163, v131
	s_waitcnt lgkmcnt(0)
	global_store_dwordx4 v[194:195], v[190:193], off
	ds_read_b128 v[190:193], v135 offset:2304
	v_lshl_add_u64 v[194:195], v[146:147], 0, v[160:161]
	v_mov_b32_e32 v165, v131
	v_mov_b32_e32 v167, v131
	v_mov_b32_e32 v169, v131
	s_waitcnt lgkmcnt(0)
	global_store_dwordx4 v[194:195], v[190:193], off
	ds_read_b128 v[190:193], v135 offset:3456
	v_lshl_add_u64 v[194:195], v[146:147], 0, v[162:163]
	v_mov_b32_e32 v171, v131
	s_waitcnt lgkmcnt(0)
	global_store_dwordx4 v[194:195], v[190:193], off
	ds_read_b128 v[190:193], v135 offset:4608
	v_lshl_add_u64 v[194:195], v[146:147], 0, v[164:165]
	s_waitcnt lgkmcnt(0)
	global_store_dwordx4 v[194:195], v[190:193], off
	ds_read_b128 v[190:193], v135 offset:5760
	v_lshl_add_u64 v[194:195], v[146:147], 0, v[166:167]
	s_waitcnt lgkmcnt(0)
	global_store_dwordx4 v[194:195], v[190:193], off
	ds_read_b128 v[190:193], v135 offset:6912
	v_lshl_add_u64 v[194:195], v[146:147], 0, v[168:169]
	v_lshl_add_u64 v[146:147], v[146:147], 0, v[170:171]
	s_waitcnt lgkmcnt(0)
	global_store_dwordx4 v[194:195], v[190:193], off
	ds_read_b128 v[190:193], v135 offset:8064
	s_waitcnt lgkmcnt(0)
	global_store_dwordx4 v[146:147], v[190:193], off

.LBB0_1024:
	s_andn2_b64 vcc, exec, s[0:1]
	s_cbranch_vccnz .LBB0_1005
	v_lshlrev_b32_e32 v130, 3, v129
	s_and_b64 s[0:1], s[70:71], exec
	v_lshl_or_b32 v130, v173, 6, v130
	s_cselect_b32 s1, s61, s67
	s_cselect_b32 s0, s60, s66
	v_lshlrev_b32_e32 v190, 2, v128
	v_lshl_add_u64 v[146:147], s[44:45], 0, v[130:131]
	global_load_dword v137, v190, s[0:1] offset:128
	global_load_dwordx2 v[194:195], v[146:147], off
	global_load_dwordx2 v[218:219], v[146:147], off offset:512
	global_load_dwordx2 v[220:221], v[146:147], off offset:1024
	global_load_dwordx2 v[222:223], v[146:147], off offset:1536
	global_load_dwordx2 v[224:225], v[146:147], off offset:2048
	global_load_dwordx2 v[226:227], v[146:147], off offset:2560
	global_load_dwordx2 v[228:229], v[146:147], off offset:3072
	s_nop 0
	global_load_dwordx2 v[146:147], v[146:147], off offset:3584
	s_nop 0
	global_load_dword v139, v190, s[0:1]
	v_mov_b32_e32 v230, v32
	v_mov_b32_e32 v231, v48
	v_mov_b32_e32 v232, v33
	v_mov_b32_e32 v233, v49
	v_pk_mul_f32 v[230:231], v[230:231], v[230:231]
	v_pk_mul_f32 v[232:233], v[232:233], v[232:233]
	v_mov_b32_e32 v239, v230
	v_mov_b32_e32 v238, v232
	v_mov_b32_e32 v230, v233
	v_pk_add_f32 v[230:231], v[238:239], v[230:231]
	v_and_b32_e32 v130, 64, v216
	v_xor_b32_e32 v135, 16, v216
	v_mov_b32_dpp v233, v231 quad_perm:[1,0,3,2] row_mask:0xf bank_mask:0xf bound_ctrl:1
	v_mov_b32_dpp v232, v230 quad_perm:[1,0,3,2] row_mask:0xf bank_mask:0xf bound_ctrl:1
	v_pk_add_f32 v[230:231], v[230:231], v[232:233]
	v_add_u32_e32 v130, 64, v130
	v_cmp_lt_i32_e32 vcc, v135, v130
	v_mov_b32_dpp v233, v231 quad_perm:[2,3,0,1] row_mask:0xf bank_mask:0xf bound_ctrl:1
	v_mov_b32_dpp v232, v230 quad_perm:[2,3,0,1] row_mask:0xf bank_mask:0xf bound_ctrl:1
	v_pk_add_f32 v[230:231], v[230:231], v[232:233]
	v_cndmask_b32_e32 v135, v216, v135, vcc
	v_lshlrev_b32_e32 v135, 2, v135
	v_mov_b32_dpp v233, v231 row_half_mirror row_mask:0xf bank_mask:0xf bound_ctrl:1
	v_mov_b32_dpp v232, v230 row_half_mirror row_mask:0xf bank_mask:0xf bound_ctrl:1
	v_pk_add_f32 v[230:231], v[230:231], v[232:233]
	v_mov_b32_e32 v234, v34
	v_mov_b32_e32 v235, v50
	v_mov_b32_dpp v233, v231 row_mirror row_mask:0xf bank_mask:0xf bound_ctrl:1
	v_mov_b32_dpp v232, v230 row_mirror row_mask:0xf bank_mask:0xf bound_ctrl:1
	v_pk_add_f32 v[230:231], v[230:231], v[232:233]
	ds_bpermute_b32 v233, v135, v231
	ds_bpermute_b32 v232, v135, v230
	v_mov_b32_e32 v236, v35
	v_mov_b32_e32 v237, v51
	v_mov_b64_e32 v[192:193], s[64:65]
	v_pk_mul_f32 v[234:235], v[234:235], v[234:235]
	v_pk_mul_f32 v[236:237], v[236:237], v[236:237]
	s_waitcnt lgkmcnt(0)
	v_pk_add_f32 v[230:231], v[230:231], v[232:233]
	v_mov_b32_e32 v238, v236
	v_mov_b32_e32 v239, v234
	v_mov_b32_e32 v234, v237
	v_pk_fma_f32 v[230:231], v[230:231], s[62:63], v[192:193] op_sel_hi:[1,0,0]
	v_pk_add_f32 v[234:235], v[238:239], v[234:235]
	v_mul_f32_e32 v143, 0x4b800000, v231
	v_mul_f32_e32 v149, 0x4b800000, v230
	v_cmp_gt_f32_e32 vcc, s46, v231
	v_cmp_gt_f32_e64 s[0:1], s46, v230
	v_cndmask_b32_e64 v141, 1.0, v215, s[8:9]
	v_cndmask_b32_e32 v143, v231, v143, vcc
	v_cndmask_b32_e64 v149, v230, v149, s[0:1]
	v_mov_b32_dpp v231, v235 quad_perm:[1,0,3,2] row_mask:0xf bank_mask:0xf bound_ctrl:1
	v_mov_b32_dpp v230, v234 quad_perm:[1,0,3,2] row_mask:0xf bank_mask:0xf bound_ctrl:1
	v_rsq_f32_e32 v143, v143
	v_rsq_f32_e32 v149, v149
	s_waitcnt vmcnt(0)
	ds_write2st64_b64 v211, v[194:195], v[218:219] offset1:1
	ds_write2st64_b64 v211, v[220:221], v[222:223] offset0:2 offset1:3
	ds_write2st64_b64 v211, v[224:225], v[226:227] offset0:4 offset1:5
	ds_write2st64_b64 v211, v[228:229], v[146:147] offset0:6 offset1:7
	v_pk_add_f32 v[146:147], v[234:235], v[230:231]
	ds_read2_b64 v[218:221], v212 offset1:8
	v_mul_f32_e32 v151, 0x45800000, v143
	v_mov_b32_dpp v195, v147 quad_perm:[2,3,0,1] row_mask:0xf bank_mask:0xf bound_ctrl:1
	v_mov_b32_dpp v194, v146 quad_perm:[2,3,0,1] row_mask:0xf bank_mask:0xf bound_ctrl:1
	v_pk_add_f32 v[146:147], v[146:147], v[194:195]
	v_mul_f32_e32 v153, 0x45800000, v149
	v_cndmask_b32_e32 v143, v143, v151, vcc
	v_mov_b32_dpp v195, v147 row_half_mirror row_mask:0xf bank_mask:0xf bound_ctrl:1
	v_mov_b32_dpp v194, v146 row_half_mirror row_mask:0xf bank_mask:0xf bound_ctrl:1
	v_pk_add_f32 v[146:147], v[146:147], v[194:195]
	v_cndmask_b32_e64 v149, v149, v153, s[0:1]
	v_mul_f32_e32 v32, v32, v143
	v_mov_b32_dpp v195, v147 row_mirror row_mask:0xf bank_mask:0xf bound_ctrl:1
	v_mov_b32_dpp v194, v146 row_mirror row_mask:0xf bank_mask:0xf bound_ctrl:1
	v_pk_add_f32 v[146:147], v[146:147], v[194:195]
	ds_bpermute_b32 v195, v135, v147
	ds_bpermute_b32 v194, v135, v146
	v_mul_f32_e32 v139, v141, v139
	v_mul_f32_e32 v33, v33, v149
	v_mul_f32_e32 v137, v141, v137
	v_mul_f32_e32 v141, v139, v32
	v_mul_f32_e32 v48, v48, v143
	v_mul_f32_e32 v143, v139, v33
	s_waitcnt lgkmcnt(2)
	v_mul_f32_dpp v33, v141, v219 row_ror:8 row_mask:0xf bank_mask:0xf bound_ctrl:1
	v_cndmask_b32_e64 v33, v33, -v33, s[2:3]
	s_waitcnt lgkmcnt(0)
	v_pk_add_f32 v[146:147], v[146:147], v[194:195]
	v_fmac_f32_e32 v33, v218, v141
	v_pk_fma_f32 v[146:147], v[146:147], s[62:63], v[192:193] op_sel_hi:[1,0,0]
	v_mul_f32_e32 v32, v137, v48
	v_cndmask_b32_e64 v48, v141, v33, s[4:5]
	v_mul_f32_e32 v141, 0x4b800000, v147
	v_cmp_gt_f32_e32 vcc, s46, v147
	v_mul_f32_e32 v33, v49, v149
	v_mul_f32_dpp v49, v143, v221 row_ror:8 row_mask:0xf bank_mask:0xf bound_ctrl:1
	v_cndmask_b32_e32 v141, v147, v141, vcc
	v_rsq_f32_e32 v141, v141
	v_cndmask_b32_e64 v49, v49, -v49, s[2:3]
	v_fmac_f32_e32 v49, v220, v143
	ds_read2_b64 v[218:221], v212 offset0:16 offset1:24
	v_cndmask_b32_e64 v49, v143, v49, s[4:5]
	v_mul_f32_e32 v143, 0x45800000, v141
	v_cndmask_b32_e32 v141, v141, v143, vcc
	v_mul_f32_e32 v34, v34, v141
	v_mul_f32_e32 v143, v139, v34
	v_mul_f32_e32 v34, v50, v141
	v_mul_f32_e32 v141, 0x4b800000, v146
	v_cmp_gt_f32_e32 vcc, s46, v146
	s_waitcnt lgkmcnt(0)
	v_mul_f32_dpp v50, v143, v219 row_ror:8 row_mask:0xf bank_mask:0xf bound_ctrl:1
	v_mov_b32_e32 v147, v52
	v_cndmask_b32_e32 v141, v146, v141, vcc
	v_mov_b32_e32 v146, v36
	v_mov_b32_e32 v194, v37
	v_mov_b32_e32 v195, v53
	v_cndmask_b32_e64 v50, v50, -v50, s[2:3]
	v_pk_mul_f32 v[146:147], v[146:147], v[146:147]
	v_pk_mul_f32 v[194:195], v[194:195], v[194:195]
	v_fmac_f32_e32 v50, v218, v143
	v_mov_b32_e32 v218, v194
	v_mov_b32_e32 v219, v146
	v_mov_b32_e32 v146, v195
	v_pk_add_f32 v[146:147], v[218:219], v[146:147]
	v_rsq_f32_e32 v141, v141
	v_cndmask_b32_e64 v50, v143, v50, s[4:5]
	v_mov_b32_dpp v195, v147 quad_perm:[1,0,3,2] row_mask:0xf bank_mask:0xf bound_ctrl:1
	v_mov_b32_dpp v194, v146 quad_perm:[1,0,3,2] row_mask:0xf bank_mask:0xf bound_ctrl:1
	v_pk_add_f32 v[146:147], v[146:147], v[194:195]
	v_mul_f32_e32 v143, 0x45800000, v141
	v_cndmask_b32_e32 v141, v141, v143, vcc
	v_mov_b32_dpp v195, v147 quad_perm:[2,3,0,1] row_mask:0xf bank_mask:0xf bound_ctrl:1
	v_mov_b32_dpp v194, v146 quad_perm:[2,3,0,1] row_mask:0xf bank_mask:0xf bound_ctrl:1
	v_pk_add_f32 v[146:147], v[146:147], v[194:195]
	v_mul_f32_e32 v35, v35, v141
	v_mul_f32_e32 v143, v139, v35
	v_mov_b32_dpp v195, v147 row_half_mirror row_mask:0xf bank_mask:0xf bound_ctrl:1
	v_mov_b32_dpp v194, v146 row_half_mirror row_mask:0xf bank_mask:0xf bound_ctrl:1
	v_pk_add_f32 v[146:147], v[146:147], v[194:195]
	v_mul_f32_e32 v35, v51, v141
	v_mul_f32_dpp v51, v143, v221 row_ror:8 row_mask:0xf bank_mask:0xf bound_ctrl:1
	v_mov_b32_dpp v195, v147 row_mirror row_mask:0xf bank_mask:0xf bound_ctrl:1
	v_mov_b32_dpp v194, v146 row_mirror row_mask:0xf bank_mask:0xf bound_ctrl:1
	v_pk_add_f32 v[146:147], v[146:147], v[194:195]
	ds_bpermute_b32 v195, v135, v147
	ds_bpermute_b32 v194, v135, v146
	v_cndmask_b32_e64 v51, v51, -v51, s[2:3]
	v_fmac_f32_e32 v51, v220, v143
	ds_read2_b64 v[218:221], v212 offset0:64 offset1:72
	v_cndmask_b32_e64 v51, v143, v51, s[4:5]
	s_waitcnt lgkmcnt(1)
	v_pk_add_f32 v[146:147], v[146:147], v[194:195]
	v_mov_b32_e32 v194, v39
	v_pk_fma_f32 v[146:147], v[146:147], s[62:63], v[192:193] op_sel_hi:[1,0,0]
	v_mov_b32_e32 v195, v55
	v_mul_f32_e32 v141, 0x4b800000, v147
	v_cmp_gt_f32_e32 vcc, s46, v147
	v_pk_mul_f32 v[194:195], v[194:195], v[194:195]
	v_add_u32_e32 v149, 0x800, v212
	v_cndmask_b32_e32 v141, v147, v141, vcc
	v_rsq_f32_e32 v141, v141
	v_mov_b32_e32 v147, v54
	v_mul_f32_e32 v33, v137, v33
	v_mul_f32_e32 v34, v137, v34
	v_mul_f32_e32 v143, 0x45800000, v141
	v_cndmask_b32_e32 v141, v141, v143, vcc
	v_mul_f32_e32 v36, v36, v141
	v_mul_f32_e32 v143, v139, v36
	v_mul_f32_e32 v36, v52, v141
	v_mul_f32_e32 v141, 0x4b800000, v146
	v_cmp_gt_f32_e32 vcc, s46, v146
	s_waitcnt lgkmcnt(0)
	v_mul_f32_dpp v52, v143, v219 row_ror:8 row_mask:0xf bank_mask:0xf bound_ctrl:1
	v_cndmask_b32_e64 v52, v52, -v52, s[2:3]
	v_cndmask_b32_e32 v141, v146, v141, vcc
	v_mov_b32_e32 v146, v38
	v_pk_mul_f32 v[146:147], v[146:147], v[146:147]
	v_fmac_f32_e32 v52, v218, v143
	v_mov_b32_e32 v218, v194
	v_mov_b32_e32 v219, v146
	v_mov_b32_e32 v146, v195
	v_pk_add_f32 v[146:147], v[218:219], v[146:147]
	v_rsq_f32_e32 v141, v141
	v_cndmask_b32_e64 v52, v143, v52, s[4:5]
	v_mov_b32_dpp v195, v147 quad_perm:[1,0,3,2] row_mask:0xf bank_mask:0xf bound_ctrl:1
	v_mov_b32_dpp v194, v146 quad_perm:[1,0,3,2] row_mask:0xf bank_mask:0xf bound_ctrl:1
	v_pk_add_f32 v[146:147], v[146:147], v[194:195]
	v_mul_f32_e32 v143, 0x45800000, v141
	v_cndmask_b32_e32 v141, v141, v143, vcc
	v_mov_b32_dpp v195, v147 quad_perm:[2,3,0,1] row_mask:0xf bank_mask:0xf bound_ctrl:1
	v_mov_b32_dpp v194, v146 quad_perm:[2,3,0,1] row_mask:0xf bank_mask:0xf bound_ctrl:1
	v_pk_add_f32 v[146:147], v[146:147], v[194:195]
	v_mul_f32_e32 v37, v37, v141
	v_mul_f32_e32 v143, v139, v37
	v_mov_b32_dpp v195, v147 row_half_mirror row_mask:0xf bank_mask:0xf bound_ctrl:1
	v_mov_b32_dpp v194, v146 row_half_mirror row_mask:0xf bank_mask:0xf bound_ctrl:1
	v_pk_add_f32 v[146:147], v[146:147], v[194:195]
	v_mul_f32_e32 v37, v53, v141
	v_mul_f32_dpp v53, v143, v221 row_ror:8 row_mask:0xf bank_mask:0xf bound_ctrl:1
	v_mov_b32_dpp v195, v147 row_mirror row_mask:0xf bank_mask:0xf bound_ctrl:1
	v_mov_b32_dpp v194, v146 row_mirror row_mask:0xf bank_mask:0xf bound_ctrl:1
	v_pk_add_f32 v[146:147], v[146:147], v[194:195]
	ds_bpermute_b32 v195, v135, v147
	ds_bpermute_b32 v194, v135, v146
	v_cndmask_b32_e64 v53, v53, -v53, s[2:3]
	v_fmac_f32_e32 v53, v220, v143
	ds_read2_b64 v[218:221], v212 offset0:80 offset1:88
	v_cndmask_b32_e64 v53, v143, v53, s[4:5]
	s_waitcnt lgkmcnt(1)
	v_pk_add_f32 v[146:147], v[146:147], v[194:195]
	v_mov_b32_e32 v194, v41
	v_pk_fma_f32 v[146:147], v[146:147], s[62:63], v[192:193] op_sel_hi:[1,0,0]
	v_mov_b32_e32 v195, v57
	v_mul_f32_e32 v141, 0x4b800000, v147
	v_cmp_gt_f32_e32 vcc, s46, v147
	v_pk_mul_f32 v[194:195], v[194:195], v[194:195]
	v_mul_f32_e32 v35, v137, v35
	v_cndmask_b32_e32 v141, v147, v141, vcc
	v_rsq_f32_e32 v141, v141
	v_mov_b32_e32 v147, v56
	v_mul_f32_e32 v36, v137, v36
	v_mul_f32_e32 v37, v137, v37
	v_mul_f32_e32 v143, 0x45800000, v141
	v_cndmask_b32_e32 v141, v141, v143, vcc
	v_mul_f32_e32 v38, v38, v141
	v_mul_f32_e32 v143, v139, v38
	v_mul_f32_e32 v38, v54, v141
	v_mul_f32_e32 v141, 0x4b800000, v146
	v_cmp_gt_f32_e32 vcc, s46, v146
	s_waitcnt lgkmcnt(0)
	v_mul_f32_dpp v54, v143, v219 row_ror:8 row_mask:0xf bank_mask:0xf bound_ctrl:1
	v_cndmask_b32_e64 v54, v54, -v54, s[2:3]
	v_cndmask_b32_e32 v141, v146, v141, vcc
	v_mov_b32_e32 v146, v40
	v_pk_mul_f32 v[146:147], v[146:147], v[146:147]
	v_fmac_f32_e32 v54, v218, v143
	v_mov_b32_e32 v218, v194
	v_mov_b32_e32 v219, v146
	v_mov_b32_e32 v146, v195
	v_pk_add_f32 v[146:147], v[218:219], v[146:147]
	v_rsq_f32_e32 v141, v141
	v_cndmask_b32_e64 v54, v143, v54, s[4:5]
	v_mov_b32_dpp v195, v147 quad_perm:[1,0,3,2] row_mask:0xf bank_mask:0xf bound_ctrl:1
	v_mov_b32_dpp v194, v146 quad_perm:[1,0,3,2] row_mask:0xf bank_mask:0xf bound_ctrl:1
	v_pk_add_f32 v[146:147], v[146:147], v[194:195]
	v_mul_f32_e32 v143, 0x45800000, v141
	v_cndmask_b32_e32 v141, v141, v143, vcc
	v_mov_b32_dpp v195, v147 quad_perm:[2,3,0,1] row_mask:0xf bank_mask:0xf bound_ctrl:1
	v_mov_b32_dpp v194, v146 quad_perm:[2,3,0,1] row_mask:0xf bank_mask:0xf bound_ctrl:1
	v_pk_add_f32 v[146:147], v[146:147], v[194:195]
	v_mul_f32_e32 v39, v39, v141
	v_mul_f32_e32 v143, v139, v39
	v_mov_b32_dpp v195, v147 row_half_mirror row_mask:0xf bank_mask:0xf bound_ctrl:1
	v_mov_b32_dpp v194, v146 row_half_mirror row_mask:0xf bank_mask:0xf bound_ctrl:1
	v_pk_add_f32 v[146:147], v[146:147], v[194:195]
	v_mul_f32_e32 v39, v55, v141
	v_mul_f32_dpp v55, v143, v221 row_ror:8 row_mask:0xf bank_mask:0xf bound_ctrl:1
	v_mov_b32_dpp v195, v147 row_mirror row_mask:0xf bank_mask:0xf bound_ctrl:1
	v_mov_b32_dpp v194, v146 row_mirror row_mask:0xf bank_mask:0xf bound_ctrl:1
	v_pk_add_f32 v[146:147], v[146:147], v[194:195]
	ds_bpermute_b32 v195, v135, v147
	ds_bpermute_b32 v194, v135, v146
	v_cndmask_b32_e64 v55, v55, -v55, s[2:3]
	v_fmac_f32_e32 v55, v220, v143
	ds_read2_b64 v[218:221], v212 offset0:128 offset1:136
	v_cndmask_b32_e64 v55, v143, v55, s[4:5]
	s_waitcnt lgkmcnt(1)
	v_pk_add_f32 v[146:147], v[146:147], v[194:195]
	v_mov_b32_e32 v194, v43
	v_pk_fma_f32 v[146:147], v[146:147], s[62:63], v[192:193] op_sel_hi:[1,0,0]
	v_mov_b32_e32 v195, v59
	v_mul_f32_e32 v141, 0x4b800000, v147
	v_cmp_gt_f32_e32 vcc, s46, v147
	v_pk_mul_f32 v[194:195], v[194:195], v[194:195]
	v_mul_f32_e32 v38, v137, v38
	v_cndmask_b32_e32 v141, v147, v141, vcc
	v_rsq_f32_e32 v141, v141
	v_mov_b32_e32 v147, v58
	v_mul_f32_e32 v39, v137, v39
	v_mul_f32_e32 v143, 0x45800000, v141
	v_cndmask_b32_e32 v141, v141, v143, vcc
	v_mul_f32_e32 v40, v40, v141
	v_mul_f32_e32 v143, v139, v40
	v_mul_f32_e32 v40, v56, v141
	v_mul_f32_e32 v141, 0x4b800000, v146
	v_cmp_gt_f32_e32 vcc, s46, v146
	s_waitcnt lgkmcnt(0)
	v_mul_f32_dpp v56, v143, v219 row_ror:8 row_mask:0xf bank_mask:0xf bound_ctrl:1
	v_cndmask_b32_e64 v56, v56, -v56, s[2:3]
	v_cndmask_b32_e32 v141, v146, v141, vcc
	v_mov_b32_e32 v146, v42
	v_pk_mul_f32 v[146:147], v[146:147], v[146:147]
	v_fmac_f32_e32 v56, v218, v143
	v_mov_b32_e32 v218, v194
	v_mov_b32_e32 v219, v146
	v_mov_b32_e32 v146, v195
	v_pk_add_f32 v[146:147], v[218:219], v[146:147]
	v_rsq_f32_e32 v141, v141
	v_cndmask_b32_e64 v56, v143, v56, s[4:5]
	v_mov_b32_dpp v195, v147 quad_perm:[1,0,3,2] row_mask:0xf bank_mask:0xf bound_ctrl:1
	v_mov_b32_dpp v194, v146 quad_perm:[1,0,3,2] row_mask:0xf bank_mask:0xf bound_ctrl:1
	v_pk_add_f32 v[146:147], v[146:147], v[194:195]
	v_mul_f32_e32 v143, 0x45800000, v141
	v_cndmask_b32_e32 v141, v141, v143, vcc
	v_mov_b32_dpp v195, v147 quad_perm:[2,3,0,1] row_mask:0xf bank_mask:0xf bound_ctrl:1
	v_mov_b32_dpp v194, v146 quad_perm:[2,3,0,1] row_mask:0xf bank_mask:0xf bound_ctrl:1
	v_pk_add_f32 v[146:147], v[146:147], v[194:195]
	v_mul_f32_e32 v41, v41, v141
	v_mul_f32_e32 v143, v139, v41
	v_mov_b32_dpp v195, v147 row_half_mirror row_mask:0xf bank_mask:0xf bound_ctrl:1
	v_mov_b32_dpp v194, v146 row_half_mirror row_mask:0xf bank_mask:0xf bound_ctrl:1
	v_pk_add_f32 v[146:147], v[146:147], v[194:195]
	v_mul_f32_e32 v41, v57, v141
	v_mul_f32_dpp v57, v143, v221 row_ror:8 row_mask:0xf bank_mask:0xf bound_ctrl:1
	v_mov_b32_dpp v195, v147 row_mirror row_mask:0xf bank_mask:0xf bound_ctrl:1
	v_mov_b32_dpp v194, v146 row_mirror row_mask:0xf bank_mask:0xf bound_ctrl:1
	v_pk_add_f32 v[146:147], v[146:147], v[194:195]
	ds_bpermute_b32 v195, v135, v147
	ds_bpermute_b32 v194, v135, v146
	v_cndmask_b32_e64 v57, v57, -v57, s[2:3]
	v_fmac_f32_e32 v57, v220, v143
	ds_read2_b64 v[218:221], v212 offset0:144 offset1:152
	v_cndmask_b32_e64 v57, v143, v57, s[4:5]
	s_waitcnt lgkmcnt(1)
	v_pk_add_f32 v[146:147], v[146:147], v[194:195]
	v_mov_b32_e32 v194, v45
	v_pk_fma_f32 v[146:147], v[146:147], s[62:63], v[192:193] op_sel_hi:[1,0,0]
	v_mov_b32_e32 v195, v61
	v_mul_f32_e32 v141, 0x4b800000, v147
	v_cmp_gt_f32_e32 vcc, s46, v147
	v_pk_mul_f32 v[194:195], v[194:195], v[194:195]
	v_mul_f32_e32 v40, v137, v40
	v_cndmask_b32_e32 v141, v147, v141, vcc
	v_rsq_f32_e32 v141, v141
	v_mov_b32_e32 v147, v60
	v_mul_f32_e32 v41, v137, v41
	v_mul_f32_e32 v143, 0x45800000, v141
	v_cndmask_b32_e32 v141, v141, v143, vcc
	v_mul_f32_e32 v42, v42, v141
	v_mul_f32_e32 v143, v139, v42
	v_mul_f32_e32 v42, v58, v141
	v_mul_f32_e32 v141, 0x4b800000, v146
	v_cmp_gt_f32_e32 vcc, s46, v146
	s_waitcnt lgkmcnt(0)
	v_mul_f32_dpp v58, v143, v219 row_ror:8 row_mask:0xf bank_mask:0xf bound_ctrl:1
	v_cndmask_b32_e64 v58, v58, -v58, s[2:3]
	v_cndmask_b32_e32 v141, v146, v141, vcc
	v_mov_b32_e32 v146, v44
	v_pk_mul_f32 v[146:147], v[146:147], v[146:147]
	v_fmac_f32_e32 v58, v218, v143
	v_mov_b32_e32 v218, v194
	v_mov_b32_e32 v219, v146
	v_mov_b32_e32 v146, v195
	v_pk_add_f32 v[146:147], v[218:219], v[146:147]
	v_rsq_f32_e32 v141, v141
	v_cndmask_b32_e64 v58, v143, v58, s[4:5]
	v_mov_b32_dpp v195, v147 quad_perm:[1,0,3,2] row_mask:0xf bank_mask:0xf bound_ctrl:1
	v_mov_b32_dpp v194, v146 quad_perm:[1,0,3,2] row_mask:0xf bank_mask:0xf bound_ctrl:1
	v_pk_add_f32 v[146:147], v[146:147], v[194:195]
	v_mul_f32_e32 v143, 0x45800000, v141
	v_cndmask_b32_e32 v141, v141, v143, vcc
	v_mov_b32_dpp v195, v147 quad_perm:[2,3,0,1] row_mask:0xf bank_mask:0xf bound_ctrl:1
	v_mov_b32_dpp v194, v146 quad_perm:[2,3,0,1] row_mask:0xf bank_mask:0xf bound_ctrl:1
	v_pk_add_f32 v[146:147], v[146:147], v[194:195]
	v_mul_f32_e32 v43, v43, v141
	v_mul_f32_e32 v143, v139, v43
	v_mov_b32_dpp v195, v147 row_half_mirror row_mask:0xf bank_mask:0xf bound_ctrl:1
	v_mov_b32_dpp v194, v146 row_half_mirror row_mask:0xf bank_mask:0xf bound_ctrl:1
	v_pk_add_f32 v[146:147], v[146:147], v[194:195]
	v_mul_f32_e32 v43, v59, v141
	v_mul_f32_dpp v59, v143, v221 row_ror:8 row_mask:0xf bank_mask:0xf bound_ctrl:1
	v_mov_b32_dpp v195, v147 row_mirror row_mask:0xf bank_mask:0xf bound_ctrl:1
	v_mov_b32_dpp v194, v146 row_mirror row_mask:0xf bank_mask:0xf bound_ctrl:1
	v_pk_add_f32 v[146:147], v[146:147], v[194:195]
	ds_bpermute_b32 v195, v135, v147
	ds_bpermute_b32 v194, v135, v146
	v_cndmask_b32_e64 v59, v59, -v59, s[2:3]
	v_fmac_f32_e32 v59, v220, v143
	ds_read2_b64 v[218:221], v212 offset0:192 offset1:200
	v_cndmask_b32_e64 v59, v143, v59, s[4:5]
	s_waitcnt lgkmcnt(1)
	v_pk_add_f32 v[146:147], v[146:147], v[194:195]
	v_mov_b32_e32 v194, v47
	v_pk_fma_f32 v[146:147], v[146:147], s[62:63], v[192:193] op_sel_hi:[1,0,0]
	v_mov_b32_e32 v195, v63
	v_mul_f32_e32 v141, 0x4b800000, v147
	v_cmp_gt_f32_e32 vcc, s46, v147
	v_pk_mul_f32 v[194:195], v[194:195], v[194:195]
	v_mul_f32_e32 v42, v137, v42
	v_cndmask_b32_e32 v141, v147, v141, vcc
	v_rsq_f32_e32 v141, v141
	v_mov_b32_e32 v147, v62
	v_mul_f32_e32 v43, v137, v43
	v_mul_f32_e32 v143, 0x45800000, v141
	v_cndmask_b32_e32 v141, v141, v143, vcc
	v_mul_f32_e32 v44, v44, v141
	v_mul_f32_e32 v143, v139, v44
	v_mul_f32_e32 v44, v60, v141
	v_mul_f32_e32 v141, 0x4b800000, v146
	v_cmp_gt_f32_e32 vcc, s46, v146
	s_waitcnt lgkmcnt(0)
	v_mul_f32_dpp v60, v143, v219 row_ror:8 row_mask:0xf bank_mask:0xf bound_ctrl:1
	v_cndmask_b32_e64 v60, v60, -v60, s[2:3]
	v_cndmask_b32_e32 v141, v146, v141, vcc
	v_mov_b32_e32 v146, v46
	v_pk_mul_f32 v[146:147], v[146:147], v[146:147]
	v_fmac_f32_e32 v60, v218, v143
	v_mov_b32_e32 v218, v194
	v_mov_b32_e32 v219, v146
	v_mov_b32_e32 v146, v195
	v_pk_add_f32 v[146:147], v[218:219], v[146:147]
	v_rsq_f32_e32 v141, v141
	v_cndmask_b32_e64 v60, v143, v60, s[4:5]
	v_mov_b32_dpp v195, v147 quad_perm:[1,0,3,2] row_mask:0xf bank_mask:0xf bound_ctrl:1
	v_mov_b32_dpp v194, v146 quad_perm:[1,0,3,2] row_mask:0xf bank_mask:0xf bound_ctrl:1
	v_pk_add_f32 v[146:147], v[146:147], v[194:195]
	v_mul_f32_e32 v143, 0x45800000, v141
	v_cndmask_b32_e32 v141, v141, v143, vcc
	v_mov_b32_dpp v195, v147 quad_perm:[2,3,0,1] row_mask:0xf bank_mask:0xf bound_ctrl:1
	v_mov_b32_dpp v194, v146 quad_perm:[2,3,0,1] row_mask:0xf bank_mask:0xf bound_ctrl:1
	v_pk_add_f32 v[146:147], v[146:147], v[194:195]
	v_mul_f32_e32 v45, v45, v141
	v_mul_f32_e32 v143, v139, v45
	v_mov_b32_dpp v195, v147 row_half_mirror row_mask:0xf bank_mask:0xf bound_ctrl:1
	v_mov_b32_dpp v194, v146 row_half_mirror row_mask:0xf bank_mask:0xf bound_ctrl:1
	v_pk_add_f32 v[146:147], v[146:147], v[194:195]
	v_mul_f32_e32 v45, v61, v141
	v_mul_f32_dpp v61, v143, v221 row_ror:8 row_mask:0xf bank_mask:0xf bound_ctrl:1
	v_mov_b32_dpp v195, v147 row_mirror row_mask:0xf bank_mask:0xf bound_ctrl:1
	v_mov_b32_dpp v194, v146 row_mirror row_mask:0xf bank_mask:0xf bound_ctrl:1
	v_pk_add_f32 v[146:147], v[146:147], v[194:195]
	ds_bpermute_b32 v195, v135, v147
	ds_bpermute_b32 v194, v135, v146
	v_cndmask_b32_e64 v61, v61, -v61, s[2:3]
	v_fmac_f32_e32 v61, v220, v143
	ds_read2_b64 v[218:221], v212 offset0:208 offset1:216
	v_cndmask_b32_e64 v61, v143, v61, s[4:5]
	s_waitcnt lgkmcnt(1)
	v_pk_add_f32 v[146:147], v[146:147], v[194:195]
	v_mov_b32_e32 v194, v1
	v_pk_fma_f32 v[146:147], v[146:147], s[62:63], v[192:193] op_sel_hi:[1,0,0]
	v_mov_b32_e32 v195, v17
	v_mul_f32_e32 v141, 0x4b800000, v147
	v_cmp_gt_f32_e32 vcc, s46, v147
	v_pk_mul_f32 v[194:195], v[194:195], v[194:195]
	v_mul_f32_e32 v44, v137, v44
	v_cndmask_b32_e32 v141, v147, v141, vcc
	v_rsq_f32_e32 v141, v141
	v_mov_b32_e32 v147, v16
	v_mul_f32_e32 v45, v137, v45
	v_mul_f32_e32 v143, 0x45800000, v141
	v_cndmask_b32_e32 v141, v141, v143, vcc
	v_mul_f32_e32 v46, v46, v141
	v_mul_f32_e32 v143, v139, v46
	v_mul_f32_e32 v46, v62, v141
	v_mul_f32_e32 v141, 0x4b800000, v146
	v_cmp_gt_f32_e32 vcc, s46, v146
	s_waitcnt lgkmcnt(0)
	v_mul_f32_dpp v62, v143, v219 row_ror:8 row_mask:0xf bank_mask:0xf bound_ctrl:1
	v_cndmask_b32_e64 v62, v62, -v62, s[2:3]
	v_cndmask_b32_e32 v141, v146, v141, vcc
	v_mov_b32_e32 v146, v0
	v_pk_mul_f32 v[146:147], v[146:147], v[146:147]
	v_fmac_f32_e32 v62, v218, v143
	v_mov_b32_e32 v218, v194
	v_mov_b32_e32 v219, v146
	v_mov_b32_e32 v146, v195
	v_pk_add_f32 v[146:147], v[218:219], v[146:147]
	v_rsq_f32_e32 v141, v141
	v_cndmask_b32_e64 v62, v143, v62, s[4:5]
	v_mov_b32_dpp v195, v147 quad_perm:[1,0,3,2] row_mask:0xf bank_mask:0xf bound_ctrl:1
	v_mov_b32_dpp v194, v146 quad_perm:[1,0,3,2] row_mask:0xf bank_mask:0xf bound_ctrl:1
	v_pk_add_f32 v[146:147], v[146:147], v[194:195]
	v_mul_f32_e32 v143, 0x45800000, v141
	v_cndmask_b32_e32 v141, v141, v143, vcc
	v_mov_b32_dpp v195, v147 quad_perm:[2,3,0,1] row_mask:0xf bank_mask:0xf bound_ctrl:1
	v_mov_b32_dpp v194, v146 quad_perm:[2,3,0,1] row_mask:0xf bank_mask:0xf bound_ctrl:1
	v_pk_add_f32 v[146:147], v[146:147], v[194:195]
	v_mul_f32_e32 v47, v47, v141
	v_mul_f32_e32 v143, v139, v47
	v_mov_b32_dpp v195, v147 row_half_mirror row_mask:0xf bank_mask:0xf bound_ctrl:1
	v_mov_b32_dpp v194, v146 row_half_mirror row_mask:0xf bank_mask:0xf bound_ctrl:1
	v_pk_add_f32 v[146:147], v[146:147], v[194:195]
	v_mul_f32_e32 v47, v63, v141
	v_mul_f32_dpp v63, v143, v221 row_ror:8 row_mask:0xf bank_mask:0xf bound_ctrl:1
	v_mov_b32_dpp v195, v147 row_mirror row_mask:0xf bank_mask:0xf bound_ctrl:1
	v_mov_b32_dpp v194, v146 row_mirror row_mask:0xf bank_mask:0xf bound_ctrl:1
	v_pk_add_f32 v[146:147], v[146:147], v[194:195]
	ds_bpermute_b32 v195, v135, v147
	ds_bpermute_b32 v194, v135, v146
	v_cndmask_b32_e64 v63, v63, -v63, s[2:3]
	v_fmac_f32_e32 v63, v220, v143
	ds_read2_b64 v[218:221], v149 offset1:8
	v_mul_f32_e32 v46, v137, v46
	s_waitcnt lgkmcnt(1)
	v_pk_add_f32 v[146:147], v[146:147], v[194:195]
	v_mul_f32_e32 v47, v137, v47
	v_pk_fma_f32 v[146:147], v[146:147], s[62:63], v[192:193] op_sel_hi:[1,0,0]
	s_nop 0
	v_mul_f32_e32 v141, 0x4b800000, v147
	v_cmp_gt_f32_e32 vcc, s46, v147
	s_nop 1
	v_cndmask_b32_e32 v141, v147, v141, vcc
	v_rsq_f32_e32 v147, v141
	v_cndmask_b32_e64 v141, v143, v63, s[4:5]
	v_mul_f32_e32 v143, 0x4b800000, v146
	v_mul_f32_e32 v63, 0x45800000, v147
	v_cndmask_b32_e32 v63, v147, v63, vcc
	v_cmp_gt_f32_e32 vcc, s46, v146
	v_mul_f32_e32 v0, v0, v63
	v_mul_f32_e32 v0, v139, v0
	v_cndmask_b32_e32 v143, v146, v143, vcc
	v_rsq_f32_e32 v143, v143
	v_mul_f32_e32 v16, v16, v63
	s_waitcnt lgkmcnt(0)
	v_mul_f32_dpp v63, v0, v219 row_ror:8 row_mask:0xf bank_mask:0xf bound_ctrl:1
	v_cndmask_b32_e64 v63, v63, -v63, s[2:3]
	v_fmac_f32_e32 v63, v218, v0
	v_cndmask_b32_e64 v63, v0, v63, s[4:5]
	v_mul_f32_e32 v0, 0x45800000, v143
	v_cndmask_b32_e32 v143, v143, v0, vcc
	v_mul_f32_e32 v0, v1, v143
	v_mul_f32_e32 v151, v139, v0
	v_mov_b32_e32 v0, v2
	v_mov_b32_e32 v1, v18
	v_mov_b32_e32 v146, v3
	v_mov_b32_e32 v147, v19
	v_pk_mul_f32 v[0:1], v[0:1], v[0:1]
	v_pk_mul_f32 v[146:147], v[146:147], v[146:147]
	v_mov_b32_e32 v195, v0
	v_mov_b32_e32 v194, v146
	v_mov_b32_e32 v0, v147
	v_pk_add_f32 v[0:1], v[194:195], v[0:1]
	v_mul_f32_e32 v17, v17, v143
	v_mul_f32_dpp v143, v151, v221 row_ror:8 row_mask:0xf bank_mask:0xf bound_ctrl:1
	v_mov_b32_dpp v147, v1 quad_perm:[1,0,3,2] row_mask:0xf bank_mask:0xf bound_ctrl:1
	v_mov_b32_dpp v146, v0 quad_perm:[1,0,3,2] row_mask:0xf bank_mask:0xf bound_ctrl:1
	v_pk_add_f32 v[0:1], v[0:1], v[146:147]
	v_cndmask_b32_e64 v143, v143, -v143, s[2:3]
	v_fmac_f32_e32 v143, v220, v151
	v_mov_b32_dpp v147, v1 quad_perm:[2,3,0,1] row_mask:0xf bank_mask:0xf bound_ctrl:1
	v_mov_b32_dpp v146, v0 quad_perm:[2,3,0,1] row_mask:0xf bank_mask:0xf bound_ctrl:1
	v_pk_add_f32 v[0:1], v[0:1], v[146:147]
	ds_read2_b64 v[218:221], v149 offset0:16 offset1:24
	v_cndmask_b32_e64 v143, v151, v143, s[4:5]
	v_mov_b32_dpp v147, v1 row_half_mirror row_mask:0xf bank_mask:0xf bound_ctrl:1
	v_mov_b32_dpp v146, v0 row_half_mirror row_mask:0xf bank_mask:0xf bound_ctrl:1
	v_pk_add_f32 v[0:1], v[0:1], v[146:147]
	v_mul_f32_e32 v16, v137, v16
	v_mul_f32_e32 v17, v137, v17
	v_mov_b32_dpp v147, v1 row_mirror row_mask:0xf bank_mask:0xf bound_ctrl:1
	v_mov_b32_dpp v146, v0 row_mirror row_mask:0xf bank_mask:0xf bound_ctrl:1
	v_pk_add_f32 v[0:1], v[0:1], v[146:147]
	ds_bpermute_b32 v147, v135, v1
	ds_bpermute_b32 v146, v135, v0
	s_waitcnt lgkmcnt(0)
	v_pk_add_f32 v[0:1], v[0:1], v[146:147]
	s_nop 0
	v_pk_fma_f32 v[0:1], v[0:1], s[62:63], v[192:193] op_sel_hi:[1,0,0]
	v_mov_b32_e32 v147, v21
	v_mul_f32_e32 v146, 0x4b800000, v1
	v_cmp_gt_f32_e32 vcc, s46, v1
	s_nop 1
	v_cndmask_b32_e32 v1, v1, v146, vcc
	v_rsq_f32_e32 v1, v1
	s_nop 0
	v_mul_f32_e32 v146, 0x45800000, v1
	v_cndmask_b32_e32 v1, v1, v146, vcc
	v_mul_f32_e32 v2, v2, v1
	v_mul_f32_e32 v1, v18, v1
	v_mul_f32_e32 v18, 0x4b800000, v0
	v_cmp_gt_f32_e32 vcc, s46, v0
	v_mul_f32_e32 v146, v139, v2
	v_mul_f32_e32 v2, v137, v1
	v_cndmask_b32_e32 v0, v0, v18, vcc
	v_rsq_f32_e32 v0, v0
	v_mul_f32_dpp v1, v146, v219 row_ror:8 row_mask:0xf bank_mask:0xf bound_ctrl:1
	v_cndmask_b32_e64 v1, v1, -v1, s[2:3]
	v_fmac_f32_e32 v1, v218, v146
	v_cndmask_b32_e64 v18, v146, v1, s[4:5]
	v_mul_f32_e32 v1, 0x45800000, v0
	v_cndmask_b32_e32 v151, v0, v1, vcc
	v_mul_f32_e32 v0, v3, v151
	v_mul_f32_e32 v153, v139, v0
	v_mov_b32_e32 v0, v4
	v_mov_b32_e32 v1, v20
	v_mov_b32_e32 v146, v5
	v_pk_mul_f32 v[0:1], v[0:1], v[0:1]
	v_pk_mul_f32 v[146:147], v[146:147], v[146:147]
	v_mov_b32_e32 v195, v0
	v_mov_b32_e32 v194, v146
	v_mov_b32_e32 v0, v147
	v_pk_add_f32 v[0:1], v[194:195], v[0:1]
	v_mul_f32_e32 v3, v19, v151
	v_mul_f32_dpp v19, v153, v221 row_ror:8 row_mask:0xf bank_mask:0xf bound_ctrl:1
	v_mov_b32_dpp v147, v1 quad_perm:[1,0,3,2] row_mask:0xf bank_mask:0xf bound_ctrl:1
	v_mov_b32_dpp v146, v0 quad_perm:[1,0,3,2] row_mask:0xf bank_mask:0xf bound_ctrl:1
	v_pk_add_f32 v[0:1], v[0:1], v[146:147]
	v_cndmask_b32_e64 v19, v19, -v19, s[2:3]
	v_fmac_f32_e32 v19, v220, v153
	v_mov_b32_dpp v147, v1 quad_perm:[2,3,0,1] row_mask:0xf bank_mask:0xf bound_ctrl:1
	v_mov_b32_dpp v146, v0 quad_perm:[2,3,0,1] row_mask:0xf bank_mask:0xf bound_ctrl:1
	v_pk_add_f32 v[0:1], v[0:1], v[146:147]
	ds_read2_b64 v[218:221], v149 offset0:64 offset1:72
	v_cndmask_b32_e64 v19, v153, v19, s[4:5]
	v_mov_b32_dpp v147, v1 row_half_mirror row_mask:0xf bank_mask:0xf bound_ctrl:1
	v_mov_b32_dpp v146, v0 row_half_mirror row_mask:0xf bank_mask:0xf bound_ctrl:1
	v_pk_add_f32 v[0:1], v[0:1], v[146:147]
	v_mul_f32_e32 v3, v137, v3
	s_nop 0
	v_mov_b32_dpp v147, v1 row_mirror row_mask:0xf bank_mask:0xf bound_ctrl:1
	v_mov_b32_dpp v146, v0 row_mirror row_mask:0xf bank_mask:0xf bound_ctrl:1
	v_pk_add_f32 v[0:1], v[0:1], v[146:147]
	ds_bpermute_b32 v147, v135, v1
	ds_bpermute_b32 v146, v135, v0
	s_waitcnt lgkmcnt(0)
	v_pk_add_f32 v[0:1], v[0:1], v[146:147]
	s_nop 0
	v_pk_fma_f32 v[0:1], v[0:1], s[62:63], v[192:193] op_sel_hi:[1,0,0]
	v_mov_b32_e32 v147, v23
	v_mul_f32_e32 v146, 0x4b800000, v1
	v_cmp_gt_f32_e32 vcc, s46, v1
	s_nop 1
	v_cndmask_b32_e32 v1, v1, v146, vcc
	v_rsq_f32_e32 v1, v1
	s_nop 0
	v_mul_f32_e32 v146, 0x45800000, v1
	v_cndmask_b32_e32 v1, v1, v146, vcc
	v_mul_f32_e32 v4, v4, v1
	v_mul_f32_e32 v1, v20, v1
	v_mul_f32_e32 v20, 0x4b800000, v0
	v_cmp_gt_f32_e32 vcc, s46, v0
	v_mul_f32_e32 v146, v139, v4
	v_mul_f32_e32 v4, v137, v1
	v_cndmask_b32_e32 v0, v0, v20, vcc
	v_rsq_f32_e32 v0, v0
	v_mul_f32_dpp v1, v146, v219 row_ror:8 row_mask:0xf bank_mask:0xf bound_ctrl:1
	v_cndmask_b32_e64 v1, v1, -v1, s[2:3]
	v_fmac_f32_e32 v1, v218, v146
	v_cndmask_b32_e64 v20, v146, v1, s[4:5]
	v_mul_f32_e32 v1, 0x45800000, v0
	v_cndmask_b32_e32 v151, v0, v1, vcc
	v_mul_f32_e32 v0, v5, v151
	v_mul_f32_e32 v153, v139, v0
	v_mov_b32_e32 v0, v6
	v_mov_b32_e32 v1, v22
	v_mov_b32_e32 v146, v7
	v_pk_mul_f32 v[0:1], v[0:1], v[0:1]
	v_pk_mul_f32 v[146:147], v[146:147], v[146:147]
	v_mov_b32_e32 v195, v0
	v_mov_b32_e32 v194, v146
	v_mov_b32_e32 v0, v147
	v_pk_add_f32 v[0:1], v[194:195], v[0:1]
	v_mul_f32_e32 v5, v21, v151
	v_mul_f32_dpp v21, v153, v221 row_ror:8 row_mask:0xf bank_mask:0xf bound_ctrl:1
	v_mov_b32_dpp v147, v1 quad_perm:[1,0,3,2] row_mask:0xf bank_mask:0xf bound_ctrl:1
	v_mov_b32_dpp v146, v0 quad_perm:[1,0,3,2] row_mask:0xf bank_mask:0xf bound_ctrl:1
	v_pk_add_f32 v[0:1], v[0:1], v[146:147]
	v_cndmask_b32_e64 v21, v21, -v21, s[2:3]
	v_fmac_f32_e32 v21, v220, v153
	v_mov_b32_dpp v147, v1 quad_perm:[2,3,0,1] row_mask:0xf bank_mask:0xf bound_ctrl:1
	v_mov_b32_dpp v146, v0 quad_perm:[2,3,0,1] row_mask:0xf bank_mask:0xf bound_ctrl:1
	v_pk_add_f32 v[0:1], v[0:1], v[146:147]
	ds_read2_b64 v[218:221], v149 offset0:80 offset1:88
	v_cndmask_b32_e64 v21, v153, v21, s[4:5]
	v_mov_b32_dpp v147, v1 row_half_mirror row_mask:0xf bank_mask:0xf bound_ctrl:1
	v_mov_b32_dpp v146, v0 row_half_mirror row_mask:0xf bank_mask:0xf bound_ctrl:1
	v_pk_add_f32 v[0:1], v[0:1], v[146:147]
	v_mul_f32_e32 v5, v137, v5
	s_nop 0
	v_mov_b32_dpp v147, v1 row_mirror row_mask:0xf bank_mask:0xf bound_ctrl:1
	v_mov_b32_dpp v146, v0 row_mirror row_mask:0xf bank_mask:0xf bound_ctrl:1
	v_pk_add_f32 v[0:1], v[0:1], v[146:147]
	ds_bpermute_b32 v147, v135, v1
	ds_bpermute_b32 v146, v135, v0
	s_waitcnt lgkmcnt(0)
	v_pk_add_f32 v[0:1], v[0:1], v[146:147]
	s_nop 0
	v_pk_fma_f32 v[0:1], v[0:1], s[62:63], v[192:193] op_sel_hi:[1,0,0]
	v_mov_b32_e32 v147, v25
	v_mul_f32_e32 v146, 0x4b800000, v1
	v_cmp_gt_f32_e32 vcc, s46, v1
	s_nop 1
	v_cndmask_b32_e32 v1, v1, v146, vcc
	v_rsq_f32_e32 v1, v1
	s_nop 0
	v_mul_f32_e32 v146, 0x45800000, v1
	v_cndmask_b32_e32 v1, v1, v146, vcc
	v_mul_f32_e32 v6, v6, v1
	v_mul_f32_e32 v1, v22, v1
	v_mul_f32_e32 v22, 0x4b800000, v0
	v_cmp_gt_f32_e32 vcc, s46, v0
	v_mul_f32_e32 v146, v139, v6
	v_mul_f32_e32 v6, v137, v1
	v_cndmask_b32_e32 v0, v0, v22, vcc
	v_rsq_f32_e32 v0, v0
	v_mul_f32_dpp v1, v146, v219 row_ror:8 row_mask:0xf bank_mask:0xf bound_ctrl:1
	v_cndmask_b32_e64 v1, v1, -v1, s[2:3]
	v_fmac_f32_e32 v1, v218, v146
	v_cndmask_b32_e64 v22, v146, v1, s[4:5]
	v_mul_f32_e32 v1, 0x45800000, v0
	v_cndmask_b32_e32 v151, v0, v1, vcc
	v_mul_f32_e32 v0, v7, v151
	v_mul_f32_e32 v153, v139, v0
	v_mov_b32_e32 v0, v8
	v_mov_b32_e32 v1, v24
	v_mov_b32_e32 v146, v9
	v_pk_mul_f32 v[0:1], v[0:1], v[0:1]
	v_pk_mul_f32 v[146:147], v[146:147], v[146:147]
	v_mov_b32_e32 v195, v0
	v_mov_b32_e32 v194, v146
	v_mov_b32_e32 v0, v147
	v_pk_add_f32 v[0:1], v[194:195], v[0:1]
	v_mul_f32_e32 v7, v23, v151
	v_mul_f32_dpp v23, v153, v221 row_ror:8 row_mask:0xf bank_mask:0xf bound_ctrl:1
	v_mov_b32_dpp v147, v1 quad_perm:[1,0,3,2] row_mask:0xf bank_mask:0xf bound_ctrl:1
	v_mov_b32_dpp v146, v0 quad_perm:[1,0,3,2] row_mask:0xf bank_mask:0xf bound_ctrl:1
	v_pk_add_f32 v[0:1], v[0:1], v[146:147]
	v_cndmask_b32_e64 v23, v23, -v23, s[2:3]
	v_fmac_f32_e32 v23, v220, v153
	v_mov_b32_dpp v147, v1 quad_perm:[2,3,0,1] row_mask:0xf bank_mask:0xf bound_ctrl:1
	v_mov_b32_dpp v146, v0 quad_perm:[2,3,0,1] row_mask:0xf bank_mask:0xf bound_ctrl:1
	v_pk_add_f32 v[0:1], v[0:1], v[146:147]
	ds_read2_b64 v[218:221], v149 offset0:128 offset1:136
	v_cndmask_b32_e64 v23, v153, v23, s[4:5]
	v_mov_b32_dpp v147, v1 row_half_mirror row_mask:0xf bank_mask:0xf bound_ctrl:1
	v_mov_b32_dpp v146, v0 row_half_mirror row_mask:0xf bank_mask:0xf bound_ctrl:1
	v_pk_add_f32 v[0:1], v[0:1], v[146:147]
	v_mul_f32_e32 v7, v137, v7
	s_nop 0
	v_mov_b32_dpp v147, v1 row_mirror row_mask:0xf bank_mask:0xf bound_ctrl:1
	v_mov_b32_dpp v146, v0 row_mirror row_mask:0xf bank_mask:0xf bound_ctrl:1
	v_pk_add_f32 v[0:1], v[0:1], v[146:147]
	ds_bpermute_b32 v147, v135, v1
	ds_bpermute_b32 v146, v135, v0
	s_waitcnt lgkmcnt(0)
	v_pk_add_f32 v[0:1], v[0:1], v[146:147]
	s_nop 0
	v_pk_fma_f32 v[0:1], v[0:1], s[62:63], v[192:193] op_sel_hi:[1,0,0]
	v_mov_b32_e32 v147, v27
	v_mul_f32_e32 v146, 0x4b800000, v1
	v_cmp_gt_f32_e32 vcc, s46, v1
	s_nop 1
	v_cndmask_b32_e32 v1, v1, v146, vcc
	v_rsq_f32_e32 v1, v1
	s_nop 0
	v_mul_f32_e32 v146, 0x45800000, v1
	v_cndmask_b32_e32 v1, v1, v146, vcc
	v_mul_f32_e32 v8, v8, v1
	v_mul_f32_e32 v1, v24, v1
	v_mul_f32_e32 v24, 0x4b800000, v0
	v_cmp_gt_f32_e32 vcc, s46, v0
	v_mul_f32_e32 v146, v139, v8
	v_mul_f32_e32 v8, v137, v1
	v_cndmask_b32_e32 v0, v0, v24, vcc
	v_rsq_f32_e32 v0, v0
	v_mul_f32_dpp v1, v146, v219 row_ror:8 row_mask:0xf bank_mask:0xf bound_ctrl:1
	v_cndmask_b32_e64 v1, v1, -v1, s[2:3]
	v_fmac_f32_e32 v1, v218, v146
	v_cndmask_b32_e64 v24, v146, v1, s[4:5]
	v_mul_f32_e32 v1, 0x45800000, v0
	v_cndmask_b32_e32 v151, v0, v1, vcc
	v_mul_f32_e32 v0, v9, v151
	v_mul_f32_e32 v153, v139, v0
	v_mov_b32_e32 v0, v10
	v_mov_b32_e32 v1, v26
	v_mov_b32_e32 v146, v11
	v_pk_mul_f32 v[0:1], v[0:1], v[0:1]
	v_pk_mul_f32 v[146:147], v[146:147], v[146:147]
	v_mov_b32_e32 v195, v0
	v_mov_b32_e32 v194, v146
	v_mov_b32_e32 v0, v147
	v_pk_add_f32 v[0:1], v[194:195], v[0:1]
	v_mul_f32_e32 v9, v25, v151
	v_mul_f32_dpp v25, v153, v221 row_ror:8 row_mask:0xf bank_mask:0xf bound_ctrl:1
	v_mov_b32_dpp v147, v1 quad_perm:[1,0,3,2] row_mask:0xf bank_mask:0xf bound_ctrl:1
	v_mov_b32_dpp v146, v0 quad_perm:[1,0,3,2] row_mask:0xf bank_mask:0xf bound_ctrl:1
	v_pk_add_f32 v[0:1], v[0:1], v[146:147]
	v_cndmask_b32_e64 v25, v25, -v25, s[2:3]
	v_fmac_f32_e32 v25, v220, v153
	v_mov_b32_dpp v147, v1 quad_perm:[2,3,0,1] row_mask:0xf bank_mask:0xf bound_ctrl:1
	v_mov_b32_dpp v146, v0 quad_perm:[2,3,0,1] row_mask:0xf bank_mask:0xf bound_ctrl:1
	v_pk_add_f32 v[0:1], v[0:1], v[146:147]
	ds_read2_b64 v[218:221], v149 offset0:144 offset1:152
	v_cndmask_b32_e64 v25, v153, v25, s[4:5]
	v_mov_b32_dpp v147, v1 row_half_mirror row_mask:0xf bank_mask:0xf bound_ctrl:1
	v_mov_b32_dpp v146, v0 row_half_mirror row_mask:0xf bank_mask:0xf bound_ctrl:1
	v_pk_add_f32 v[0:1], v[0:1], v[146:147]
	v_mul_f32_e32 v9, v137, v9
	s_nop 0
	v_mov_b32_dpp v147, v1 row_mirror row_mask:0xf bank_mask:0xf bound_ctrl:1
	v_mov_b32_dpp v146, v0 row_mirror row_mask:0xf bank_mask:0xf bound_ctrl:1
	v_pk_add_f32 v[0:1], v[0:1], v[146:147]
	ds_bpermute_b32 v147, v135, v1
	ds_bpermute_b32 v146, v135, v0
	s_waitcnt lgkmcnt(0)
	v_pk_add_f32 v[0:1], v[0:1], v[146:147]
	s_nop 0
	v_pk_fma_f32 v[0:1], v[0:1], s[62:63], v[192:193] op_sel_hi:[1,0,0]
	v_mov_b32_e32 v147, v29
	v_mul_f32_e32 v146, 0x4b800000, v1
	v_cmp_gt_f32_e32 vcc, s46, v1
	s_nop 1
	v_cndmask_b32_e32 v1, v1, v146, vcc
	v_rsq_f32_e32 v1, v1
	s_nop 0
	v_mul_f32_e32 v146, 0x45800000, v1
	v_cndmask_b32_e32 v1, v1, v146, vcc
	v_mul_f32_e32 v10, v10, v1
	v_mul_f32_e32 v1, v26, v1
	v_mul_f32_e32 v26, 0x4b800000, v0
	v_cmp_gt_f32_e32 vcc, s46, v0
	v_mul_f32_e32 v146, v139, v10
	v_mul_f32_e32 v10, v137, v1
	v_cndmask_b32_e32 v0, v0, v26, vcc
	v_rsq_f32_e32 v0, v0
	v_mul_f32_dpp v1, v146, v219 row_ror:8 row_mask:0xf bank_mask:0xf bound_ctrl:1
	v_cndmask_b32_e64 v1, v1, -v1, s[2:3]
	v_fmac_f32_e32 v1, v218, v146
	v_cndmask_b32_e64 v26, v146, v1, s[4:5]
	v_mul_f32_e32 v1, 0x45800000, v0
	v_cndmask_b32_e32 v151, v0, v1, vcc
	v_mul_f32_e32 v0, v11, v151
	v_mul_f32_e32 v153, v139, v0
	v_mov_b32_e32 v0, v12
	v_mov_b32_e32 v1, v28
	v_mov_b32_e32 v146, v13
	v_pk_mul_f32 v[0:1], v[0:1], v[0:1]
	v_pk_mul_f32 v[146:147], v[146:147], v[146:147]
	v_mov_b32_e32 v195, v0
	v_mov_b32_e32 v194, v146
	v_mov_b32_e32 v0, v147
	v_pk_add_f32 v[0:1], v[194:195], v[0:1]
	v_mul_f32_e32 v11, v27, v151
	v_mul_f32_dpp v27, v153, v221 row_ror:8 row_mask:0xf bank_mask:0xf bound_ctrl:1
	v_mov_b32_dpp v147, v1 quad_perm:[1,0,3,2] row_mask:0xf bank_mask:0xf bound_ctrl:1
	v_mov_b32_dpp v146, v0 quad_perm:[1,0,3,2] row_mask:0xf bank_mask:0xf bound_ctrl:1
	v_pk_add_f32 v[0:1], v[0:1], v[146:147]
	v_cndmask_b32_e64 v27, v27, -v27, s[2:3]
	v_fmac_f32_e32 v27, v220, v153
	v_mov_b32_dpp v147, v1 quad_perm:[2,3,0,1] row_mask:0xf bank_mask:0xf bound_ctrl:1
	v_mov_b32_dpp v146, v0 quad_perm:[2,3,0,1] row_mask:0xf bank_mask:0xf bound_ctrl:1
	v_pk_add_f32 v[0:1], v[0:1], v[146:147]
	ds_read2_b64 v[218:221], v149 offset0:192 offset1:200
	v_cndmask_b32_e64 v27, v153, v27, s[4:5]
	v_mov_b32_dpp v147, v1 row_half_mirror row_mask:0xf bank_mask:0xf bound_ctrl:1
	v_mov_b32_dpp v146, v0 row_half_mirror row_mask:0xf bank_mask:0xf bound_ctrl:1
	v_pk_add_f32 v[0:1], v[0:1], v[146:147]
	v_mul_f32_e32 v11, v137, v11
	s_nop 0
	v_mov_b32_dpp v147, v1 row_mirror row_mask:0xf bank_mask:0xf bound_ctrl:1
	v_mov_b32_dpp v146, v0 row_mirror row_mask:0xf bank_mask:0xf bound_ctrl:1
	v_pk_add_f32 v[0:1], v[0:1], v[146:147]
	ds_bpermute_b32 v147, v135, v1
	ds_bpermute_b32 v146, v135, v0
	s_waitcnt lgkmcnt(0)
	v_pk_add_f32 v[0:1], v[0:1], v[146:147]
	s_nop 0
	v_pk_fma_f32 v[0:1], v[0:1], s[62:63], v[192:193] op_sel_hi:[1,0,0]
	v_mov_b32_e32 v147, v31
	v_mul_f32_e32 v146, 0x4b800000, v1
	v_cmp_gt_f32_e32 vcc, s46, v1
	s_nop 1
	v_cndmask_b32_e32 v1, v1, v146, vcc
	v_rsq_f32_e32 v1, v1
	s_nop 0
	v_mul_f32_e32 v146, 0x45800000, v1
	v_cndmask_b32_e32 v1, v1, v146, vcc
	v_mul_f32_e32 v12, v12, v1
	v_mul_f32_e32 v1, v28, v1
	v_mul_f32_e32 v28, 0x4b800000, v0
	v_cmp_gt_f32_e32 vcc, s46, v0
	v_mul_f32_e32 v146, v139, v12
	v_mul_f32_e32 v12, v137, v1
	v_cndmask_b32_e32 v0, v0, v28, vcc
	v_rsq_f32_e32 v0, v0
	v_mul_f32_dpp v1, v146, v219 row_ror:8 row_mask:0xf bank_mask:0xf bound_ctrl:1
	v_cndmask_b32_e64 v1, v1, -v1, s[2:3]
	v_fmac_f32_e32 v1, v218, v146
	v_cndmask_b32_e64 v28, v146, v1, s[4:5]
	v_mul_f32_e32 v1, 0x45800000, v0
	v_cndmask_b32_e32 v151, v0, v1, vcc
	v_mul_f32_e32 v0, v13, v151
	v_mul_f32_e32 v153, v139, v0
	v_mov_b32_e32 v0, v14
	v_mov_b32_e32 v1, v30
	v_mov_b32_e32 v146, v15
	v_pk_mul_f32 v[0:1], v[0:1], v[0:1]
	v_pk_mul_f32 v[146:147], v[146:147], v[146:147]
	v_mov_b32_e32 v195, v0
	v_mov_b32_e32 v194, v146
	v_mov_b32_e32 v0, v147
	v_pk_add_f32 v[0:1], v[194:195], v[0:1]
	v_mul_f32_e32 v13, v29, v151
	v_mul_f32_dpp v29, v153, v221 row_ror:8 row_mask:0xf bank_mask:0xf bound_ctrl:1
	v_mov_b32_dpp v147, v1 quad_perm:[1,0,3,2] row_mask:0xf bank_mask:0xf bound_ctrl:1
	v_mov_b32_dpp v146, v0 quad_perm:[1,0,3,2] row_mask:0xf bank_mask:0xf bound_ctrl:1
	v_pk_add_f32 v[0:1], v[0:1], v[146:147]
	v_cndmask_b32_e64 v29, v29, -v29, s[2:3]
	v_fmac_f32_e32 v29, v220, v153
	v_mov_b32_dpp v147, v1 quad_perm:[2,3,0,1] row_mask:0xf bank_mask:0xf bound_ctrl:1
	v_mov_b32_dpp v146, v0 quad_perm:[2,3,0,1] row_mask:0xf bank_mask:0xf bound_ctrl:1
	v_pk_add_f32 v[0:1], v[0:1], v[146:147]
	v_mul_f32_e32 v13, v137, v13
	v_cndmask_b32_e64 v29, v153, v29, s[4:5]
	v_mov_b32_dpp v147, v1 row_half_mirror row_mask:0xf bank_mask:0xf bound_ctrl:1
	v_mov_b32_dpp v146, v0 row_half_mirror row_mask:0xf bank_mask:0xf bound_ctrl:1
	v_pk_add_f32 v[0:1], v[0:1], v[146:147]
	s_nop 1
	v_mov_b32_dpp v147, v1 row_mirror row_mask:0xf bank_mask:0xf bound_ctrl:1
	v_mov_b32_dpp v146, v0 row_mirror row_mask:0xf bank_mask:0xf bound_ctrl:1
	v_pk_add_f32 v[0:1], v[0:1], v[146:147]
	ds_bpermute_b32 v147, v135, v1
	ds_bpermute_b32 v146, v135, v0
	s_waitcnt lgkmcnt(0)
	v_pk_add_f32 v[0:1], v[0:1], v[146:147]
	s_nop 0
	v_pk_fma_f32 v[0:1], v[0:1], s[62:63], v[192:193] op_sel_hi:[1,0,0]
	ds_read2_b64 v[192:195], v149 offset0:208 offset1:216
	v_mul_f32_e32 v135, 0x4b800000, v1
	v_cmp_gt_f32_e32 vcc, s46, v1
	s_nop 1
	v_cndmask_b32_e32 v1, v1, v135, vcc
	v_rsq_f32_e32 v1, v1
	s_nop 0
	v_mul_f32_e32 v135, 0x45800000, v1
	v_cndmask_b32_e32 v1, v1, v135, vcc
	v_mul_f32_e32 v14, v14, v1
	v_mul_f32_e32 v1, v30, v1
	v_mul_f32_e32 v30, 0x4b800000, v0
	v_cmp_gt_f32_e32 vcc, s46, v0
	v_mul_f32_e32 v135, v139, v14
	v_mul_f32_e32 v14, v137, v1
	v_cndmask_b32_e32 v0, v0, v30, vcc
	v_rsq_f32_e32 v0, v0
	s_waitcnt lgkmcnt(0)
	v_mul_f32_dpp v1, v135, v193 row_ror:8 row_mask:0xf bank_mask:0xf bound_ctrl:1
	v_cndmask_b32_e64 v1, v1, -v1, s[2:3]
	v_fmac_f32_e32 v1, v192, v135
	v_cndmask_b32_e64 v30, v135, v1, s[4:5]
	v_mul_f32_e32 v1, 0x45800000, v0
	v_cndmask_b32_e32 v0, v0, v1, vcc
	v_mul_f32_e32 v1, v15, v0
	v_mul_f32_e32 v1, v139, v1
	v_mul_f32_e32 v0, v31, v0
	v_mul_f32_e32 v15, v137, v0
	s_andn2_b64 vcc, exec, s[70:71]
	v_mul_f32_dpp v0, v1, v195 row_ror:8 row_mask:0xf bank_mask:0xf bound_ctrl:1
	v_cndmask_b32_e64 v0, v0, -v0, s[2:3]
	v_fmac_f32_e32 v0, v194, v1
	v_cndmask_b32_e64 v31, v1, v0, s[4:5]
	s_cbranch_vccnz .LBB0_1004
	v_add_f32_e32 v137, 0, v48
	v_add_f32_e32 v137, v137, v49
	v_add_f32_e32 v137, v137, v50
	v_add_f32_e32 v137, v137, v51
	v_add_f32_e32 v137, v137, v52
	v_add_f32_e32 v137, v137, v53
	v_add_f32_e32 v137, v137, v54
	v_add_f32_e32 v137, v137, v55
	v_add_f32_e32 v137, v137, v56
	v_add_f32_e32 v137, v137, v57
	v_add_f32_e32 v137, v137, v58
	v_add_f32_e32 v137, v137, v59
	v_add_f32_e32 v137, v137, v60
	v_add_f32_e32 v137, v137, v61
	v_add_f32_e32 v137, v137, v62
	v_add_f32_e32 v137, v137, v141
	v_add_f32_e32 v137, v137, v63
	v_add_f32_e32 v137, v137, v143
	v_add_f32_e32 v137, v137, v18
	v_add_f32_e32 v137, v137, v19
	v_add_f32_e32 v137, v137, v20
	v_add_f32_e32 v137, v137, v21
	v_add_f32_e32 v137, v137, v22
	v_add_f32_e32 v137, v137, v23
	v_add_f32_e32 v137, v137, v24
	v_add_f32_e32 v137, v137, v25
	v_add_f32_e32 v137, v137, v26
	v_xor_b32_e32 v0, 32, v216
	v_add_f32_e32 v137, v137, v27
	v_cmp_lt_i32_e32 vcc, v0, v130
	v_add_f32_e32 v137, v137, v28
	v_add_f32_e32 v137, v137, v29
	v_cndmask_b32_e32 v0, v216, v0, vcc
	v_lshlrev_b32_e32 v135, 2, v0
	v_lshlrev_b32_e32 v0, 9, v177
	v_lshlrev_b32_e32 v1, 5, v175
	v_lshrrev_b32_e32 v130, 8, v173
	v_add_f32_e32 v137, v137, v30
	v_or3_b32 v0, v1, v0, v130
	v_add_f32_e32 v137, v137, v31
	v_ashrrev_i32_e32 v1, 31, v0
	ds_bpermute_b32 v139, v135, v137
	v_and_b32_e32 v130, 0xc0, v188
	v_lshlrev_b64 v[0:1], 10, v[0:1]
	v_lshl_add_u64 v[0:1], s[50:51], 0, v[0:1]
	v_lshlrev_b32_e32 v130, 2, v130
	v_lshl_add_u64 v[0:1], v[0:1], 0, v[130:131]
	v_mov_b32_e32 v191, v131
	v_lshl_add_u64 v[0:1], v[0:1], 0, v[190:191]
	s_and_saveexec_b64 s[0:1], s[6:7]
	s_cbranch_execz .LBB0_1028
	s_waitcnt lgkmcnt(0)
	v_add_f32_e32 v130, v137, v139
	global_store_dword v[0:1], v130, off
.LBB0_1028:
	s_or_b64 exec, exec, s[0:1]
	v_add_f32_e32 v130, 0, v32
	v_add_f32_e32 v130, v130, v33
	v_add_f32_e32 v130, v130, v34
	v_add_f32_e32 v130, v130, v35
	v_add_f32_e32 v130, v130, v36
	v_add_f32_e32 v130, v130, v37
	v_add_f32_e32 v130, v130, v38
	v_add_f32_e32 v130, v130, v39
	v_add_f32_e32 v130, v130, v40
	v_add_f32_e32 v130, v130, v41
	v_add_f32_e32 v130, v130, v42
	v_add_f32_e32 v130, v130, v43
	v_add_f32_e32 v130, v130, v44
	v_add_f32_e32 v130, v130, v45
	v_add_f32_e32 v130, v130, v46
	v_add_f32_e32 v130, v130, v47
	v_add_f32_e32 v130, v130, v16
	v_add_f32_e32 v130, v130, v17
	v_add_f32_e32 v130, v130, v2
	v_add_f32_e32 v130, v130, v3
	v_add_f32_e32 v130, v130, v4
	v_add_f32_e32 v130, v130, v5
	v_add_f32_e32 v130, v130, v6
	v_add_f32_e32 v130, v130, v7
	v_add_f32_e32 v130, v130, v8
	v_add_f32_e32 v130, v130, v9
	v_add_f32_e32 v130, v130, v10
	v_add_f32_e32 v130, v130, v11
	v_add_f32_e32 v130, v130, v12
	v_add_f32_e32 v130, v130, v13
	v_add_f32_e32 v130, v130, v14
	v_add_f32_e32 v130, v130, v15
	ds_bpermute_b32 v135, v135, v130
	s_and_saveexec_b64 s[0:1], s[6:7]
	s_cbranch_execz .LBB0_1003
	s_waitcnt lgkmcnt(0)
	v_add_f32_e32 v130, v130, v135
	global_store_dword v[0:1], v130, off offset:128
	s_branch .LBB0_1003

.LBB0_1436:
	s_or_b64 exec, exec, s[0:1]
	v_readlane_b32 s0, v255, 5
	v_readlane_b32 s1, v255, 6
	v_mov_b32_e32 v0, v196
	s_andn2_b64 vcc, exec, s[0:1]
	s_waitcnt lgkmcnt(0)
	s_barrier
	s_cbranch_vccnz .LBB0_1449
	s_lshl_b32 s65, s12, 1
	s_lshl_b32 s66, s58, 1
	s_mov_b32 s72, 0
	s_lshr_b32 s0, s65, 6
	s_mov_b32 s1, 0
	s_lshl_b32 s2, s65, 7
	s_and_b32 s10, s2, 0x1f00
	s_lshl_b64 s[2:3], s[0:1], 20
	s_add_u32 s0, s26, s2
	s_addc_u32 s5, s27, s3
	s_lshl_b32 s4, s10, 7
	s_add_u32 s4, s0, s4
	v_mov_b32_e32 v1, v196
	s_addc_u32 s5, s5, 0
	s_add_u32 s0, s46, s2
	v_ashrrev_i32_e32 v2, 3, v1
	v_ashrrev_i32_e32 v4, 5, v1
	v_lshlrev_b32_e32 v1, 4, v1
	s_addc_u32 s3, s47, s3
	s_lshl_b32 s2, s10, 1
	v_and_b32_e32 v144, 0x70, v1
	v_mov_b32_e32 v145, 0
	v_ashrrev_i32_e32 v3, 31, v2
	s_add_u32 s2, s0, s2
	v_lshl_add_u64 v[6:7], s[4:5], 0, v[144:145]
	v_lshlrev_b64 v[2:3], 7, v[2:3]
	s_addc_u32 s3, s3, 0
	v_and_b32_e32 v144, 0x1f0, v1
	v_lshl_add_u64 v[2:3], v[6:7], 0, v[2:3]
	v_ashrrev_i32_e32 v5, 31, v4
	s_movk_i32 s10, 0x2000
	v_lshl_add_u64 v[8:9], s[2:3], 0, v[144:145]
	v_lshlrev_b64 v[4:5], 14, v[4:5]
	v_add_co_u32_e32 v6, vcc, s10, v2
	v_lshl_add_u64 v[4:5], v[8:9], 0, v[4:5]
	s_nop 0
	v_addc_co_u32_e32 v7, vcc, 0, v3, vcc
	s_mov_b32 s11, 0x20000
	v_add_co_u32_e32 v8, vcc, s11, v4
	s_mov_b32 s14, 0x40000
	s_nop 0
	v_addc_co_u32_e32 v9, vcc, 0, v5, vcc
	global_load_dwordx4 v[64:67], v[2:3], off
	global_load_dwordx4 v[68:71], v[4:5], off
	global_load_dwordx4 v[72:75], v[6:7], off offset:-4096
	global_load_dwordx4 v[76:79], v[6:7], off
	v_add_co_u32_e32 v6, vcc, s14, v4
	s_movk_i32 s15, 0x4000
	s_nop 0
	v_addc_co_u32_e32 v7, vcc, 0, v5, vcc
	global_load_dwordx4 v[80:83], v[8:9], off
	global_load_dwordx4 v[84:87], v[6:7], off
	v_add_co_u32_e32 v6, vcc, s15, v2
	s_mov_b32 s33, 0x60000
	s_nop 0
	v_addc_co_u32_e32 v7, vcc, 0, v3, vcc
	v_add_co_u32_e32 v8, vcc, s33, v4
	s_mov_b32 s38, 0x80000
	s_nop 0
	v_addc_co_u32_e32 v9, vcc, 0, v5, vcc
	global_load_dwordx4 v[88:91], v[6:7], off offset:-4096
	global_load_dwordx4 v[92:95], v[6:7], off
	v_add_co_u32_e32 v6, vcc, s38, v4
	s_movk_i32 s0, 0x6000
	s_nop 0
	v_addc_co_u32_e32 v7, vcc, 0, v5, vcc
	global_load_dwordx4 v[96:99], v[8:9], off
	global_load_dwordx4 v[100:103], v[6:7], off
	v_add_co_u32_e32 v6, vcc, s0, v2
	s_mov_b32 s39, 0xa0000
	s_nop 0
	v_addc_co_u32_e32 v7, vcc, 0, v3, vcc
	v_add_co_u32_e32 v8, vcc, s39, v4
	s_mov_b32 s0, 0xc0000
	s_nop 0
	v_addc_co_u32_e32 v9, vcc, 0, v5, vcc
	global_load_dwordx4 v[104:107], v[6:7], off offset:-4096
	global_load_dwordx4 v[112:115], v[6:7], off
	v_add_co_u32_e32 v6, vcc, s0, v4
	s_movk_i32 s0, 0x7000
	s_nop 0
	v_addc_co_u32_e32 v7, vcc, 0, v5, vcc
	v_add_co_u32_e32 v2, vcc, s0, v2
	s_mov_b32 s0, 0xe0000
	s_nop 0
	v_addc_co_u32_e32 v3, vcc, 0, v3, vcc
	v_add_co_u32_e32 v4, vcc, s0, v4
	global_load_dwordx4 v[108:111], v[8:9], off
	global_load_dwordx4 v[116:119], v[6:7], off
	v_addc_co_u32_e32 v5, vcc, 0, v5, vcc
	global_load_dwordx4 v[120:123], v[2:3], off
	global_load_dwordx4 v[124:127], v[4:5], off
	v_and_b32_e32 v152, 31, v0
	v_bfe_u32 v1, v0, 5, 1
	v_ashrrev_i32_e32 v0, 1, v0
	v_and_b32_e32 v153, 0xffffffe0, v0
	v_lshlrev_b32_e32 v144, 4, v1
	v_lshlrev_b32_e32 v0, 2, v1
	s_add_u32 s41, s56, 0x2e00000
	s_movk_i32 s40, 0x5000
	v_lshl_add_u64 v[146:147], s[6:7], 0, v[144:145]
	s_addc_u32 s42, s57, 0
	s_movk_i32 s43, 0x208
	s_mov_b32 s44, 0xf149f2ca
	s_mov_b32 s45, 0x400000
	v_lshlrev_b32_e32 v144, 1, v0
	v_mbcnt_hi_u32_b32 v154, -1, v253
	v_mov_b32_e32 v155, 0xf149f2ca
	s_mov_b32 s0, s65
	s_branch .LBB0_1439
.LBB0_1438:
	s_or_b64 exec, exec, s[36:37]
	s_ashr_i32 s36, s0, 10
	v_lshl_add_u32 v34, s36, 13, v148
	v_ashrrev_i32_e32 v35, 31, v34
	s_and_b32 s34, s34, 15
	v_lshlrev_b64 v[34:35], 11, v[34:35]
	v_lshl_add_u64 v[34:35], s[18:19], 0, v[34:35]
	s_lshl_b32 s0, s34, 7
	s_ashr_i32 s37, s36, 31
	v_lshl_add_u64 v[34:35], v[34:35], 0, s[0:1]
	s_lshl_b32 s0, s34, 13
	s_lshl_b64 s[34:35], s[36:37], 24
	v_lshl_add_u64 v[38:39], v[148:149], 0, s[0:1]
	s_add_u32 s50, s30, s34
	v_lshlrev_b64 v[38:39], 7, v[38:39]
	s_addc_u32 s51, s31, s35
	v_lshl_add_u64 v[40:41], s[50:51], 0, v[38:39]
	s_add_u32 s50, s20, s34
	s_addc_u32 s51, s21, s35
	s_add_u32 s0, s28, s34
	s_addc_u32 s34, s29, s35
	s_add_u32 s0, s0, 0x1000000
	v_lshl_add_u64 v[40:41], v[40:41], 0, v[144:145]
	v_lshl_add_u64 v[42:43], s[50:51], 0, v[38:39]
	s_addc_u32 s34, s34, 0
	s_cmp_eq_u32 s67, 0
	s_cbranch_scc1 .Lao_w0
	s_waitcnt vmcnt(16)
	s_branch .Lao_w1

.Lao_w1:
	v_mov_b32_e32 v52, v184
	v_mov_b32_e32 v53, v185
	v_lshl_add_u64 v[42:43], v[42:43], 0, v[144:145]
	s_cmp_lt_i32 s36, 3
	v_mov_b32_e32 v54, v202
	v_mov_b32_e32 v55, v203
	s_cselect_b32 s35, s34, s42
	s_cselect_b32 s34, s0, s41
	v_lshl_add_u64 v[38:39], s[34:35], 0, v[38:39]
	v_lshl_add_u64 v[38:39], v[38:39], 0, v[144:145]
	v_mov_b32_e32 v56, v218
	v_mov_b32_e32 v57, v219
	v_lshl_add_u64 v[34:35], v[34:35], 0, v[144:145]
	v_mov_b32_e32 v50, v234
	v_mov_b32_e32 v51, v235
	v_sub_f32_e32 v46, v46, v48
	v_sub_f32_e32 v49, v36, v48
	v_sub_f32_e32 v44, v44, v48
	v_exp_f32_e32 v36, v46
	v_exp_f32_e32 v46, v49
	v_exp_f32_e32 v44, v44
	s_waitcnt lgkmcnt(0)
	v_add_f32_e32 v33, v47, v33
	v_fma_f32 v33, v33, v36, v32
	v_mul_f32_e32 v37, v37, v46
	v_mul_f32_e32 v44, v45, v44
	v_pk_mul_f32 v[48:49], v[18:19], v[36:37] op_sel_hi:[1,0]
	v_cndmask_b32_e64 v18, 0, v37, s[6:7]
	v_pk_mul_f32 v[46:47], v[16:17], v[36:37] op_sel_hi:[1,0]
	v_cndmask_b32_e64 v16, 0, v44, s[2:3]
	v_add_f32_e32 v17, v18, v33
	v_add_f32_e32 v17, v16, v17
	v_div_scale_f32 v19, s[34:35], v17, v17, 1.0
	v_rcp_f32_e32 v37, v19
	v_div_scale_f32 v33, vcc, 1.0, v17, 1.0
	v_mov_b32_e32 v58, v236
	v_mov_b32_e32 v59, v237
	v_mov_b32_e32 v60, v238
	v_mov_b32_e32 v61, v239
	v_mov_b32_e32 v62, v240
	v_mov_b32_e32 v63, v241
	v_fma_f32 v44, -v19, v37, 1.0
	v_fmac_f32_e32 v37, v44, v37
	v_mul_f32_e32 v44, v33, v37
	v_fma_f32 v45, -v19, v44, v33
	v_fmac_f32_e32 v44, v45, v37
	v_fma_f32 v19, -v19, v44, v33
	v_div_fmas_f32 v19, v19, v37, v44
	v_div_fixup_f32 v44, v19, v17, 1.0
	v_mov_b32_e32 v128, v186
	v_mov_b32_e32 v129, v187
	v_mov_b32_e32 v130, v188
	v_mov_b32_e32 v131, v189
	v_mov_b32_e32 v132, v190
	v_mov_b32_e32 v133, v191
	v_mov_b32_e32 v134, v204
	v_mov_b32_e32 v135, v205
	v_mov_b32_e32 v136, v206
	v_mov_b32_e32 v137, v207
	v_mov_b32_e32 v138, v208
	v_mov_b32_e32 v139, v209
	v_pk_mul_f32 v[20:21], v[20:21], v[36:37] op_sel_hi:[1,0]
	v_pk_mul_f32 v[22:23], v[22:23], v[36:37] op_sel_hi:[1,0]
	v_pk_mul_f32 v[0:1], v[0:1], v[36:37] op_sel_hi:[1,0]
	v_pk_mul_f32 v[2:3], v[2:3], v[36:37] op_sel_hi:[1,0]
	s_andn2_b64 vcc, exec, s[16:17]
	s_add_i32 s0, s68, 1
	s_bitcmp1_b32 s68, 0
	s_cselect_b32 s0, s48, s0
	s_cselect_b64 vcc, vcc, exec
	s_nop 0
	v_cndmask_b32_e64 v17, 0, v53, s[6:7]
	v_cndmask_b32_e64 v19, 0, v52, s[6:7]
	v_lshlrev_b32_e32 v52, 16, v19
	v_and_b32_e32 v53, 0xffff0000, v19
	v_lshlrev_b32_e32 v142, 16, v17
	v_and_b32_e32 v143, 0xffff0000, v17
	s_nop 0
	v_cndmask_b32_e64 v17, 0, v55, s[4:5]
	v_cndmask_b32_e64 v19, 0, v54, s[4:5]
	v_lshlrev_b32_e32 v54, 16, v19
	v_and_b32_e32 v55, 0xffff0000, v19
	v_lshlrev_b32_e32 v148, 16, v17
	v_and_b32_e32 v149, 0xffff0000, v17
	v_pk_fma_f32 v[46:47], v[54:55], v[32:33], v[46:47] op_sel_hi:[1,0,1]
	v_pk_fma_f32 v[48:49], v[148:149], v[32:33], v[48:49] op_sel_hi:[1,0,1]
	v_pk_fma_f32 v[46:47], v[52:53], v[18:19], v[46:47] op_sel_hi:[1,0,1]
	v_pk_fma_f32 v[48:49], v[142:143], v[18:19], v[48:49] op_sel_hi:[1,0,1]
	s_nop 0
	v_cndmask_b32_e64 v17, 0, v57, s[2:3]
	v_cndmask_b32_e64 v19, 0, v56, s[2:3]
	v_lshlrev_b32_e32 v52, 16, v19
	v_and_b32_e32 v53, 0xffff0000, v19
	v_lshlrev_b32_e32 v54, 16, v17
	v_and_b32_e32 v55, 0xffff0000, v17
	v_pk_fma_f32 v[46:47], v[52:53], v[16:17], v[46:47] op_sel_hi:[1,0,1]
	v_pk_fma_f32 v[48:49], v[54:55], v[16:17], v[48:49] op_sel_hi:[1,0,1]
	s_nop 0
	v_lshlrev_b32_e32 v140, 16, v50
	v_and_b32_e32 v141, 0xffff0000, v50
	v_lshlrev_b32_e32 v50, 16, v51
	v_and_b32_e32 v51, 0xffff0000, v51
	v_pk_mul_f32 v[46:47], v[44:45], v[46:47] op_sel_hi:[0,1]
	v_pk_mul_f32 v[48:49], v[44:45], v[48:49] op_sel_hi:[0,1]
	v_pk_mul_f32 v[46:47], v[46:47], v[140:141]
	v_pk_mul_f32 v[48:49], v[48:49], v[50:51]
	v_cvt_pk_bf16_f32 v46, v46, v47
	v_cvt_pk_bf16_f32 v47, v48, v49
	global_store_dwordx2 v[34:35], v[46:47], off
	v_mov_b32_e32 v46, v220
	v_mov_b32_e32 v47, v221
	s_nop 0
	v_cndmask_b32_e64 v17, 0, v129, s[6:7]
	v_cndmask_b32_e64 v19, 0, v128, s[6:7]
	v_lshlrev_b32_e32 v52, 16, v19
	v_and_b32_e32 v53, 0xffff0000, v19
	v_lshlrev_b32_e32 v54, 16, v17
	v_and_b32_e32 v55, 0xffff0000, v17
	s_nop 0
	v_cndmask_b32_e64 v17, 0, v135, s[4:5]
	v_cndmask_b32_e64 v19, 0, v134, s[4:5]
	v_lshlrev_b32_e32 v48, 16, v58
	v_and_b32_e32 v49, 0xffff0000, v58
	v_lshlrev_b32_e32 v50, 16, v59
	v_and_b32_e32 v51, 0xffff0000, v59
	v_lshlrev_b32_e32 v56, 16, v19
	v_and_b32_e32 v57, 0xffff0000, v19
	v_lshlrev_b32_e32 v58, 16, v17
	v_and_b32_e32 v59, 0xffff0000, v17
	v_pk_fma_f32 v[20:21], v[56:57], v[32:33], v[20:21] op_sel_hi:[1,0,1]
	v_pk_fma_f32 v[22:23], v[58:59], v[32:33], v[22:23] op_sel_hi:[1,0,1]
	v_pk_fma_f32 v[20:21], v[52:53], v[18:19], v[20:21] op_sel_hi:[1,0,1]
	v_pk_fma_f32 v[22:23], v[54:55], v[18:19], v[22:23] op_sel_hi:[1,0,1]
	s_nop 0
	v_cndmask_b32_e64 v17, 0, v47, s[2:3]
	v_cndmask_b32_e64 v19, 0, v46, s[2:3]
	v_lshlrev_b32_e32 v46, 16, v19
	v_and_b32_e32 v47, 0xffff0000, v19
	v_lshlrev_b32_e32 v52, 16, v17
	v_and_b32_e32 v53, 0xffff0000, v17
	v_pk_fma_f32 v[20:21], v[46:47], v[16:17], v[20:21] op_sel_hi:[1,0,1]
	v_pk_fma_f32 v[22:23], v[52:53], v[16:17], v[22:23] op_sel_hi:[1,0,1]
	v_pk_mul_f32 v[20:21], v[44:45], v[20:21] op_sel_hi:[0,1]
	v_pk_mul_f32 v[22:23], v[44:45], v[22:23] op_sel_hi:[0,1]
	v_pk_mul_f32 v[20:21], v[20:21], v[48:49]
	v_pk_mul_f32 v[22:23], v[22:23], v[50:51]
	v_cvt_pk_bf16_f32 v20, v20, v21
	v_cvt_pk_bf16_f32 v21, v22, v23
	global_store_dwordx2 v[34:35], v[20:21], off offset:16
	v_mov_b32_e32 v20, v222
	v_mov_b32_e32 v21, v223
	v_cndmask_b32_e64 v17, 0, v131, s[6:7]
	v_cndmask_b32_e64 v19, 0, v130, s[6:7]
	v_lshlrev_b32_e32 v48, 16, v19
	v_and_b32_e32 v49, 0xffff0000, v19
	v_lshlrev_b32_e32 v50, 16, v17
	v_and_b32_e32 v51, 0xffff0000, v17
	v_cndmask_b32_e64 v17, 0, v137, s[4:5]
	v_cndmask_b32_e64 v19, 0, v136, s[4:5]
	v_pk_mul_f32 v[22:23], v[24:25], v[36:37] op_sel_hi:[1,0]
	v_pk_mul_f32 v[24:25], v[26:27], v[36:37] op_sel_hi:[1,0]
	v_lshlrev_b32_e32 v52, 16, v19
	v_and_b32_e32 v53, 0xffff0000, v19
	v_lshlrev_b32_e32 v54, 16, v17
	v_and_b32_e32 v55, 0xffff0000, v17
	v_pk_fma_f32 v[22:23], v[52:53], v[32:33], v[22:23] op_sel_hi:[1,0,1]
	v_pk_fma_f32 v[24:25], v[54:55], v[32:33], v[24:25] op_sel_hi:[1,0,1]
	v_pk_fma_f32 v[22:23], v[48:49], v[18:19], v[22:23] op_sel_hi:[1,0,1]
	v_pk_fma_f32 v[24:25], v[50:51], v[18:19], v[24:25] op_sel_hi:[1,0,1]
	v_lshlrev_b32_e32 v26, 16, v60
	v_and_b32_e32 v27, 0xffff0000, v60
	v_lshlrev_b32_e32 v46, 16, v61
	v_and_b32_e32 v47, 0xffff0000, v61
	s_nop 0
	v_cndmask_b32_e64 v17, 0, v21, s[2:3]
	v_cndmask_b32_e64 v19, 0, v20, s[2:3]
	v_lshlrev_b32_e32 v20, 16, v19
	v_and_b32_e32 v21, 0xffff0000, v19
	v_lshlrev_b32_e32 v48, 16, v17
	v_and_b32_e32 v49, 0xffff0000, v17
	v_pk_fma_f32 v[20:21], v[20:21], v[16:17], v[22:23] op_sel_hi:[1,0,1]
	v_pk_fma_f32 v[22:23], v[48:49], v[16:17], v[24:25] op_sel_hi:[1,0,1]
	v_pk_mul_f32 v[20:21], v[44:45], v[20:21] op_sel_hi:[0,1]
	v_pk_mul_f32 v[22:23], v[44:45], v[22:23] op_sel_hi:[0,1]
	v_pk_mul_f32 v[20:21], v[20:21], v[26:27]
	v_pk_mul_f32 v[22:23], v[22:23], v[46:47]
	v_cvt_pk_bf16_f32 v20, v20, v21
	v_cvt_pk_bf16_f32 v21, v22, v23
	global_store_dwordx2 v[34:35], v[20:21], off offset:32
	v_mov_b32_e32 v20, v224
	v_mov_b32_e32 v21, v225
	v_cndmask_b32_e64 v17, 0, v133, s[6:7]
	v_cndmask_b32_e64 v19, 0, v132, s[6:7]
	v_lshlrev_b32_e32 v50, 16, v19
	v_and_b32_e32 v51, 0xffff0000, v19
	v_lshlrev_b32_e32 v52, 16, v17
	v_and_b32_e32 v53, 0xffff0000, v17
	v_cndmask_b32_e64 v17, 0, v139, s[4:5]
	v_cndmask_b32_e64 v19, 0, v138, s[4:5]
	v_pk_mul_f32 v[22:23], v[28:29], v[36:37] op_sel_hi:[1,0]
	v_pk_mul_f32 v[24:25], v[30:31], v[36:37] op_sel_hi:[1,0]
	v_lshlrev_b32_e32 v54, 16, v19
	v_and_b32_e32 v55, 0xffff0000, v19
	v_lshlrev_b32_e32 v56, 16, v17
	v_and_b32_e32 v57, 0xffff0000, v17
	v_pk_fma_f32 v[22:23], v[54:55], v[32:33], v[22:23] op_sel_hi:[1,0,1]
	v_pk_fma_f32 v[24:25], v[56:57], v[32:33], v[24:25] op_sel_hi:[1,0,1]
	v_pk_fma_f32 v[22:23], v[50:51], v[18:19], v[22:23] op_sel_hi:[1,0,1]
	v_pk_fma_f32 v[24:25], v[52:53], v[18:19], v[24:25] op_sel_hi:[1,0,1]
	v_lshlrev_b32_e32 v46, 16, v62
	v_and_b32_e32 v47, 0xffff0000, v62
	v_lshlrev_b32_e32 v48, 16, v63
	v_and_b32_e32 v49, 0xffff0000, v63
	v_mov_b32_e32 v26, v242
	v_mov_b32_e32 v27, v243
	v_mov_b32_e32 v28, v192
	v_mov_b32_e32 v29, v193
	v_mov_b32_e32 v30, v210
	v_mov_b32_e32 v31, v211
	s_nop 0
	v_cndmask_b32_e64 v17, 0, v21, s[2:3]
	v_cndmask_b32_e64 v19, 0, v20, s[2:3]
	v_lshlrev_b32_e32 v20, 16, v19
	v_and_b32_e32 v21, 0xffff0000, v19
	v_lshlrev_b32_e32 v50, 16, v17
	v_and_b32_e32 v51, 0xffff0000, v17
	v_pk_fma_f32 v[20:21], v[20:21], v[16:17], v[22:23] op_sel_hi:[1,0,1]
	v_pk_fma_f32 v[22:23], v[50:51], v[16:17], v[24:25] op_sel_hi:[1,0,1]
	v_pk_mul_f32 v[20:21], v[44:45], v[20:21] op_sel_hi:[0,1]
	v_pk_mul_f32 v[22:23], v[44:45], v[22:23] op_sel_hi:[0,1]
	v_pk_mul_f32 v[20:21], v[20:21], v[46:47]
	v_pk_mul_f32 v[22:23], v[22:23], v[48:49]
	v_cvt_pk_bf16_f32 v20, v20, v21
	v_cvt_pk_bf16_f32 v21, v22, v23
	global_store_dwordx2 v[34:35], v[20:21], off offset:48
	v_mov_b32_e32 v20, v226
	v_mov_b32_e32 v21, v227
	s_nop 0
	v_mov_b32_e32 v22, v244
	v_mov_b32_e32 v23, v245
	v_mov_b32_e32 v24, v246
	v_mov_b32_e32 v25, v247
	v_mov_b32_e32 v46, v248
	v_mov_b32_e32 v47, v249
	v_mov_b32_e32 v48, v194
	v_mov_b32_e32 v49, v195
	v_mov_b32_e32 v50, v198
	v_mov_b32_e32 v51, v199
	s_nop 0
	v_mov_b32_e32 v40, v200
	v_mov_b32_e32 v41, v201
	s_nop 0
	v_mov_b32_e32 v52, v212
	v_mov_b32_e32 v53, v213
	v_mov_b32_e32 v54, v214
	v_mov_b32_e32 v55, v215
	s_nop 0
	v_mov_b32_e32 v42, v216
	v_mov_b32_e32 v43, v217
	s_nop 0
	v_lshlrev_b32_e32 v56, 16, v26
	s_nop 0
	v_cndmask_b32_e64 v17, 0, v29, s[6:7]
	v_cndmask_b32_e64 v19, 0, v28, s[6:7]
	v_lshlrev_b32_e32 v28, 16, v19
	v_and_b32_e32 v29, 0xffff0000, v19
	v_lshlrev_b32_e32 v58, 16, v17
	v_and_b32_e32 v59, 0xffff0000, v17
	s_nop 0
	v_cndmask_b32_e64 v17, 0, v31, s[4:5]
	v_cndmask_b32_e64 v19, 0, v30, s[4:5]
	v_lshlrev_b32_e32 v30, 16, v19
	v_and_b32_e32 v31, 0xffff0000, v19
	v_lshlrev_b32_e32 v60, 16, v17
	v_and_b32_e32 v61, 0xffff0000, v17
	v_pk_fma_f32 v[0:1], v[30:31], v[32:33], v[0:1] op_sel_hi:[1,0,1]
	v_pk_fma_f32 v[2:3], v[60:61], v[32:33], v[2:3] op_sel_hi:[1,0,1]
	v_pk_fma_f32 v[0:1], v[28:29], v[18:19], v[0:1] op_sel_hi:[1,0,1]
	v_pk_fma_f32 v[2:3], v[58:59], v[18:19], v[2:3] op_sel_hi:[1,0,1]
	v_and_b32_e32 v57, 0xffff0000, v26
	v_lshlrev_b32_e32 v26, 16, v27
	v_and_b32_e32 v27, 0xffff0000, v27
	s_nop 0
	v_cndmask_b32_e64 v17, 0, v21, s[2:3]
	v_cndmask_b32_e64 v19, 0, v20, s[2:3]
	v_lshlrev_b32_e32 v20, 16, v19
	v_and_b32_e32 v21, 0xffff0000, v19
	v_lshlrev_b32_e32 v28, 16, v17
	v_and_b32_e32 v29, 0xffff0000, v17
	v_pk_fma_f32 v[0:1], v[20:21], v[16:17], v[0:1] op_sel_hi:[1,0,1]
	v_pk_fma_f32 v[2:3], v[28:29], v[16:17], v[2:3] op_sel_hi:[1,0,1]
	v_pk_mul_f32 v[0:1], v[44:45], v[0:1] op_sel_hi:[0,1]
	v_pk_mul_f32 v[2:3], v[44:45], v[2:3] op_sel_hi:[0,1]
	v_pk_mul_f32 v[0:1], v[0:1], v[56:57]
	v_pk_mul_f32 v[2:3], v[2:3], v[26:27]
	v_cvt_pk_bf16_f32 v0, v0, v1
	v_cvt_pk_bf16_f32 v1, v2, v3
	global_store_dwordx2 v[34:35], v[0:1], off offset:64
	v_mov_b32_e32 v0, v228
	v_mov_b32_e32 v1, v229
	s_nop 0
	v_cndmask_b32_e64 v17, 0, v49, s[6:7]
	v_cndmask_b32_e64 v19, 0, v48, s[6:7]
	v_pk_mul_f32 v[2:3], v[4:5], v[36:37] op_sel_hi:[1,0]
	v_pk_mul_f32 v[4:5], v[6:7], v[36:37] op_sel_hi:[1,0]
	v_lshlrev_b32_e32 v6, 16, v22
	v_and_b32_e32 v7, 0xffff0000, v22
	v_lshlrev_b32_e32 v20, 16, v23
	v_and_b32_e32 v21, 0xffff0000, v23
	v_lshlrev_b32_e32 v22, 16, v19
	v_and_b32_e32 v23, 0xffff0000, v19
	v_lshlrev_b32_e32 v26, 16, v17
	v_and_b32_e32 v27, 0xffff0000, v17
	s_nop 0
	v_cndmask_b32_e64 v17, 0, v53, s[4:5]
	v_cndmask_b32_e64 v19, 0, v52, s[4:5]
	v_lshlrev_b32_e32 v28, 16, v19
	v_and_b32_e32 v29, 0xffff0000, v19
	v_lshlrev_b32_e32 v30, 16, v17
	v_and_b32_e32 v31, 0xffff0000, v17
	v_pk_fma_f32 v[2:3], v[28:29], v[32:33], v[2:3] op_sel_hi:[1,0,1]
	v_pk_fma_f32 v[4:5], v[30:31], v[32:33], v[4:5] op_sel_hi:[1,0,1]
	v_pk_fma_f32 v[2:3], v[22:23], v[18:19], v[2:3] op_sel_hi:[1,0,1]
	v_pk_fma_f32 v[4:5], v[26:27], v[18:19], v[4:5] op_sel_hi:[1,0,1]
	s_nop 0
	v_cndmask_b32_e64 v19, 0, v54, s[4:5]
	s_nop 0
	v_cndmask_b32_e64 v17, 0, v1, s[2:3]
	v_cndmask_b32_e64 v1, 0, v0, s[2:3]
	v_lshlrev_b32_e32 v0, 16, v1
	v_and_b32_e32 v1, 0xffff0000, v1
	v_lshlrev_b32_e32 v22, 16, v17
	v_and_b32_e32 v23, 0xffff0000, v17
	v_pk_fma_f32 v[0:1], v[0:1], v[16:17], v[2:3] op_sel_hi:[1,0,1]
	v_pk_fma_f32 v[2:3], v[22:23], v[16:17], v[4:5] op_sel_hi:[1,0,1]
	v_pk_mul_f32 v[0:1], v[44:45], v[0:1] op_sel_hi:[0,1]
	v_pk_mul_f32 v[2:3], v[44:45], v[2:3] op_sel_hi:[0,1]
	v_pk_mul_f32 v[0:1], v[0:1], v[6:7]
	v_pk_mul_f32 v[2:3], v[2:3], v[20:21]
	v_cvt_pk_bf16_f32 v0, v0, v1
	v_cvt_pk_bf16_f32 v1, v2, v3
	global_store_dwordx2 v[34:35], v[0:1], off offset:80
	v_mov_b32_e32 v0, v230
	v_mov_b32_e32 v1, v231
	v_cndmask_b32_e64 v17, 0, v51, s[6:7]
	v_pk_mul_f32 v[2:3], v[8:9], v[36:37] op_sel_hi:[1,0]
	v_pk_mul_f32 v[4:5], v[10:11], v[36:37] op_sel_hi:[1,0]
	v_cndmask_b32_e64 v11, 0, v50, s[6:7]
	v_lshlrev_b32_e32 v20, 16, v17
	v_and_b32_e32 v21, 0xffff0000, v17
	v_cndmask_b32_e64 v17, 0, v55, s[4:5]
	v_lshlrev_b32_e32 v22, 16, v19
	v_and_b32_e32 v23, 0xffff0000, v19
	v_lshlrev_b32_e32 v6, 16, v24
	v_and_b32_e32 v7, 0xffff0000, v24
	v_lshlrev_b32_e32 v8, 16, v25
	v_and_b32_e32 v9, 0xffff0000, v25
	v_lshlrev_b32_e32 v10, 16, v11
	v_and_b32_e32 v11, 0xffff0000, v11
	v_lshlrev_b32_e32 v24, 16, v17
	v_and_b32_e32 v25, 0xffff0000, v17
	v_pk_fma_f32 v[2:3], v[22:23], v[32:33], v[2:3] op_sel_hi:[1,0,1]
	v_pk_fma_f32 v[4:5], v[24:25], v[32:33], v[4:5] op_sel_hi:[1,0,1]
	v_pk_fma_f32 v[2:3], v[10:11], v[18:19], v[2:3] op_sel_hi:[1,0,1]
	v_pk_fma_f32 v[4:5], v[20:21], v[18:19], v[4:5] op_sel_hi:[1,0,1]
	s_nop 0
	v_cndmask_b32_e64 v11, 0, v1, s[2:3]
	v_cndmask_b32_e64 v1, 0, v0, s[2:3]
	v_lshlrev_b32_e32 v0, 16, v1
	v_and_b32_e32 v1, 0xffff0000, v1
	v_lshlrev_b32_e32 v10, 16, v11
	v_and_b32_e32 v11, 0xffff0000, v11
	v_pk_fma_f32 v[0:1], v[0:1], v[16:17], v[2:3] op_sel_hi:[1,0,1]
	v_pk_fma_f32 v[2:3], v[10:11], v[16:17], v[4:5] op_sel_hi:[1,0,1]
	v_pk_mul_f32 v[0:1], v[44:45], v[0:1] op_sel_hi:[0,1]
	v_pk_mul_f32 v[2:3], v[44:45], v[2:3] op_sel_hi:[0,1]
	v_pk_mul_f32 v[0:1], v[0:1], v[6:7]
	v_pk_mul_f32 v[2:3], v[2:3], v[8:9]
	v_cvt_pk_bf16_f32 v0, v0, v1
	v_cvt_pk_bf16_f32 v1, v2, v3
	global_store_dwordx2 v[34:35], v[0:1], off offset:96
	v_mov_b32_e32 v0, v232
	v_mov_b32_e32 v1, v233
	v_pk_mul_f32 v[4:5], v[14:15], v[36:37] op_sel_hi:[1,0]
	v_cndmask_b32_e64 v15, 0, v42, s[4:5]
	v_pk_mul_f32 v[2:3], v[12:13], v[36:37] op_sel_hi:[1,0]
	v_cndmask_b32_e64 v11, 0, v40, s[6:7]
	v_cndmask_b32_e64 v17, 0, v43, s[4:5]
	v_lshlrev_b32_e32 v14, 16, v15
	v_and_b32_e32 v15, 0xffff0000, v15
	v_cndmask_b32_e64 v13, 0, v41, s[6:7]
	v_lshlrev_b32_e32 v10, 16, v11
	v_and_b32_e32 v11, 0xffff0000, v11
	v_lshlrev_b32_e32 v20, 16, v17
	v_and_b32_e32 v21, 0xffff0000, v17
	v_pk_fma_f32 v[2:3], v[14:15], v[32:33], v[2:3] op_sel_hi:[1,0,1]
	v_lshlrev_b32_e32 v12, 16, v13
	v_and_b32_e32 v13, 0xffff0000, v13
	v_pk_fma_f32 v[4:5], v[20:21], v[32:33], v[4:5] op_sel_hi:[1,0,1]
	v_pk_fma_f32 v[2:3], v[10:11], v[18:19], v[2:3] op_sel_hi:[1,0,1]
	v_pk_fma_f32 v[4:5], v[12:13], v[18:19], v[4:5] op_sel_hi:[1,0,1]
	v_lshlrev_b32_e32 v6, 16, v46
	v_and_b32_e32 v7, 0xffff0000, v46
	v_lshlrev_b32_e32 v8, 16, v47
	v_and_b32_e32 v9, 0xffff0000, v47
	s_nop 0
	v_cndmask_b32_e64 v11, 0, v1, s[2:3]
	v_cndmask_b32_e64 v1, 0, v0, s[2:3]
	v_lshlrev_b32_e32 v0, 16, v1
	v_and_b32_e32 v1, 0xffff0000, v1
	v_lshlrev_b32_e32 v10, 16, v11
	v_and_b32_e32 v11, 0xffff0000, v11
	v_pk_fma_f32 v[0:1], v[0:1], v[16:17], v[2:3] op_sel_hi:[1,0,1]
	v_pk_fma_f32 v[2:3], v[10:11], v[16:17], v[4:5] op_sel_hi:[1,0,1]
	v_pk_mul_f32 v[0:1], v[44:45], v[0:1] op_sel_hi:[0,1]
	v_pk_mul_f32 v[2:3], v[44:45], v[2:3] op_sel_hi:[0,1]
	v_pk_mul_f32 v[0:1], v[0:1], v[6:7]
	v_pk_mul_f32 v[2:3], v[2:3], v[8:9]
	v_cvt_pk_bf16_f32 v0, v0, v1
	v_cvt_pk_bf16_f32 v1, v2, v3
	global_store_dwordx2 v[34:35], v[0:1], off offset:112
	s_cbranch_vccz .LBB0_1449
.LBB0_1439:
	s_mov_b32 s68, s0
	s_bitcmp1_b32 s0, 0
	s_cbranch_scc1 .Lao_odd
	v_mov_b32_e32 v0, v196
	s_barrier
	s_add_i32 s48, s0, s66
	v_ashrrev_i32_e32 v1, 3, v0
	v_lshlrev_b32_e32 v3, 7, v1
	v_lshrrev_b32_e32 v1, 1, v1
	v_ashrrev_i32_e32 v2, 5, v0
	v_xor_b32_e32 v1, v1, v0
	v_lshlrev_b32_e32 v0, 4, v0
	v_lshlrev_b32_e32 v1, 4, v1
	v_and_b32_e32 v0, 0x1f0, v0
	v_mul_lo_u32 v2, v2, s43
	v_and_b32_e32 v1, 0x70, v1
	v_add3_u32 v0, 16, v0, v2
	v_add3_u32 v1, 16, v1, v3
	v_add_u32_e32 v2, 0x8000, v0
	s_waitcnt vmcnt(0)
	ds_write_b128 v1, v[64:67]
	ds_write2_b64 v2, v[68:69], v[70:71] offset1:1
	ds_write_b128 v1, v[72:75] offset:4096
	v_add_u32_e32 v2, 0x9040, v0
	ds_write2_b64 v2, v[80:81], v[82:83] offset1:1
	ds_write_b128 v1, v[76:79] offset:8192
	v_add_u32_e32 v2, 0xa080, v0
	ds_write2_b64 v2, v[84:85], v[86:87] offset1:1
	ds_write_b128 v1, v[88:91] offset:12288
	v_add_u32_e32 v2, 0xb0c0, v0
	ds_write2_b64 v2, v[96:97], v[98:99] offset1:1
	ds_write_b128 v1, v[92:95] offset:16384
	v_add_u32_e32 v2, 0xc100, v0
	s_cmpk_gt_i32 s48, 0xfff
	ds_write2_b64 v2, v[100:101], v[102:103] offset1:1
	ds_write_b128 v1, v[104:107] offset:20480
	v_add_u32_e32 v2, 0xd140, v0
	s_cselect_b64 s[16:17], -1, 0
	ds_write2_b64 v2, v[108:109], v[110:111] offset1:1
	ds_write_b128 v1, v[112:115] offset:24576
	v_add_u32_e32 v2, 0xe180, v0
	v_add_u32_e32 v0, 0xf1c0, v0
	s_and_b64 vcc, exec, s[16:17]
	ds_write2_b64 v2, v[116:117], v[118:119] offset1:1
	ds_write_b128 v1, v[120:123] offset:28672
	ds_write2_b64 v0, v[124:125], v[126:127] offset1:1
	s_waitcnt lgkmcnt(0)
	s_barrier
	s_mov_b32 s72, 0
	s_andn2_b32 s67, 1, s16
	s_branch .Lao_q
.Lao_odd:
	s_waitcnt vmcnt(8)
	s_movk_i32 s72, 0x60
	s_mov_b32 s67, 0
	s_mov_b64 vcc, exec
.Lao_q:
	s_lshl_b32 s2, s0, 7
	s_and_b32 s3, s2, 0x80
	v_xor_b32_e32 v251, s72, v153
	v_add_u32_e32 v1, s3, v251
	s_ashr_i32 s34, s0, 6
	v_or_b32_e32 v0, v1, v152
	s_and_b32 s2, s2, 0x1f00
	v_add_u32_e32 v148, s2, v0
	s_ashr_i32 s35, s34, 31
	s_lshl_b64 s[2:3], s[34:35], 13
	v_ashrrev_i32_e32 v149, 31, v148
	v_lshl_add_u64 v[150:151], s[2:3], 0, v[148:149]
	v_lshlrev_b64 v[2:3], 7, v[150:151]
	v_lshl_add_u64 v[2:3], v[146:147], 0, v[2:3]
	global_load_dwordx4 v[128:131], v[2:3], off
	global_load_dwordx4 v[132:135], v[2:3], off offset:32
	global_load_dwordx4 v[136:139], v[2:3], off offset:64
	global_load_dwordx4 v[140:143], v[2:3], off offset:96
	s_ashr_i32 s60, s0, 10
	s_and_b32 s61, s34, 15
	v_lshlrev_b32_e32 v250, 2, v150
	global_load_dword v197, v250, s[8:9]
	s_lshl_b64 s[62:63], s[34:35], 16
	s_add_u32 s62, s22, s62
	s_addc_u32 s63, s23, s63
	v_lshlrev_b32_e32 v252, 3, v148
	global_load_dwordx2 v[178:179], v252, s[62:63]
	s_add_u32 s62, s62, 0x400000
	s_addc_u32 s63, s63, 0
	global_load_dwordx2 v[180:181], v252, s[62:63]
	s_add_u32 s62, s62, 0x400000
	s_addc_u32 s63, s63, 0
	global_load_dwordx2 v[182:183], v252, s[62:63]
	s_lshl_b32 s62, s60, 13
	v_add_u32_e32 v254, s62, v148
	v_lshlrev_b32_e32 v254, 11, v254
	s_lshl_b32 s62, s61, 7
	v_add3_u32 v254, v254, s62, v144
	s_lshl_b32 s62, s61, 13
	v_add_u32_e32 v252, s62, v148
	v_lshlrev_b32_e32 v252, 7, v252
	v_add_u32_e32 v252, v252, v144
	s_lshl_b32 s61, s60, 24
	s_add_u32 s62, s30, s61
	s_addc_u32 s63, s31, 0
	global_load_dwordx2 v[184:185], v252, s[62:63]
	global_load_dwordx2 v[186:187], v252, s[62:63] offset:16
	global_load_dwordx2 v[188:189], v252, s[62:63] offset:32
	global_load_dwordx2 v[190:191], v252, s[62:63] offset:48
	global_load_dwordx2 v[192:193], v252, s[62:63] offset:64
	global_load_dwordx2 v[194:195], v252, s[62:63] offset:80
	global_load_dwordx2 v[198:199], v252, s[62:63] offset:96
	global_load_dwordx2 v[200:201], v252, s[62:63] offset:112
	s_add_u32 s62, s20, s61
	s_addc_u32 s63, s21, 0
	global_load_dwordx2 v[202:203], v252, s[62:63]
	global_load_dwordx2 v[204:205], v252, s[62:63] offset:16
	global_load_dwordx2 v[206:207], v252, s[62:63] offset:32
	global_load_dwordx2 v[208:209], v252, s[62:63] offset:48
	global_load_dwordx2 v[210:211], v252, s[62:63] offset:64
	global_load_dwordx2 v[212:213], v252, s[62:63] offset:80
	global_load_dwordx2 v[214:215], v252, s[62:63] offset:96
	global_load_dwordx2 v[216:217], v252, s[62:63] offset:112
	s_add_u32 s62, s28, s61
	s_addc_u32 s63, s29, 0
	s_add_u32 s62, s62, 0x1000000
	s_addc_u32 s63, s63, 0
	s_cmp_lt_i32 s60, 3
	s_cselect_b32 s62, s62, s41
	s_cselect_b32 s63, s63, s42
	global_load_dwordx2 v[218:219], v252, s[62:63]
	global_load_dwordx2 v[220:221], v252, s[62:63] offset:16
	global_load_dwordx2 v[222:223], v252, s[62:63] offset:32
	global_load_dwordx2 v[224:225], v252, s[62:63] offset:48
	global_load_dwordx2 v[226:227], v252, s[62:63] offset:64
	global_load_dwordx2 v[228:229], v252, s[62:63] offset:80
	global_load_dwordx2 v[230:231], v252, s[62:63] offset:96
	global_load_dwordx2 v[232:233], v252, s[62:63] offset:112
	global_load_dwordx2 v[234:235], v254, s[18:19]
	global_load_dwordx2 v[236:237], v254, s[18:19] offset:16
	global_load_dwordx2 v[238:239], v254, s[18:19] offset:32
	global_load_dwordx2 v[240:241], v254, s[18:19] offset:48
	global_load_dwordx2 v[242:243], v254, s[18:19] offset:64
	global_load_dwordx2 v[244:245], v254, s[18:19] offset:80
	global_load_dwordx2 v[246:247], v254, s[18:19] offset:96
	global_load_dwordx2 v[248:249], v254, s[18:19] offset:112
	s_cbranch_vccnz .Lao_nokv
	s_ashr_i32 s2, s48, 6
	s_ashr_i32 s3, s2, 31
	s_lshl_b32 s4, s48, 7
	s_and_b32 s6, s4, 0x1f00
	s_lshl_b64 s[2:3], s[2:3], 20
	s_add_u32 s4, s26, s2
	s_addc_u32 s5, s27, s3
	s_lshl_b32 s7, s6, 7
	s_add_u32 s4, s4, s7
	v_mov_b32_e32 v1, v196
	s_addc_u32 s5, s5, 0
	s_add_u32 s2, s46, s2
	v_ashrrev_i32_e32 v0, 3, v1
	v_ashrrev_i32_e32 v2, 5, v1
	v_lshlrev_b32_e32 v1, 4, v1
	s_addc_u32 s3, s47, s3
	s_lshl_b32 s6, s6, 1
	v_and_b32_e32 v4, 0x70, v1
	v_mov_b32_e32 v5, v145
	v_and_b32_e32 v6, 0x1f0, v1
	v_ashrrev_i32_e32 v1, 31, v0
	s_add_u32 s2, s2, s6
	v_lshl_add_u64 v[4:5], s[4:5], 0, v[4:5]
	v_lshlrev_b64 v[0:1], 7, v[0:1]
	s_addc_u32 s3, s3, 0
	v_mov_b32_e32 v7, v145
	v_lshl_add_u64 v[0:1], v[4:5], 0, v[0:1]
	v_ashrrev_i32_e32 v3, 31, v2
	v_lshl_add_u64 v[6:7], s[2:3], 0, v[6:7]
	v_lshlrev_b64 v[2:3], 14, v[2:3]
	v_add_co_u32_e32 v4, vcc, s10, v0
	v_lshl_add_u64 v[2:3], v[6:7], 0, v[2:3]
	s_nop 0
	v_addc_co_u32_e32 v5, vcc, 0, v1, vcc
	v_add_co_u32_e32 v6, vcc, s11, v2
	global_load_dwordx4 v[64:67], v[0:1], off
	global_load_dwordx4 v[68:71], v[2:3], off
	v_addc_co_u32_e32 v7, vcc, 0, v3, vcc
	global_load_dwordx4 v[72:75], v[4:5], off offset:-4096
	global_load_dwordx4 v[76:79], v[4:5], off
	v_add_co_u32_e32 v4, vcc, s14, v2
	s_nop 1
	v_addc_co_u32_e32 v5, vcc, 0, v3, vcc
	global_load_dwordx4 v[80:83], v[6:7], off
	global_load_dwordx4 v[84:87], v[4:5], off
	v_add_co_u32_e32 v4, vcc, s15, v0
	s_nop 1
	v_addc_co_u32_e32 v5, vcc, 0, v1, vcc
	v_add_co_u32_e32 v6, vcc, s33, v2
	global_load_dwordx4 v[88:91], v[4:5], off offset:-4096
	global_load_dwordx4 v[92:95], v[4:5], off
	v_addc_co_u32_e32 v7, vcc, 0, v3, vcc
	v_add_co_u32_e32 v4, vcc, s38, v2
	s_nop 1
	v_addc_co_u32_e32 v5, vcc, 0, v3, vcc
	global_load_dwordx4 v[96:99], v[6:7], off
	global_load_dwordx4 v[100:103], v[4:5], off
	v_add_co_u32_e32 v4, vcc, s40, v0
	s_nop 1
	v_addc_co_u32_e32 v5, vcc, 0, v1, vcc
	v_add_co_u32_e32 v6, vcc, s39, v2
	s_nop 1
	v_addc_co_u32_e32 v7, vcc, 0, v3, vcc
	global_load_dwordx4 v[104:107], v[4:5], off
	global_load_dwordx4 v[108:111], v[6:7], off
	v_add_co_u32_e32 v4, vcc, 0x6000, v0
	s_nop 1
	v_addc_co_u32_e32 v5, vcc, 0, v1, vcc
	v_add_co_u32_e32 v6, vcc, 0xc0000, v2
	s_nop 1
	v_addc_co_u32_e32 v7, vcc, 0, v3, vcc
	v_add_co_u32_e32 v0, vcc, 0x7000, v0
	global_load_dwordx4 v[112:115], v[4:5], off
	global_load_dwordx4 v[116:119], v[6:7], off
	v_addc_co_u32_e32 v1, vcc, 0, v1, vcc
	v_add_co_u32_e32 v2, vcc, 0xe0000, v2
	s_nop 1
	v_addc_co_u32_e32 v3, vcc, 0, v3, vcc
	global_load_dwordx4 v[120:123], v[0:1], off
	global_load_dwordx4 v[124:127], v[2:3], off
	s_lshl_b32 s2, s0, 7
	s_and_b32 s3, s2, 0x80
	v_xor_b32_e32 v251, s72, v153
	v_add_u32_e32 v1, s3, v251
	v_or_b32_e32 v0, v1, v152
.Lao_nokv:
	v_ashrrev_i32_e32 v1, 6, v1
	v_mov_b32_e32 v2, v196
	v_cmp_lt_i32_e32 vcc, -1, v1
	s_and_saveexec_b64 s[2:3], vcc
	s_xor_b64 s[2:3], exec, s[2:3]
	s_cbranch_execz .LBB0_1445
	v_bfe_u32 v4, v2, 5, 1
	v_lshlrev_b32_e32 v6, 2, v4
	v_sub_u32_e32 v158, v0, v6
	v_and_b32_e32 v0, 64, v154
	v_xor_b32_e32 v156, 32, v154
	v_add_u32_e32 v157, 64, v0
	v_cmp_lt_i32_e32 vcc, v156, v157
	v_lshrrev_b32_e32 v3, 5, v2
	v_and_b32_e32 v5, 31, v2
	v_bfe_u32 v2, v2, 1, 3
	v_cndmask_b32_e32 v0, v154, v156, vcc
	v_lshlrev_b32_e32 v159, 2, v0
	v_lshlrev_b32_e32 v0, 3, v4
	v_bitop3_b32 v3, v3, v2, 1 bitop3:0x6c
	v_lshlrev_b32_e32 v6, 7, v5
	v_bitop3_b32 v7, v4, v2, 2 bitop3:0x36
	v_bitop3_b32 v8, v4, v2, 4 bitop3:0x36
	v_bitop3_b32 v2, v4, v2, 6 bitop3:0x36
	v_mul_u32_u24_e32 v4, 0x208, v5
	s_add_i32 s4, 16, 0x8000
	v_add3_u32 v161, v4, v0, s4
	v_lshl_or_b32 v0, v2, 4, v6
	v_add_u32_e32 v162, 16, v0
	v_lshl_or_b32 v0, v8, 4, v6
	v_add_u32_e32 v163, 16, v0
	v_lshl_or_b32 v0, v7, 4, v6
	v_add_u32_e32 v164, 16, v0
	v_lshl_or_b32 v0, v3, 4, v6
	v_mov_b32_e32 v47, 0
	v_add_u32_e32 v160, 1, v1
	v_add_u32_e32 v165, 16, v0
	v_mov_b32_e32 v46, 0xf149f2ca
	s_mov_b32 s6, 59
	s_mov_b64 s[4:5], 0
	v_mov_b32_e32 v0, 0
	v_mov_b32_e32 v1, v47
	v_mov_b32_e32 v2, v47
	v_mov_b32_e32 v3, v47
	v_mov_b32_e32 v4, v47
	v_mov_b32_e32 v5, v47
	v_mov_b32_e32 v6, v47
	v_mov_b32_e32 v7, v47
	v_mov_b32_e32 v8, v47
	v_mov_b32_e32 v9, v47
	v_mov_b32_e32 v10, v47
	v_mov_b32_e32 v11, v47
	v_mov_b32_e32 v12, v47
	v_mov_b32_e32 v13, v47
	v_mov_b32_e32 v14, v47
	v_mov_b32_e32 v15, v47
	v_mov_b32_e32 v16, 0
	v_mov_b32_e32 v17, v47
	v_mov_b32_e32 v18, v47
	v_mov_b32_e32 v19, v47
	v_mov_b32_e32 v20, v47
	v_mov_b32_e32 v21, v47
	v_mov_b32_e32 v22, v47
	v_mov_b32_e32 v23, v47
	v_mov_b32_e32 v24, v47
	v_mov_b32_e32 v25, v47
	v_mov_b32_e32 v26, v47
	v_mov_b32_e32 v27, v47
	v_mov_b32_e32 v28, v47
	v_mov_b32_e32 v29, v47
	v_mov_b32_e32 v30, v47
	v_mov_b32_e32 v31, v47
.LBB0_1443:
	ds_read_b128 v[32:35], v165
	v_mov_b32_e32 v167, v46
	v_mov_b32_e32 v166, v47
	s_sub_i32 s7, s6, 59
	v_cmp_le_i32_e32 vcc, s7, v158
	v_add_u32_e32 v160, -1, v160
	s_waitcnt vmcnt(39) lgkmcnt(0)
	v_mfma_f32_32x32x16_bf16 v[48:63], v[32:35], v[128:131], 0
	ds_read_b128 v[32:35], v164
	ds_read_b128 v[168:171], v164 offset:4096
	v_add_u32_e32 v164, 0x2000, v164
	s_waitcnt vmcnt(38) lgkmcnt(1)
	v_mfma_f32_32x32x16_bf16 v[48:63], v[32:35], v[132:135], v[48:63]
	ds_read_b128 v[32:35], v163
	s_waitcnt vmcnt(37) lgkmcnt(0)
	v_mfma_f32_32x32x16_bf16 v[48:63], v[32:35], v[136:139], v[48:63]
	ds_read_b128 v[32:35], v162
	s_waitcnt vmcnt(36) lgkmcnt(0)
	v_mfma_f32_32x32x16_bf16 v[48:63], v[32:35], v[140:143], v[48:63]
	ds_read_b128 v[32:35], v165 offset:4096
	v_add_u32_e32 v165, 0x2000, v165
	s_waitcnt lgkmcnt(0)
	v_mfma_f32_32x32x16_bf16 v[32:47], v[32:35], v[128:131], 0
	v_mfma_f32_32x32x16_bf16 v[32:47], v[168:171], v[132:135], v[32:47]
	ds_read_b128 v[168:171], v163 offset:4096
	v_add_u32_e32 v163, 0x2000, v163
	s_waitcnt lgkmcnt(0)
	v_mfma_f32_32x32x16_bf16 v[32:47], v[168:171], v[136:139], v[32:47]
	ds_read_b128 v[168:171], v162 offset:4096
	v_add_u32_e32 v162, 0x2000, v162
	s_waitcnt lgkmcnt(0)
	v_mfma_f32_32x32x16_bf16 v[32:47], v[168:171], v[140:143], v[32:47]
	v_cndmask_b32_e32 v168, v155, v48, vcc
	v_cmp_lt_i32_e32 vcc, s7, v158
	s_sub_i32 s7, s6, 57
	s_nop 0
	v_cndmask_b32_e32 v48, v168, v48, vcc
	v_cndmask_b32_e32 v49, v155, v49, vcc
	v_cmp_le_i32_e32 vcc, s7, v158
	s_sub_i32 s7, s6, 56
	v_max3_f32 v168, v168, s44, v49
	v_cndmask_b32_e32 v50, v155, v50, vcc
	v_cmp_le_i32_e32 vcc, s7, v158
	s_sub_i32 s7, s6, 51
	s_nop 0
	v_cndmask_b32_e32 v51, v155, v51, vcc
	v_cmp_le_i32_e32 vcc, s7, v158
	s_sub_i32 s7, s6, 50
	v_max3_f32 v168, v168, v50, v51
	v_cndmask_b32_e32 v52, v155, v52, vcc
	v_cmp_le_i32_e32 vcc, s7, v158
	s_sub_i32 s7, s6, 49
	s_nop 0
	v_cndmask_b32_e32 v53, v155, v53, vcc
	v_cmp_le_i32_e32 vcc, s7, v158
	s_sub_i32 s7, s6, 48
	v_max3_f32 v168, v168, v52, v53
	v_cndmask_b32_e32 v54, v155, v54, vcc
	v_cmp_le_i32_e32 vcc, s7, v158
	s_sub_i32 s7, s6, 43
	s_nop 0
	v_cndmask_b32_e32 v55, v155, v55, vcc
	v_cmp_le_i32_e32 vcc, s7, v158
	s_sub_i32 s7, s6, 42
	v_max3_f32 v168, v168, v54, v55
	v_cndmask_b32_e32 v56, v155, v56, vcc
	v_cmp_le_i32_e32 vcc, s7, v158
	s_sub_i32 s7, s6, 41
	s_nop 0
	v_cndmask_b32_e32 v57, v155, v57, vcc
	v_cmp_le_i32_e32 vcc, s7, v158
	s_sub_i32 s7, s6, 40
	v_max3_f32 v168, v168, v56, v57
	v_cndmask_b32_e32 v58, v155, v58, vcc
	v_cmp_le_i32_e32 vcc, s7, v158
	s_sub_i32 s7, s6, 35
	s_nop 0
	v_cndmask_b32_e32 v59, v155, v59, vcc
	v_cmp_le_i32_e32 vcc, s7, v158
	s_sub_i32 s7, s6, 34
	v_max3_f32 v168, v168, v58, v59
	v_cndmask_b32_e32 v60, v155, v60, vcc
	v_cmp_le_i32_e32 vcc, s7, v158
	s_sub_i32 s7, s6, 33
	s_nop 0
	v_cndmask_b32_e32 v61, v155, v61, vcc
	v_cmp_le_i32_e32 vcc, s7, v158
	s_sub_i32 s7, s6, 32
	v_max3_f32 v168, v168, v60, v61
	v_cndmask_b32_e32 v62, v155, v62, vcc
	v_cmp_le_i32_e32 vcc, s7, v158
	s_sub_i32 s7, s6, 27
	s_nop 0
	v_cndmask_b32_e32 v63, v155, v63, vcc
	v_cmp_le_i32_e32 vcc, s7, v158
	s_sub_i32 s7, s6, 26
	v_max3_f32 v168, v168, v62, v63
	v_cndmask_b32_e32 v32, v155, v32, vcc
	v_cmp_le_i32_e32 vcc, s7, v158
	s_sub_i32 s7, s6, 25
	s_nop 0
	v_cndmask_b32_e32 v33, v155, v33, vcc
	v_cmp_le_i32_e32 vcc, s7, v158
	s_sub_i32 s7, s6, 24
	v_max3_f32 v168, v168, v32, v33
	v_cndmask_b32_e32 v34, v155, v34, vcc
	v_cmp_le_i32_e32 vcc, s7, v158
	s_sub_i32 s7, s6, 19
	s_nop 0
	v_cndmask_b32_e32 v35, v155, v35, vcc
	v_cmp_le_i32_e32 vcc, s7, v158
	s_sub_i32 s7, s6, 18
	v_max3_f32 v168, v168, v34, v35
	v_cndmask_b32_e32 v169, v155, v36, vcc
	v_cmp_le_i32_e32 vcc, s7, v158
	s_sub_i32 s7, s6, 17
	s_nop 0
	v_cndmask_b32_e32 v37, v155, v37, vcc
	v_cmp_le_i32_e32 vcc, s7, v158
	s_add_i32 s7, s6, -16
	v_max3_f32 v36, v168, v169, v37
	v_cndmask_b32_e32 v38, v155, v38, vcc
	v_cmp_le_i32_e32 vcc, s7, v158
	s_add_i32 s7, s6, -11
	s_nop 0
	v_cndmask_b32_e32 v39, v155, v39, vcc
	v_cmp_le_i32_e32 vcc, s7, v158
	s_add_i32 s7, s6, -10
	v_max3_f32 v36, v36, v38, v39
	v_cndmask_b32_e32 v40, v155, v40, vcc
	v_cmp_le_i32_e32 vcc, s7, v158
	s_add_i32 s7, s6, -9
	s_nop 0
	v_cndmask_b32_e32 v41, v155, v41, vcc
	v_cmp_le_i32_e32 vcc, s7, v158
	s_add_i32 s7, s6, -8
	v_max3_f32 v36, v36, v40, v41
	v_cndmask_b32_e32 v42, v155, v42, vcc
	v_cmp_le_i32_e32 vcc, s7, v158
	s_add_i32 s7, s6, -3
	s_nop 0
	v_cndmask_b32_e32 v43, v155, v43, vcc
	v_cmp_le_i32_e32 vcc, s7, v158
	s_add_i32 s7, s6, -2
	v_max3_f32 v36, v36, v42, v43
	v_cndmask_b32_e32 v44, v155, v44, vcc
	v_cmp_le_i32_e32 vcc, s7, v158
	s_add_i32 s7, s6, -1
	s_nop 0
	v_cndmask_b32_e32 v168, v155, v45, vcc
	v_cmp_le_i32_e32 vcc, s7, v158
	v_max3_f32 v36, v36, v44, v168
	s_nop 0
	v_cndmask_b32_e32 v170, v155, v46, vcc
	v_cmp_le_i32_e32 vcc, s6, v158
	s_add_i32 s6, s6, 64
	s_nop 0
	v_cndmask_b32_e32 v47, v155, v47, vcc
	v_max3_f32 v36, v36, v170, v47
	ds_bpermute_b32 v45, v159, v36
	v_cmp_eq_u32_e32 vcc, 0, v160
	s_or_b64 s[4:5], vcc, s[4:5]
	s_waitcnt lgkmcnt(0)
	v_max3_f32 v46, v167, v36, v45
	v_sub_f32_e32 v45, v48, v46
	v_sub_f32_e32 v36, v167, v46
	v_exp_f32_e32 v167, v45
	v_sub_f32_e32 v48, v49, v46
	v_exp_f32_e32 v171, v48
	v_sub_f32_e32 v48, v50, v46
	v_exp_f32_e32 v172, v48
	v_sub_f32_e32 v48, v51, v46
	v_exp_f32_e32 v173, v48
	v_sub_f32_e32 v48, v52, v46
	v_add_f32_e32 v45, 0, v167
	v_exp_f32_e32 v174, v48
	v_sub_f32_e32 v48, v53, v46
	v_add_f32_e32 v45, v171, v45
	v_exp_f32_e32 v175, v48
	v_sub_f32_e32 v48, v54, v46
	v_add_f32_e32 v45, v172, v45
	v_exp_f32_e32 v176, v48
	v_sub_f32_e32 v48, v55, v46
	v_add_f32_e32 v45, v173, v45
	v_exp_f32_e32 v177, v48
	v_add_f32_e32 v45, v174, v45
	v_add_f32_e32 v45, v175, v45
	v_add_f32_e32 v45, v176, v45
	v_add_f32_e32 v48, v177, v45
	v_sub_f32_e32 v45, v56, v46
	v_exp_f32_e32 v45, v45
	v_sub_f32_e32 v55, v63, v46
	v_exp_f32_e32 v55, v55
	v_sub_f32_e32 v32, v32, v46
	v_add_f32_e32 v49, v45, v48
	v_sub_f32_e32 v48, v57, v46
	v_exp_f32_e32 v48, v48
	v_exp_f32_e32 v36, v36
	v_add_f32_e32 v50, v48, v49
	v_sub_f32_e32 v49, v58, v46
	v_exp_f32_e32 v49, v49
	s_nop 0
	v_add_f32_e32 v51, v49, v50
	v_sub_f32_e32 v50, v59, v46
	v_exp_f32_e32 v50, v50
	s_nop 0
	v_add_f32_e32 v52, v50, v51
	v_sub_f32_e32 v51, v60, v46
	v_exp_f32_e32 v51, v51
	s_nop 0
	v_add_f32_e32 v53, v51, v52
	v_sub_f32_e32 v52, v61, v46
	v_exp_f32_e32 v52, v52
	s_nop 0
	v_add_f32_e32 v54, v52, v53
	v_sub_f32_e32 v53, v62, v46
	v_exp_f32_e32 v53, v53
	s_nop 0
	v_add_f32_e32 v54, v53, v54
	v_add_f32_e32 v63, v55, v54
	v_exp_f32_e32 v54, v32
	v_sub_f32_e32 v32, v33, v46
	v_exp_f32_e32 v56, v32
	v_sub_f32_e32 v32, v34, v46
	v_exp_f32_e32 v57, v32
	v_sub_f32_e32 v32, v35, v46
	v_exp_f32_e32 v58, v32
	v_sub_f32_e32 v32, v169, v46
	v_exp_f32_e32 v59, v32
	v_sub_f32_e32 v32, v37, v46
	v_exp_f32_e32 v60, v32
	v_sub_f32_e32 v32, v38, v46
	v_exp_f32_e32 v61, v32
	v_sub_f32_e32 v32, v39, v46
	v_exp_f32_e32 v62, v32
	v_sub_f32_e32 v32, v40, v46
	v_exp_f32_e32 v37, v32
	v_sub_f32_e32 v32, v41, v46
	v_exp_f32_e32 v38, v32
	v_sub_f32_e32 v32, v42, v46
	v_exp_f32_e32 v39, v32
	v_sub_f32_e32 v32, v43, v46
	v_exp_f32_e32 v40, v32
	v_sub_f32_e32 v32, v44, v46
	v_exp_f32_e32 v41, v32
	v_sub_f32_e32 v32, v168, v46
	v_exp_f32_e32 v42, v32
	v_sub_f32_e32 v32, v170, v46
	v_exp_f32_e32 v43, v32
	v_sub_f32_e32 v32, v47, v46
	v_exp_f32_e32 v44, v32
	v_add_f32_e32 v32, v54, v63
	v_add_f32_e32 v32, v56, v32
	v_add_f32_e32 v32, v57, v32
	v_add_f32_e32 v32, v58, v32
	v_add_f32_e32 v32, v59, v32
	v_add_f32_e32 v32, v60, v32
	v_add_f32_e32 v32, v61, v32
	v_add_f32_e32 v32, v62, v32
	v_add_f32_e32 v32, v37, v32
	v_add_f32_e32 v32, v38, v32
	v_add_f32_e32 v32, v39, v32
	v_add_f32_e32 v32, v40, v32
	v_add_f32_e32 v32, v41, v32
	v_add_f32_e32 v32, v42, v32
	v_add_f32_e32 v32, v43, v32
	v_add_f32_e32 v47, v44, v32
	v_cvt_pk_bf16_f32 v32, v167, v171
	v_cvt_pk_bf16_f32 v33, v172, v173
	v_cvt_pk_bf16_f32 v34, v174, v175
	ds_read2_b64 v[168:171], v161 offset1:2
	ds_read2_b64 v[172:175], v161 offset0:4 offset1:6
	v_pk_mul_f32 v[30:31], v[30:31], v[36:37] op_sel_hi:[1,0]
	v_pk_mul_f32 v[28:29], v[28:29], v[36:37] op_sel_hi:[1,0]
	v_pk_mul_f32 v[26:27], v[26:27], v[36:37] op_sel_hi:[1,0]
	v_pk_mul_f32 v[24:25], v[24:25], v[36:37] op_sel_hi:[1,0]
	v_pk_mul_f32 v[22:23], v[22:23], v[36:37] op_sel_hi:[1,0]
	v_pk_mul_f32 v[20:21], v[20:21], v[36:37] op_sel_hi:[1,0]
	v_pk_mul_f32 v[18:19], v[18:19], v[36:37] op_sel_hi:[1,0]
	v_pk_mul_f32 v[16:17], v[16:17], v[36:37] op_sel_hi:[1,0]
	v_cvt_pk_bf16_f32 v35, v176, v177
	v_add_u32_e32 v63, 0x4000, v161
	v_pk_mul_f32 v[14:15], v[14:15], v[36:37] op_sel_hi:[1,0]
	s_waitcnt lgkmcnt(1)
	v_mfma_f32_32x32x16_bf16 v[16:31], v[168:171], v[32:35], v[16:31]
	ds_read2_b64 v[168:171], v63 offset0:32 offset1:34
	v_mul_f32_e64 v12, v12, v36
	v_mul_f32_e64 v13, v13, v36
	v_mul_f32_e64 v10, v10, v36
	v_mul_f32_e64 v11, v11, v36
	v_pk_mul_f32 v[8:9], v[8:9], v[36:37] op_sel_hi:[1,0]
	v_pk_mul_f32 v[6:7], v[6:7], v[36:37] op_sel_hi:[1,0]
	v_pk_mul_f32 v[4:5], v[4:5], v[36:37] op_sel_hi:[1,0]
	v_pk_mul_f32 v[2:3], v[2:3], v[36:37] op_sel_hi:[1,0]
	v_pk_mul_f32 v[0:1], v[0:1], v[36:37] op_sel_hi:[1,0]
	v_fmac_f32_e32 v47, v166, v36
	s_waitcnt lgkmcnt(0)
	v_mfma_f32_32x32x16_bf16 v[0:15], v[168:171], v[32:35], v[0:15]
	v_cvt_pk_bf16_f32 v32, v45, v48
	v_cvt_pk_bf16_f32 v33, v49, v50
	v_cvt_pk_bf16_f32 v34, v51, v52
	ds_read2_b64 v[48:51], v63 offset0:36 offset1:38
	v_cvt_pk_bf16_f32 v35, v53, v55
	s_waitcnt lgkmcnt(0)
	s_nop 0
	v_mfma_f32_32x32x16_bf16 v[0:15], v[48:51], v[32:35], v[0:15]
	ds_read2_b64 v[48:51], v161 offset0:8 offset1:10
	v_mfma_f32_32x32x16_bf16 v[16:31], v[172:175], v[32:35], v[16:31]
	v_cvt_pk_bf16_f32 v32, v54, v56
	v_cvt_pk_bf16_f32 v33, v57, v58
	v_cvt_pk_bf16_f32 v34, v59, v60
	v_cvt_pk_bf16_f32 v35, v61, v62
	s_waitcnt lgkmcnt(0)
	s_nop 0
	v_mfma_f32_32x32x16_bf16 v[16:31], v[48:51], v[32:35], v[16:31]
	ds_read2_b64 v[48:51], v63 offset0:40 offset1:42
	s_waitcnt lgkmcnt(0)
	v_mfma_f32_32x32x16_bf16 v[0:15], v[48:51], v[32:35], v[0:15]
	v_cvt_pk_bf16_f32 v32, v37, v38
	v_cvt_pk_bf16_f32 v33, v39, v40
	v_cvt_pk_bf16_f32 v34, v41, v42
	ds_read2_b64 v[38:41], v161 offset0:12 offset1:14
	v_cvt_pk_bf16_f32 v35, v43, v44
	v_add_u32_e32 v161, 0x80, v161
	s_waitcnt lgkmcnt(0)
	v_mfma_f32_32x32x16_bf16 v[16:31], v[38:41], v[32:35], v[16:31]
	ds_read2_b64 v[38:41], v63 offset0:44 offset1:46
	s_waitcnt lgkmcnt(0)
	v_mfma_f32_32x32x16_bf16 v[0:15], v[38:41], v[32:35], v[0:15]
	s_andn2_b64 exec, exec, s[4:5]
	s_cbranch_execnz .LBB0_1443
	s_or_b64 exec, exec, s[4:5]

.LBB0_1447:
	s_or_b64 exec, exec, s[2:3]
	s_lshl_b64 s[2:3], s[34:35], 16
	s_add_u32 s2, s22, s2
	v_lshl_add_u64 v[34:35], v[150:151], 2, s[8:9]
	s_addc_u32 s3, s23, s3
	s_waitcnt vmcnt(32)
	v_mov_b32_e32 v40, v197
	v_lshl_add_u64 v[34:35], v[148:149], 3, s[2:3]
	v_add_co_u32_e32 v36, vcc, s45, v34
	s_nop 0
	v_and_b32_e32 v41, 0xe000, v40
	v_addc_co_u32_e32 v37, vcc, 0, v35, vcc
	v_add_co_u32_e32 v38, vcc, 0x800000, v34
	v_cmp_eq_u32_e64 s[6:7], 0, v41
	s_nop 0
	v_addc_co_u32_e32 v39, vcc, 0, v35, vcc
	v_mov_b32_e32 v36, v180
	v_mov_b32_e32 v37, v181
	s_nop 0
	v_mov_b32_e32 v44, v182
	v_mov_b32_e32 v45, v183
	s_nop 0
	v_mov_b32_e32 v38, v178
	v_cmp_lt_i32_e32 vcc, v156, v157
	v_max_f32_e32 v39, v46, v46
	s_nop 0
	v_cndmask_b32_e64 v41, v155, v36, s[6:7]
	v_cndmask_b32_e32 v32, v32, v156, vcc
	v_lshlrev_b32_e32 v32, 2, v32
	ds_bpermute_b32 v33, v32, v47
	v_and_b32_e32 v32, 0xe0, v40
	v_cmp_eq_u32_e64 s[4:5], 0, v32
	v_and_b32_e32 v40, 0xe00000, v40
	v_cmp_eq_u32_e64 s[2:3], 0, v40
	s_nop 0
	v_cndmask_b32_e64 v32, v155, v38, s[4:5]
	v_max_f32_e32 v32, v32, v32
	v_cndmask_b32_e64 v40, v155, v44, s[2:3]
	v_max_f32_e32 v32, v39, v32
	v_max3_f32 v48, v32, v41, v40
	v_mov_b32_e32 v32, 0
	s_and_saveexec_b64 s[36:37], s[4:5]
	s_cbranch_execz .LBB0_1438
	v_mov_b32_e32 v32, v179
	v_sub_f32_e32 v34, v38, v48
	v_exp_f32_e32 v34, v34
	s_nop 0
	v_mul_f32_e32 v32, v34, v32
	s_branch .LBB0_1438

.LBB0_1501:
	s_or_b64 exec, exec, s[0:1]
	s_add_u32 s0, s56, 0x1300000
	s_addc_u32 s1, s57, 0
	v_mov_b32_e32 v0, v196
	s_andn2_b64 vcc, exec, s[24:25]
	s_waitcnt lgkmcnt(0)
	s_barrier
	s_cbranch_vccnz .LBB0_1514
	s_lshr_b32 s2, s12, 6
	s_and_b32 s2, s2, 24
	s_bfe_u32 s3, s12, 0x30003
	s_or_b32 s2, s2, s3
	s_or_b32 s6, s2, s96
	v_mov_b32_e32 v1, v196
	s_lshl_b32 s8, s6, 7
	s_bfe_u32 s7, s12, 0x30006
	v_ashrrev_i32_e32 v4, 3, v1
	v_add_u32_e32 v2, s8, v4
	s_lshl_b32 s9, s7, 7
	v_ashrrev_i32_e32 v3, 31, v2
	v_lshlrev_b64 v[2:3], 11, v[2:3]
	v_lshlrev_b32_e32 v1, 4, v1
	v_add_u32_e32 v4, s9, v4
	v_lshl_add_u64 v[2:3], s[18:19], 0, v[2:3]
	v_and_b32_e32 v128, 0x70, v1
	v_mov_b32_e32 v129, 0
	v_ashrrev_i32_e32 v5, 31, v4
	v_lshl_add_u64 v[2:3], v[2:3], 0, v[128:129]
	v_lshlrev_b64 v[4:5], 11, v[4:5]
	s_mov_b32 s10, 0x10000
	v_lshl_add_u64 v[4:5], s[0:1], 0, v[4:5]
	v_add_co_u32_e32 v6, vcc, s10, v2
	v_lshl_add_u64 v[4:5], v[4:5], 0, v[128:129]
	s_nop 0
	v_addc_co_u32_e32 v7, vcc, 0, v3, vcc
	v_add_co_u32_e32 v8, vcc, s10, v4
	s_mov_b32 s11, 0x20000
	s_nop 0
	v_addc_co_u32_e32 v9, vcc, 0, v5, vcc
	v_add_co_u32_e32 v10, vcc, s11, v2
	s_mov_b32 s2, 0x30000
	s_nop 0
	v_addc_co_u32_e32 v11, vcc, 0, v3, vcc
	v_add_co_u32_e32 v12, vcc, s11, v4
	v_ashrrev_i32_e32 v1, 1, v0
	s_nop 0
	v_addc_co_u32_e32 v13, vcc, 0, v5, vcc
	v_add_co_u32_e32 v14, vcc, s2, v2
	v_and_b32_e32 v166, 0xffffffc0, v1
	s_nop 0
	v_addc_co_u32_e32 v15, vcc, 0, v3, vcc
	v_add_co_u32_e32 v16, vcc, s2, v4
	v_lshrrev_b32_e32 v1, 3, v0
	s_nop 0
	v_addc_co_u32_e32 v17, vcc, 0, v5, vcc
	s_waitcnt vmcnt(0)
	global_load_dwordx4 v[64:67], v[2:3], off
	global_load_dwordx4 v[68:71], v[2:3], off offset:128
	global_load_dwordx4 v[72:75], v[4:5], off
	global_load_dwordx4 v[76:79], v[4:5], off offset:128
	global_load_dwordx4 v[80:83], v[6:7], off
	global_load_dwordx4 v[84:87], v[6:7], off offset:128
	global_load_dwordx4 v[88:91], v[8:9], off
	global_load_dwordx4 v[92:95], v[8:9], off offset:128
	global_load_dwordx4 v[96:99], v[10:11], off
	global_load_dwordx4 v[100:103], v[10:11], off offset:128
	global_load_dwordx4 v[104:107], v[12:13], off
	global_load_dwordx4 v[108:111], v[12:13], off offset:128
	global_load_dwordx4 v[112:115], v[14:15], off
	global_load_dwordx4 v[116:119], v[14:15], off offset:128
	global_load_dwordx4 v[120:123], v[16:17], off
	global_load_dwordx4 v[124:127], v[16:17], off offset:128
	s_movk_i32 s12, 0x70
	v_and_b32_e32 v167, 4, v1
	v_and_b32_e32 v168, 0x5f, v0
	s_mov_b32 s13, 0x1ffffc0
	s_mov_b64 s[2:3], 0x100
	s_branch .LBB0_1504

.LBB0_1506:
	s_cmp_lt_u32 s16, 14
	s_cselect_b64 s[6:7], -1, 0
	s_cmp_gt_u32 s16, 13
	s_cselect_b64 s[4:5], -1, 0
	s_and_b64 vcc, exec, s[4:5]
	v_lshl_add_u64 v[136:137], v[132:133], 0, v[128:129]
	v_lshl_add_u64 v[134:135], v[130:131], 0, v[128:129]
	s_cbranch_vccnz .LBB0_1508
	s_waitcnt vmcnt(8)
	v_add_co_u32_e32 v80, vcc, 0x10000, v136
	global_load_dwordx4 v[64:67], v[136:137], off offset:256
	global_load_dwordx4 v[72:75], v[134:135], off offset:256
	v_addc_co_u32_e32 v81, vcc, 0, v137, vcc
	v_add_co_u32_e32 v88, vcc, 0x10000, v134
	global_load_dwordx4 v[80:83], v[80:81], off offset:256
	s_nop 0
	v_addc_co_u32_e32 v89, vcc, 0, v135, vcc
	v_add_co_u32_e32 v96, vcc, 0x20000, v136
	global_load_dwordx4 v[88:91], v[88:89], off offset:256
	s_nop 0
	v_addc_co_u32_e32 v97, vcc, 0, v137, vcc
	v_add_co_u32_e32 v104, vcc, 0x20000, v134
	global_load_dwordx4 v[96:99], v[96:97], off offset:256
	s_nop 0
	v_addc_co_u32_e32 v105, vcc, 0, v135, vcc
	v_add_co_u32_e32 v112, vcc, 0x30000, v136
	global_load_dwordx4 v[104:107], v[104:105], off offset:256
	s_nop 0
	v_addc_co_u32_e32 v113, vcc, 0, v137, vcc
	v_add_co_u32_e32 v120, vcc, 0x30000, v134
	global_load_dwordx4 v[112:115], v[112:113], off offset:256
	s_nop 0
	v_addc_co_u32_e32 v121, vcc, 0, v135, vcc
	global_load_dwordx4 v[120:123], v[120:121], off offset:256
.LBB0_1508:
	v_add_u32_e32 v145, v139, v140
	ds_read_b128 v[148:151], v145
	v_add_u32_e32 v146, v139, v141
	ds_read_b128 v[152:155], v146 offset:16384
	ds_read_b128 v[156:159], v145 offset:4096
	ds_read_b128 v[160:163], v146 offset:20480
	v_add_u32_e32 v147, v142, v140
	s_waitcnt lgkmcnt(0)
	v_mfma_f32_32x32x16_bf16 v[16:31], v[156:159], v[152:155], v[16:31]
	s_cmp_gt_u32 s16, 12
	v_mfma_f32_32x32x16_bf16 v[48:63], v[148:151], v[152:155], v[48:63]
	v_mfma_f32_32x32x16_bf16 v[32:47], v[148:151], v[160:163], v[32:47]
	ds_read_b128 v[150:153], v147
	v_add_u32_e32 v148, v142, v141
	v_add_u32_e32 v149, v143, v140
	v_mfma_f32_32x32x16_bf16 v[0:15], v[156:159], v[160:163], v[0:15]
	ds_read_b128 v[154:157], v148 offset:16384
	ds_read_b128 v[158:161], v147 offset:4096
	ds_read_b128 v[162:165], v148 offset:20480
	s_waitcnt lgkmcnt(0)
	v_mfma_f32_32x32x16_bf16 v[48:63], v[150:153], v[154:157], v[48:63]
	v_mfma_f32_32x32x16_bf16 v[32:47], v[150:153], v[162:165], v[32:47]
	v_add_u32_e32 v150, v143, v141
	v_add_u32_e32 v151, v144, v140
	v_mfma_f32_32x32x16_bf16 v[16:31], v[158:161], v[154:157], v[16:31]
	ds_read_b128 v[152:155], v149
	v_mfma_f32_32x32x16_bf16 v[0:15], v[158:161], v[162:165], v[0:15]
	ds_read_b128 v[156:159], v150 offset:16384
	ds_read_b128 v[160:163], v149 offset:4096
	ds_read_b128 v[170:173], v150 offset:20480
	s_waitcnt lgkmcnt(0)
	v_mfma_f32_32x32x16_bf16 v[48:63], v[152:155], v[156:159], v[48:63]
	v_mfma_f32_32x32x16_bf16 v[32:47], v[152:155], v[170:173], v[32:47]
	v_add_u32_e32 v152, v144, v141
	v_mfma_f32_32x32x16_bf16 v[16:31], v[160:163], v[156:159], v[16:31]
	ds_read_b128 v[154:157], v151
	v_mfma_f32_32x32x16_bf16 v[0:15], v[160:163], v[170:173], v[0:15]
	ds_read_b128 v[158:161], v152 offset:16384
	ds_read_b128 v[162:165], v151 offset:4096
	ds_read_b128 v[170:173], v152 offset:20480
	s_mov_b64 vcc, s[4:5]
	s_cbranch_vccnz .Lgr2_cw0
	s_waitcnt vmcnt(8)
	s_branch .Lgr2_cw1

.Lgr2_cw1:
	ds_write_b128 v138, v[68:71] offset:32768
	ds_write_b128 v138, v[76:79] offset:49152
	ds_write_b128 v138, v[84:87] offset:36864
	ds_write_b128 v138, v[92:95] offset:53248
	ds_write_b128 v138, v[100:103] offset:40960
	ds_write_b128 v138, v[108:111] offset:57344
	ds_write_b128 v138, v[116:119] offset:45056
	ds_write_b128 v138, v[124:127] offset:61440
	s_waitcnt lgkmcnt(0)
	s_barrier
	v_mfma_f32_32x32x16_bf16 v[48:63], v[154:157], v[158:161], v[48:63]
	v_mfma_f32_32x32x16_bf16 v[32:47], v[154:157], v[170:173], v[32:47]
	v_mfma_f32_32x32x16_bf16 v[16:31], v[162:165], v[158:161], v[16:31]
	v_mfma_f32_32x32x16_bf16 v[0:15], v[162:165], v[170:173], v[0:15]
	s_cbranch_scc1 .LBB0_1510
	v_add_co_u32_e32 v84, vcc, 0x10000, v136
	global_load_dwordx4 v[68:71], v[136:137], off offset:384
	global_load_dwordx4 v[76:79], v[134:135], off offset:384
	v_addc_co_u32_e32 v85, vcc, 0, v137, vcc
	v_add_co_u32_e32 v92, vcc, 0x10000, v134
	global_load_dwordx4 v[84:87], v[84:85], off offset:384
	s_nop 0
	v_addc_co_u32_e32 v93, vcc, 0, v135, vcc
	v_add_co_u32_e32 v100, vcc, 0x20000, v136
	global_load_dwordx4 v[92:95], v[92:93], off offset:384
	s_nop 0
	v_addc_co_u32_e32 v101, vcc, 0, v137, vcc
	v_add_co_u32_e32 v108, vcc, 0x20000, v134
	global_load_dwordx4 v[100:103], v[100:101], off offset:384
	s_nop 0
	v_addc_co_u32_e32 v109, vcc, 0, v135, vcc
	v_add_co_u32_e32 v116, vcc, 0x30000, v136
	global_load_dwordx4 v[108:111], v[108:109], off offset:384
	s_nop 0
	v_addc_co_u32_e32 v117, vcc, 0, v137, vcc
	v_add_co_u32_e32 v124, vcc, 0x30000, v134
	global_load_dwordx4 v[116:119], v[116:117], off offset:384
	s_nop 0
	v_addc_co_u32_e32 v125, vcc, 0, v135, vcc
	global_load_dwordx4 v[124:127], v[124:125], off offset:384
.LBB0_1510:
	ds_read_b128 v[134:137], v145 offset:32768
	ds_read_b128 v[154:157], v146 offset:49152
	ds_read_b128 v[158:161], v145 offset:36864
	ds_read_b128 v[162:165], v146 offset:53248
	s_andn2_b64 vcc, exec, s[6:7]
	s_waitcnt lgkmcnt(0)
	v_mfma_f32_32x32x16_bf16 v[48:63], v[134:137], v[154:157], v[48:63]
	v_mfma_f32_32x32x16_bf16 v[32:47], v[134:137], v[162:165], v[32:47]
	v_mfma_f32_32x32x16_bf16 v[16:31], v[158:161], v[154:157], v[16:31]
	v_mfma_f32_32x32x16_bf16 v[0:15], v[158:161], v[162:165], v[0:15]
	ds_read_b128 v[134:137], v147 offset:32768
	ds_read_b128 v[154:157], v148 offset:49152
	ds_read_b128 v[158:161], v147 offset:36864
	ds_read_b128 v[162:165], v148 offset:53248
	s_waitcnt lgkmcnt(0)
	v_mfma_f32_32x32x16_bf16 v[48:63], v[134:137], v[154:157], v[48:63]
	v_mfma_f32_32x32x16_bf16 v[32:47], v[134:137], v[162:165], v[32:47]
	v_mfma_f32_32x32x16_bf16 v[16:31], v[158:161], v[154:157], v[16:31]
	v_mfma_f32_32x32x16_bf16 v[0:15], v[158:161], v[162:165], v[0:15]
	ds_read_b128 v[134:137], v149 offset:32768
	ds_read_b128 v[154:157], v150 offset:49152
	ds_read_b128 v[146:149], v149 offset:36864
	ds_read_b128 v[158:161], v150 offset:53248
	s_waitcnt lgkmcnt(0)
	v_mfma_f32_32x32x16_bf16 v[48:63], v[134:137], v[154:157], v[48:63]
	v_mfma_f32_32x32x16_bf16 v[32:47], v[134:137], v[158:161], v[32:47]
	v_mfma_f32_32x32x16_bf16 v[16:31], v[146:149], v[154:157], v[16:31]
	v_mfma_f32_32x32x16_bf16 v[0:15], v[146:149], v[158:161], v[0:15]
	ds_read_b128 v[134:137], v151 offset:32768
	ds_read_b128 v[146:149], v152 offset:49152
	ds_read_b128 v[154:157], v151 offset:36864
	ds_read_b128 v[150:153], v152 offset:53248
	s_waitcnt lgkmcnt(0)
	v_mfma_f32_32x32x16_bf16 v[48:63], v[134:137], v[146:149], v[48:63]
	v_mfma_f32_32x32x16_bf16 v[32:47], v[134:137], v[150:153], v[32:47]
	v_mfma_f32_32x32x16_bf16 v[16:31], v[154:157], v[146:149], v[16:31]
	v_mfma_f32_32x32x16_bf16 v[0:15], v[154:157], v[150:153], v[0:15]
	s_cbranch_vccnz .LBB0_1505
	s_waitcnt vmcnt(8)
	ds_write_b128 v138, v[64:67]
	ds_write_b128 v138, v[72:75] offset:16384
	ds_write_b128 v138, v[80:83] offset:4096
	ds_write_b128 v138, v[88:91] offset:20480
	ds_write_b128 v138, v[96:99] offset:8192
	ds_write_b128 v138, v[104:107] offset:24576
	ds_write_b128 v138, v[112:115] offset:12288
	ds_write_b128 v138, v[120:123] offset:28672
	s_branch .LBB0_1505
.LBB0_1512:
	s_add_i32 s95, s95, s94
	s_cmpk_gt_u32 s95, 0xff
	s_cselect_b64 s[4:5], -1, 0
	s_lshr_b32 s6, s95, 3
	s_and_b32 s6, s6, 24
	s_and_b32 s7, s95, 7
	s_or_b32 s6, s7, s6
	s_or_b32 s6, s6, s96
	s_bfe_u32 s7, s95, 0x30003
	s_and_b64 vcc, exec, s[4:5]
	s_cbranch_vccnz .LBB0_1503
	s_waitcnt vmcnt(0)
	v_mov_b32_e32 v66, v196
	s_lshl_b32 s8, s6, 7
	s_lshl_b32 s9, s7, 7
	v_ashrrev_i32_e32 v67, 3, v66
	v_add_u32_e32 v64, s8, v67
	v_ashrrev_i32_e32 v65, 31, v64
	v_lshlrev_b64 v[64:65], 11, v[64:65]
	v_lshlrev_b32_e32 v66, 4, v66
	v_lshl_add_u64 v[64:65], s[18:19], 0, v[64:65]
	v_and_b32_e32 v128, 0x70, v66
	v_lshl_add_u64 v[104:105], v[64:65], 0, v[128:129]
	v_add_u32_e32 v64, s9, v67
	v_ashrrev_i32_e32 v65, 31, v64
	v_lshlrev_b64 v[64:65], 11, v[64:65]
	v_lshl_add_u64 v[64:65], s[0:1], 0, v[64:65]
	v_add_co_u32_e32 v108, vcc, s10, v104
	v_lshl_add_u64 v[106:107], v[64:65], 0, v[128:129]
	s_nop 0
	v_addc_co_u32_e32 v109, vcc, 0, v105, vcc
	v_add_co_u32_e32 v110, vcc, s10, v106
	s_nop 1
	v_addc_co_u32_e32 v111, vcc, 0, v107, vcc
	v_add_co_u32_e32 v112, vcc, s11, v104
	s_nop 1
	v_addc_co_u32_e32 v113, vcc, 0, v105, vcc
	v_add_co_u32_e32 v116, vcc, s11, v106
	s_nop 1
	v_addc_co_u32_e32 v117, vcc, 0, v107, vcc
	v_add_co_u32_e32 v118, vcc, 0x30000, v104
	s_nop 1
	v_addc_co_u32_e32 v119, vcc, 0, v105, vcc
	v_add_co_u32_e32 v124, vcc, 0x30000, v106
	s_nop 1
	v_addc_co_u32_e32 v125, vcc, 0, v107, vcc
	global_load_dwordx4 v[64:67], v[104:105], off
	global_load_dwordx4 v[68:71], v[104:105], off offset:128
	global_load_dwordx4 v[72:75], v[106:107], off
	global_load_dwordx4 v[76:79], v[106:107], off offset:128
	global_load_dwordx4 v[80:83], v[108:109], off
	global_load_dwordx4 v[84:87], v[108:109], off offset:128
	global_load_dwordx4 v[88:91], v[110:111], off
	global_load_dwordx4 v[92:95], v[110:111], off offset:128
	global_load_dwordx4 v[96:99], v[112:113], off
	global_load_dwordx4 v[100:103], v[112:113], off offset:128
	global_load_dwordx4 v[104:107], v[116:117], off
	s_nop 0
	global_load_dwordx4 v[108:111], v[116:117], off offset:128
	global_load_dwordx4 v[112:115], v[118:119], off
	s_nop 0
	global_load_dwordx4 v[116:119], v[118:119], off offset:128
	s_nop 0
	global_load_dwordx4 v[120:123], v[124:125], off
	s_nop 0
	global_load_dwordx4 v[124:127], v[124:125], off offset:128
	s_branch .LBB0_1503
